# RET3 phase rewritten by hand: K/SPT/VT tiles staged into LDS via coalesced LDS-DMA (xor-swizzled), MFMA fragments via ds_read instead of fragment-shaped global loads
# speedup vs baseline: 1.0521x; 1.0521x over previous
.LBB0_401:
	s_abs_i32 s0, s94
	v_cvt_f32_u32_e32 v0, s0
	s_sub_i32 s1, 0, s0
	v_rcp_iflag_f32_e32 v0, v0
	s_nop 0
	v_mul_f32_e32 v0, 0x4f7ffffe, v0
	v_cvt_u32_f32_e32 v0, v0
	s_nop 0
	v_readfirstlane_b32 s4, v0
	s_mul_i32 s1, s1, s4
	s_mul_hi_u32 s1, s4, s1
	s_add_i32 s4, s4, s1
	s_mul_hi_u32 s1, s4, 0x630
	s_mul_i32 s1, s1, s0
	s_sub_i32 s1, 0x630, s1
	s_sub_i32 s4, s1, s0
	s_cmp_ge_u32 s1, s0
	s_cselect_b32 s1, s4, s1
	s_sub_i32 s4, s1, s0
	s_cmp_ge_u32 s1, s0
	s_cselect_b32 s8, s4, s1
	s_cmp_lg_u32 s8, 0
	s_cselect_b64 s[0:1], -1, 0
	s_and_b64 vcc, exec, s[0:1]
	s_cbranch_vccz .LBB0_419
	s_cmp_lt_i32 s34, s8
	s_cbranch_scc1 .LBB0_409
	s_sub_i32 s4, s34, s8
	v_lshrrev_b32_e32 v0, 6, v128
	v_lshl_add_u32 v14, s4, 3, v0
	s_movk_i32 s4, 0x1600
	v_cmp_gt_i32_e32 vcc, s4, v14
	s_and_saveexec_b64 s[4:5], vcc
	s_cbranch_execz .LBB0_408
	s_sub_i32 s6, s94, s8
	s_waitcnt vmcnt(0)
	v_lshlrev_b32_e32 v3, 3, v128
	s_lshl_b32 s9, s6, 3
	s_movk_i32 s6, 0x2200
	v_lshlrev_b32_e32 v2, 2, v128
	v_bfe_u32 v15, v128, 3, 3
	v_and_b32_e32 v3, 56, v3
	v_mad_u32_u24 v1, v0, s6, 0
	v_and_b32_e32 v6, 0x7c, v2
	v_mul_u32_u24_e32 v4, 0x84, v3
	v_lshlrev_b32_e32 v5, 2, v15
	v_mov_b32_e32 v7, 0
	v_add_u32_e32 v2, v1, v6
	v_add3_u32 v16, v1, v4, v5
	v_lshl_add_u64 v[4:5], s[40:41], 0, v[6:7]
	v_lshlrev_b32_e32 v6, 1, v3
	v_bfe_u32 v0, v128, 5, 1
	v_lshl_add_u64 v[6:7], s[50:51], 0, v[6:7]
	s_mov_b64 s[6:7], 0x2c04000
	s_movk_i32 s10, 0x84
	v_or_b32_e32 v17, 8, v15
	v_or_b32_e32 v18, 16, v15
	v_or_b32_e32 v19, 24, v15
	v_lshl_add_u64 v[6:7], v[6:7], 0, s[6:7]
	v_mov_b32_e32 v1, v0
	s_mov_b64 s[6:7], 0
	s_movk_i32 s11, 0x2c00
	s_movk_i32 s12, 0x15ff
.LBB0_405:
	v_ashrrev_i32_e32 v3, 31, v14
	v_lshrrev_b32_e32 v3, 26, v3
	v_add_u32_e32 v3, v14, v3
	v_and_b32_e32 v10, 0xffffffc0, v3
	v_lshlrev_b32_e32 v3, 5, v3
	v_and_b32_e32 v3, 0xfffff800, v3
	v_lshlrev_b32_e32 v8, 5, v14
	v_sub_u32_e32 v8, v8, v3
	v_ashrrev_i32_e32 v9, 31, v8
	v_lshl_add_u64 v[12:13], v[8:9], 2, v[4:5]
	v_mov_b32_e32 v3, v10
	s_mov_b32 s13, 32
	s_mov_b32 s14, 0
	s_mov_b32 s15, 1
.LBB0_406:
	s_lshl_b32 s26, s15, 1
	s_lshl_b32 s27, s14, 1
	v_or_b32_e32 v9, s26, v1
	v_or_b32_e32 v11, s27, v0
	s_add_i32 s28, s26, 4
	s_add_i32 s29, s27, 4
	s_add_i32 s30, s26, 8
	s_add_i32 s31, s27, 8
	s_add_i32 s33, s26, 12
	s_add_i32 s35, s27, 12
	s_add_i32 s52, s26, 16
	s_add_i32 s53, s27, 16
	s_add_i32 s54, s26, 20
	s_add_i32 s55, s27, 20
	s_add_i32 s56, s26, 24
	s_add_i32 s57, s27, 24
	s_add_i32 s26, s26, 28
	s_add_i32 s27, s27, 28
	v_add_u32_e32 v22, v11, v10
	v_or_b32_e32 v52, s28, v1
	v_or_b32_e32 v53, s29, v0
	v_or_b32_e32 v54, s30, v1
	v_or_b32_e32 v55, s31, v0
	v_or_b32_e32 v56, s33, v1
	v_or_b32_e32 v57, s35, v0
	v_or_b32_e32 v58, s52, v1
	v_or_b32_e32 v59, s53, v0
	v_or_b32_e32 v60, s54, v1
	v_or_b32_e32 v61, s55, v0
	v_or_b32_e32 v62, s56, v1
	v_or_b32_e32 v63, s57, v0
	v_or_b32_e32 v64, s26, v1
	v_or_b32_e32 v65, s27, v0
	v_add_u32_e32 v20, v9, v3
	v_ashrrev_i32_e32 v23, 31, v22
	v_add_u32_e32 v24, v52, v3
	v_add_u32_e32 v26, v53, v10
	v_add_u32_e32 v28, v54, v3
	v_add_u32_e32 v30, v55, v10
	v_add_u32_e32 v32, v56, v3
	v_add_u32_e32 v34, v57, v10
	v_add_u32_e32 v36, v58, v3
	v_add_u32_e32 v38, v59, v10
	v_add_u32_e32 v40, v60, v3
	v_add_u32_e32 v42, v61, v10
	v_add_u32_e32 v44, v62, v3
	v_add_u32_e32 v46, v63, v10
	v_add_u32_e32 v48, v64, v3
	v_add_u32_e32 v50, v65, v10
	v_ashrrev_i32_e32 v21, 31, v20
	v_lshlrev_b64 v[22:23], 13, v[22:23]
	v_ashrrev_i32_e32 v27, 31, v26
	v_ashrrev_i32_e32 v25, 31, v24
	v_ashrrev_i32_e32 v31, 31, v30
	v_ashrrev_i32_e32 v29, 31, v28
	v_ashrrev_i32_e32 v35, 31, v34
	v_ashrrev_i32_e32 v33, 31, v32
	v_ashrrev_i32_e32 v39, 31, v38
	v_ashrrev_i32_e32 v37, 31, v36
	v_ashrrev_i32_e32 v43, 31, v42
	v_ashrrev_i32_e32 v41, 31, v40
	v_ashrrev_i32_e32 v47, 31, v46
	v_ashrrev_i32_e32 v45, 31, v44
	v_ashrrev_i32_e32 v51, 31, v50
	v_ashrrev_i32_e32 v49, 31, v48
	v_lshlrev_b64 v[20:21], 13, v[20:21]
	v_lshl_add_u64 v[22:23], v[12:13], 0, v[22:23]
	v_lshlrev_b64 v[24:25], 13, v[24:25]
	v_lshlrev_b64 v[26:27], 13, v[26:27]
	v_lshlrev_b64 v[28:29], 13, v[28:29]
	v_lshlrev_b64 v[30:31], 13, v[30:31]
	v_lshlrev_b64 v[32:33], 13, v[32:33]
	v_lshlrev_b64 v[34:35], 13, v[34:35]
	v_lshlrev_b64 v[36:37], 13, v[36:37]
	v_lshlrev_b64 v[38:39], 13, v[38:39]
	v_lshlrev_b64 v[40:41], 13, v[40:41]
	v_lshlrev_b64 v[42:43], 13, v[42:43]
	v_lshlrev_b64 v[44:45], 13, v[44:45]
	v_lshlrev_b64 v[46:47], 13, v[46:47]
	v_lshlrev_b64 v[48:49], 13, v[48:49]
	v_lshlrev_b64 v[50:51], 13, v[50:51]
	v_lshl_add_u64 v[20:21], v[12:13], 0, v[20:21]
	v_lshl_add_u64 v[26:27], v[12:13], 0, v[26:27]
	v_lshl_add_u64 v[24:25], v[12:13], 0, v[24:25]
	v_lshl_add_u64 v[30:31], v[12:13], 0, v[30:31]
	v_lshl_add_u64 v[28:29], v[12:13], 0, v[28:29]
	v_lshl_add_u64 v[34:35], v[12:13], 0, v[34:35]
	v_lshl_add_u64 v[32:33], v[12:13], 0, v[32:33]
	v_lshl_add_u64 v[38:39], v[12:13], 0, v[38:39]
	v_lshl_add_u64 v[36:37], v[12:13], 0, v[36:37]
	v_lshl_add_u64 v[42:43], v[12:13], 0, v[42:43]
	v_lshl_add_u64 v[40:41], v[12:13], 0, v[40:41]
	v_lshl_add_u64 v[46:47], v[12:13], 0, v[46:47]
	v_lshl_add_u64 v[44:45], v[12:13], 0, v[44:45]
	v_lshl_add_u64 v[50:51], v[12:13], 0, v[50:51]
	v_lshl_add_u64 v[48:49], v[12:13], 0, v[48:49]
	global_load_dword v66, v[22:23], off
	global_load_dword v67, v[20:21], off
	global_load_dword v68, v[26:27], off
	global_load_dword v69, v[24:25], off
	global_load_dword v70, v[30:31], off
	global_load_dword v71, v[28:29], off
	global_load_dword v72, v[34:35], off
	global_load_dword v73, v[32:33], off
	global_load_dword v74, v[38:39], off
	global_load_dword v75, v[36:37], off
	global_load_dword v76, v[42:43], off
	global_load_dword v77, v[40:41], off
	global_load_dword v78, v[46:47], off
	global_load_dword v79, v[44:45], off
	global_load_dword v80, v[50:51], off
	global_load_dword v81, v[48:49], off
	s_add_i32 s14, s14, 16
	s_add_i32 s15, s15, 16
	s_add_i32 s13, s13, -16
	v_mad_u64_u32 v[20:21], s[26:27], v11, s10, v[2:3]
	s_cmp_lg_u32 s13, 0
	v_mad_u64_u32 v[22:23], s[26:27], v9, s10, v[2:3]
	v_mad_u64_u32 v[24:25], s[26:27], v53, s10, v[2:3]
	v_mad_u64_u32 v[26:27], s[26:27], v52, s10, v[2:3]
	v_mad_u64_u32 v[28:29], s[26:27], v55, s10, v[2:3]
	v_mad_u64_u32 v[30:31], s[26:27], v54, s10, v[2:3]
	v_mad_u64_u32 v[32:33], s[26:27], v57, s10, v[2:3]
	v_mad_u64_u32 v[34:35], s[26:27], v56, s10, v[2:3]
	v_mad_u64_u32 v[36:37], s[26:27], v59, s10, v[2:3]
	v_mad_u64_u32 v[38:39], s[26:27], v58, s10, v[2:3]
	v_mad_u64_u32 v[40:41], s[26:27], v61, s10, v[2:3]
	v_mad_u64_u32 v[42:43], s[26:27], v60, s10, v[2:3]
	v_mad_u64_u32 v[44:45], s[26:27], v63, s10, v[2:3]
	v_mad_u64_u32 v[46:47], s[26:27], v62, s10, v[2:3]
	v_mad_u64_u32 v[48:49], s[26:27], v65, s10, v[2:3]
	v_mad_u64_u32 v[50:51], s[26:27], v64, s10, v[2:3]
	s_waitcnt vmcnt(15)
	ds_write_b32 v20, v66
	s_waitcnt vmcnt(14)
	ds_write_b32 v22, v67
	s_waitcnt vmcnt(13)
	ds_write_b32 v24, v68
	s_waitcnt vmcnt(12)
	ds_write_b32 v26, v69
	s_waitcnt vmcnt(11)
	ds_write_b32 v28, v70
	s_waitcnt vmcnt(10)
	ds_write_b32 v30, v71
	s_waitcnt vmcnt(9)
	ds_write_b32 v32, v72
	s_waitcnt vmcnt(8)
	ds_write_b32 v34, v73
	s_waitcnt vmcnt(7)
	ds_write_b32 v36, v74
	s_waitcnt vmcnt(6)
	ds_write_b32 v38, v75
	s_waitcnt vmcnt(5)
	ds_write_b32 v40, v76
	s_waitcnt vmcnt(4)
	ds_write_b32 v42, v77
	s_waitcnt vmcnt(3)
	ds_write_b32 v44, v78
	s_waitcnt vmcnt(2)
	ds_write_b32 v46, v79
	s_waitcnt vmcnt(1)
	ds_write_b32 v48, v80
	s_waitcnt vmcnt(0)
	ds_write_b32 v50, v81
	s_cbranch_scc1 .LBB0_406
	s_waitcnt lgkmcnt(0)
	ds_read2_b32 v[20:21], v16 offset0:33 offset1:41
	ds_read2_b32 v[22:23], v16 offset1:8
	ds_read2_b32 v[24:25], v16 offset0:66 offset1:74
	ds_read2_b32 v[26:27], v16 offset0:99 offset1:107
	ds_read2_b32 v[28:29], v16 offset0:132 offset1:140
	ds_read2_b32 v[30:31], v16 offset0:165 offset1:173
	ds_read2_b32 v[32:33], v16 offset0:198 offset1:206
	ds_read2_b32 v[34:35], v16 offset0:231 offset1:239
	v_ashrrev_i32_e32 v11, 31, v10
	v_lshl_add_u64 v[36:37], v[10:11], 1, v[6:7]
	v_or_b32_e32 v3, v8, v15
	s_waitcnt lgkmcnt(6)
	v_cvt_pk_bf16_f32 v10, v22, v20
	s_waitcnt lgkmcnt(4)
	v_cvt_pk_bf16_f32 v11, v24, v26
	s_waitcnt lgkmcnt(2)
	v_cvt_pk_bf16_f32 v12, v28, v30
	s_waitcnt lgkmcnt(0)
	v_cvt_pk_bf16_f32 v13, v32, v34
	v_mad_i64_i32 v[38:39], s[14:15], v3, s11, v[36:37]
	global_store_dwordx4 v[38:39], v[10:13], off
	v_or_b32_e32 v3, v8, v17
	v_add_u32_e32 v14, s9, v14
	v_cvt_pk_bf16_f32 v10, v23, v21
	v_cvt_pk_bf16_f32 v11, v25, v27
	v_cvt_pk_bf16_f32 v12, v29, v31
	v_cvt_pk_bf16_f32 v13, v33, v35
	ds_read2_b32 v[22:23], v16 offset0:49 offset1:57
	ds_read2_b32 v[24:25], v16 offset0:16 offset1:24
	ds_read2_b32 v[26:27], v16 offset0:82 offset1:90
	ds_read2_b32 v[28:29], v16 offset0:115 offset1:123
	ds_read2_b32 v[30:31], v16 offset0:148 offset1:156
	ds_read2_b32 v[32:33], v16 offset0:181 offset1:189
	ds_read2_b32 v[34:35], v16 offset0:214 offset1:222
	ds_read2_b32 v[38:39], v16 offset0:247 offset1:255
	v_mad_i64_i32 v[20:21], s[14:15], v3, s11, v[36:37]
	v_or_b32_e32 v3, v8, v18
	global_store_dwordx4 v[20:21], v[10:13], off
	v_mad_i64_i32 v[20:21], s[14:15], v3, s11, v[36:37]
	s_waitcnt lgkmcnt(6)
	v_cvt_pk_bf16_f32 v10, v24, v22
	s_waitcnt lgkmcnt(4)
	v_cvt_pk_bf16_f32 v11, v26, v28
	s_waitcnt lgkmcnt(2)
	v_cvt_pk_bf16_f32 v12, v30, v32
	s_waitcnt lgkmcnt(0)
	v_cvt_pk_bf16_f32 v13, v34, v38
	v_or_b32_e32 v3, v8, v19
	global_store_dwordx4 v[20:21], v[10:13], off
	v_mad_i64_i32 v[8:9], s[14:15], v3, s11, v[36:37]
	s_nop 0
	v_cvt_pk_bf16_f32 v10, v25, v23
	v_cvt_pk_bf16_f32 v11, v27, v29
	v_cvt_pk_bf16_f32 v12, v31, v33
	v_cvt_pk_bf16_f32 v13, v35, v39
	global_store_dwordx4 v[8:9], v[10:13], off
	s_waitcnt lgkmcnt(0)
	v_cmp_lt_i32_e32 vcc, s12, v14
	s_or_b64 s[6:7], vcc, s[6:7]
	s_andn2_b64 exec, exec, s[6:7]
	s_cbranch_execnz .LBB0_405

.LBB0_409:
	s_cbranch_execz .LBB0_420
	s_and_b64 vcc, exec, s[0:1]
	s_cbranch_vccz .LBB0_426
.LBB0_411:
	s_cmp_lt_i32 s34, s8
	s_cbranch_scc1 .LBB0_418
	v_lshrrev_b32_e32 v1, 6, v128
	s_sub_i32 s0, s34, s8
	v_lshl_add_u32 v0, s0, 3, v1
	s_movk_i32 s0, 0x1600
	v_cmp_gt_i32_e32 vcc, s0, v0
	s_and_saveexec_b64 s[0:1], vcc
	s_cbranch_execz .LBB0_417
	s_waitcnt vmcnt(0)
	v_lshlrev_b32_e32 v3, 2, v128
	s_sub_i32 s4, s94, s8
	v_and_b32_e32 v8, 0x7c, v3
	v_lshlrev_b32_e32 v3, 3, v128
	s_lshl_b32 s6, s4, 3
	s_movk_i32 s4, 0x2200
	v_bfe_u32 v5, v128, 3, 3
	v_and_b32_e32 v3, 56, v3
	v_mad_u32_u24 v1, v1, s4, 0
	v_mul_u32_u24_e32 v6, 0x84, v3
	v_lshlrev_b32_e32 v7, 2, v5
	v_mov_b32_e32 v9, 0
	v_add_u32_e32 v4, v1, v8
	v_add3_u32 v18, v1, v6, v7
	v_lshl_add_u64 v[6:7], s[42:43], 0, v[8:9]
	v_lshlrev_b32_e32 v8, 1, v3
	v_bfe_u32 v2, v128, 5, 1
	v_lshl_add_u64 v[8:9], s[50:51], 0, v[8:9]
	s_mov_b64 s[4:5], 0x8404000
	s_movk_i32 s7, 0x84
	v_or_b32_e32 v19, 8, v5
	v_or_b32_e32 v20, 16, v5
	v_or_b32_e32 v21, 24, v5
	v_lshl_add_u64 v[8:9], v[8:9], 0, s[4:5]
	v_mov_b32_e32 v1, v2
	s_mov_b64 s[4:5], 0
	s_mov_b32 s8, 0x2e8ba2e9
	s_movk_i32 s9, 0xff50
	s_movk_i32 s10, 0x5800
	s_movk_i32 s11, 0x60
	s_movk_i32 s12, 0x15ff
.LBB0_414:
	v_mul_hi_i32 v3, v0, s8
	v_lshrrev_b32_e32 v10, 31, v3
	v_ashrrev_i32_e32 v3, 5, v3
	v_add_u32_e32 v3, v3, v10
	v_mad_u64_u32 v[12:13], s[14:15], v3, s9, v[0:1]
	v_lshlrev_b32_e32 v14, 5, v12
	v_lshlrev_b32_e32 v10, 6, v3
	v_ashrrev_i32_e32 v15, 31, v14
	v_lshl_add_u64 v[16:17], v[14:15], 2, v[6:7]
	v_mov_b32_e32 v3, v10
	s_mov_b32 s13, 32
	s_mov_b32 s14, 0
	s_mov_b32 s15, 1
.LBB0_415:
	s_lshl_b32 s26, s15, 1
	s_lshl_b32 s27, s14, 1
	v_or_b32_e32 v11, s26, v1
	v_or_b32_e32 v13, s27, v2
	s_add_i32 s28, s26, 4
	s_add_i32 s29, s27, 4
	s_add_i32 s30, s26, 8
	s_add_i32 s31, s27, 8
	s_add_i32 s33, s26, 12
	s_add_i32 s35, s27, 12
	s_add_i32 s52, s26, 16
	s_add_i32 s53, s27, 16
	s_add_i32 s54, s26, 20
	s_add_i32 s55, s27, 20
	s_add_i32 s56, s26, 24
	s_add_i32 s57, s27, 24
	s_add_i32 s26, s26, 28
	s_add_i32 s27, s27, 28
	v_add_u32_e32 v15, v11, v3
	v_add_u32_e32 v22, v13, v10
	v_or_b32_e32 v54, s28, v1
	v_or_b32_e32 v55, s29, v2
	v_or_b32_e32 v56, s30, v1
	v_or_b32_e32 v57, s31, v2
	v_or_b32_e32 v58, s33, v1
	v_or_b32_e32 v59, s35, v2
	v_or_b32_e32 v60, s52, v1
	v_or_b32_e32 v61, s53, v2
	v_or_b32_e32 v62, s54, v1
	v_or_b32_e32 v63, s55, v2
	v_or_b32_e32 v64, s56, v1
	v_or_b32_e32 v65, s57, v2
	v_or_b32_e32 v66, s26, v1
	v_or_b32_e32 v67, s27, v2
	v_mad_i64_i32 v[22:23], s[26:27], v22, s10, v[16:17]
	v_mad_i64_i32 v[24:25], s[26:27], v15, s10, v[16:17]
	v_add_u32_e32 v15, v54, v3
	v_add_u32_e32 v26, v55, v10
	v_add_u32_e32 v32, v56, v3
	v_add_u32_e32 v30, v57, v10
	v_add_u32_e32 v36, v58, v3
	v_add_u32_e32 v34, v59, v10
	v_add_u32_e32 v40, v60, v3
	v_add_u32_e32 v38, v61, v10
	v_add_u32_e32 v44, v62, v3
	v_add_u32_e32 v42, v63, v10
	v_add_u32_e32 v48, v64, v3
	v_add_u32_e32 v46, v65, v10
	v_add_u32_e32 v52, v66, v3
	v_add_u32_e32 v50, v67, v10
	v_mad_i64_i32 v[26:27], s[26:27], v26, s10, v[16:17]
	v_mad_i64_i32 v[28:29], s[26:27], v15, s10, v[16:17]
	v_mad_i64_i32 v[30:31], s[26:27], v30, s10, v[16:17]
	v_mad_i64_i32 v[32:33], s[26:27], v32, s10, v[16:17]
	v_mad_i64_i32 v[34:35], s[26:27], v34, s10, v[16:17]
	v_mad_i64_i32 v[36:37], s[26:27], v36, s10, v[16:17]
	v_mad_i64_i32 v[38:39], s[26:27], v38, s10, v[16:17]
	v_mad_i64_i32 v[40:41], s[26:27], v40, s10, v[16:17]
	v_mad_i64_i32 v[42:43], s[26:27], v42, s10, v[16:17]
	v_mad_i64_i32 v[44:45], s[26:27], v44, s10, v[16:17]
	v_mad_i64_i32 v[46:47], s[26:27], v46, s10, v[16:17]
	v_mad_i64_i32 v[48:49], s[26:27], v48, s10, v[16:17]
	v_mad_i64_i32 v[50:51], s[26:27], v50, s10, v[16:17]
	v_mad_i64_i32 v[52:53], s[26:27], v52, s10, v[16:17]
	global_load_dword v15, v[22:23], off
	global_load_dword v68, v[24:25], off
	global_load_dword v69, v[26:27], off
	global_load_dword v70, v[28:29], off
	global_load_dword v71, v[30:31], off
	global_load_dword v72, v[32:33], off
	global_load_dword v73, v[34:35], off
	global_load_dword v74, v[36:37], off
	global_load_dword v75, v[38:39], off
	global_load_dword v76, v[40:41], off
	global_load_dword v77, v[42:43], off
	global_load_dword v78, v[44:45], off
	global_load_dword v79, v[46:47], off
	global_load_dword v80, v[48:49], off
	global_load_dword v81, v[50:51], off
	global_load_dword v82, v[52:53], off
	s_add_i32 s14, s14, 16
	s_add_i32 s15, s15, 16
	s_add_i32 s13, s13, -16
	v_mad_u64_u32 v[22:23], s[26:27], v13, s7, v[4:5]
	s_cmp_lg_u32 s13, 0
	v_mad_u64_u32 v[24:25], s[26:27], v11, s7, v[4:5]
	v_mad_u64_u32 v[26:27], s[26:27], v55, s7, v[4:5]
	v_mad_u64_u32 v[28:29], s[26:27], v54, s7, v[4:5]
	v_mad_u64_u32 v[30:31], s[26:27], v57, s7, v[4:5]
	v_mad_u64_u32 v[32:33], s[26:27], v56, s7, v[4:5]
	v_mad_u64_u32 v[34:35], s[26:27], v59, s7, v[4:5]
	v_mad_u64_u32 v[36:37], s[26:27], v58, s7, v[4:5]
	v_mad_u64_u32 v[38:39], s[26:27], v61, s7, v[4:5]
	v_mad_u64_u32 v[40:41], s[26:27], v60, s7, v[4:5]
	v_mad_u64_u32 v[42:43], s[26:27], v63, s7, v[4:5]
	v_mad_u64_u32 v[44:45], s[26:27], v62, s7, v[4:5]
	v_mad_u64_u32 v[46:47], s[26:27], v65, s7, v[4:5]
	v_mad_u64_u32 v[48:49], s[26:27], v64, s7, v[4:5]
	v_mad_u64_u32 v[50:51], s[26:27], v67, s7, v[4:5]
	v_mad_u64_u32 v[52:53], s[26:27], v66, s7, v[4:5]
	s_waitcnt vmcnt(15)
	ds_write_b32 v22, v15
	s_waitcnt vmcnt(14)
	ds_write_b32 v24, v68
	s_waitcnt vmcnt(13)
	ds_write_b32 v26, v69
	s_waitcnt vmcnt(12)
	ds_write_b32 v28, v70
	s_waitcnt vmcnt(11)
	ds_write_b32 v30, v71
	s_waitcnt vmcnt(10)
	ds_write_b32 v32, v72
	s_waitcnt vmcnt(9)
	ds_write_b32 v34, v73
	s_waitcnt vmcnt(8)
	ds_write_b32 v36, v74
	s_waitcnt vmcnt(7)
	ds_write_b32 v38, v75
	s_waitcnt vmcnt(6)
	ds_write_b32 v40, v76
	s_waitcnt vmcnt(5)
	ds_write_b32 v42, v77
	s_waitcnt vmcnt(4)
	ds_write_b32 v44, v78
	s_waitcnt vmcnt(3)
	ds_write_b32 v46, v79
	s_waitcnt vmcnt(2)
	ds_write_b32 v48, v80
	s_waitcnt vmcnt(1)
	ds_write_b32 v50, v81
	s_waitcnt vmcnt(0)
	ds_write_b32 v52, v82
	s_cbranch_scc1 .LBB0_415
	v_lshlrev_b32_e32 v3, 6, v12
	v_and_b32_e32 v3, 0xffffff00, v3
	s_waitcnt lgkmcnt(0)
	v_and_or_b32 v3, v14, s11, v3
	ds_read2_b32 v[14:15], v18 offset0:33 offset1:41
	ds_read2_b32 v[16:17], v18 offset1:8
	ds_read2_b32 v[22:23], v18 offset0:66 offset1:74
	ds_read2_b32 v[24:25], v18 offset0:99 offset1:107
	ds_read2_b32 v[26:27], v18 offset0:132 offset1:140
	ds_read2_b32 v[28:29], v18 offset0:165 offset1:173
	ds_read2_b32 v[30:31], v18 offset0:198 offset1:206
	ds_read2_b32 v[32:33], v18 offset0:231 offset1:239
	v_or_b32_e32 v36, v3, v5
	v_ashrrev_i32_e32 v11, 31, v10
	v_ashrrev_i32_e32 v37, 31, v36
	v_lshl_add_u64 v[34:35], v[10:11], 1, v[8:9]
	v_lshlrev_b64 v[36:37], 12, v[36:37]
	s_waitcnt lgkmcnt(6)
	v_cvt_pk_bf16_f32 v10, v16, v14
	s_waitcnt lgkmcnt(4)
	v_cvt_pk_bf16_f32 v11, v22, v24
	s_waitcnt lgkmcnt(2)
	v_cvt_pk_bf16_f32 v12, v26, v28
	s_waitcnt lgkmcnt(0)
	v_cvt_pk_bf16_f32 v13, v30, v32
	v_lshl_add_u64 v[36:37], v[34:35], 0, v[36:37]
	v_or_b32_e32 v14, v3, v19
	global_store_dwordx4 v[36:37], v[10:13], off
	v_add_u32_e32 v0, s6, v0
	v_cmp_lt_i32_e32 vcc, s12, v0
	v_cvt_pk_bf16_f32 v10, v17, v15
	v_ashrrev_i32_e32 v15, 31, v14
	v_cvt_pk_bf16_f32 v11, v23, v25
	v_cvt_pk_bf16_f32 v12, v27, v29
	v_cvt_pk_bf16_f32 v13, v31, v33
	v_lshlrev_b64 v[14:15], 12, v[14:15]
	ds_read2_b32 v[16:17], v18 offset0:49 offset1:57
	ds_read2_b32 v[22:23], v18 offset0:16 offset1:24
	ds_read2_b32 v[24:25], v18 offset0:82 offset1:90
	ds_read2_b32 v[26:27], v18 offset0:115 offset1:123
	ds_read2_b32 v[28:29], v18 offset0:148 offset1:156
	ds_read2_b32 v[30:31], v18 offset0:181 offset1:189
	ds_read2_b32 v[32:33], v18 offset0:214 offset1:222
	ds_read2_b32 v[36:37], v18 offset0:247 offset1:255
	v_lshl_add_u64 v[14:15], v[34:35], 0, v[14:15]
	global_store_dwordx4 v[14:15], v[10:13], off
	v_or_b32_e32 v14, v3, v20
	v_ashrrev_i32_e32 v15, 31, v14
	v_lshlrev_b64 v[14:15], 12, v[14:15]
	s_waitcnt lgkmcnt(6)
	v_cvt_pk_bf16_f32 v10, v22, v16
	s_waitcnt lgkmcnt(4)
	v_cvt_pk_bf16_f32 v11, v24, v26
	s_waitcnt lgkmcnt(2)
	v_cvt_pk_bf16_f32 v12, v28, v30
	s_waitcnt lgkmcnt(0)
	v_cvt_pk_bf16_f32 v13, v32, v36
	v_lshl_add_u64 v[14:15], v[34:35], 0, v[14:15]
	global_store_dwordx4 v[14:15], v[10:13], off
	v_or_b32_e32 v14, v3, v21
	v_ashrrev_i32_e32 v15, 31, v14
	v_lshlrev_b64 v[14:15], 12, v[14:15]
	v_cvt_pk_bf16_f32 v10, v23, v17
	v_cvt_pk_bf16_f32 v11, v25, v27
	v_cvt_pk_bf16_f32 v12, v29, v31
	v_cvt_pk_bf16_f32 v13, v33, v37
	v_lshl_add_u64 v[14:15], v[34:35], 0, v[14:15]
	global_store_dwordx4 v[14:15], v[10:13], off
	s_waitcnt lgkmcnt(0)
	s_or_b64 s[4:5], vcc, s[4:5]
	s_andn2_b64 exec, exec, s[4:5]
	s_cbranch_execnz .LBB0_414

.LBB0_418:
	s_cbranch_execz .LBB0_427
	s_branch .LBB0_433
.LBB0_419:
.LBB0_420:
	v_lshrrev_b32_e32 v0, 6, v128
	v_lshl_add_u32 v14, s34, 3, v0
	s_movk_i32 s4, 0x1600
	v_cmp_gt_i32_e32 vcc, s4, v14
	s_and_saveexec_b64 s[4:5], vcc
	s_cbranch_execz .LBB0_425
	s_waitcnt vmcnt(0)
	v_lshlrev_b32_e32 v3, 3, v128
	s_movk_i32 s6, 0x2200
	v_lshlrev_b32_e32 v2, 2, v128
	v_bfe_u32 v15, v128, 3, 3
	v_and_b32_e32 v3, 56, v3
	v_mad_u32_u24 v1, v0, s6, 0
	v_and_b32_e32 v6, 0x7c, v2
	v_mul_u32_u24_e32 v4, 0x84, v3
	v_lshlrev_b32_e32 v5, 2, v15
	v_mov_b32_e32 v7, 0
	v_add_u32_e32 v2, v1, v6
	v_add3_u32 v16, v1, v4, v5
	v_lshl_add_u64 v[4:5], s[40:41], 0, v[6:7]
	v_lshlrev_b32_e32 v6, 1, v3
	v_bfe_u32 v0, v128, 5, 1
	v_lshl_add_u64 v[6:7], s[50:51], 0, v[6:7]
	s_mov_b64 s[6:7], 0x2c04000
	s_lshl_b32 s9, s94, 3
	s_movk_i32 s10, 0x84
	v_or_b32_e32 v17, 8, v15
	v_or_b32_e32 v18, 16, v15
	v_or_b32_e32 v19, 24, v15
	v_lshl_add_u64 v[6:7], v[6:7], 0, s[6:7]
	v_mov_b32_e32 v1, v0
	s_mov_b64 s[6:7], 0
	s_movk_i32 s11, 0x2c00
	s_movk_i32 s12, 0x15ff

.LBB0_425:
	s_or_b64 exec, exec, s[4:5]
	s_and_b64 vcc, exec, s[0:1]
	s_cbranch_vccnz .LBB0_411
.LBB0_426:
.LBB0_427:
	v_lshrrev_b32_e32 v1, 6, v128
	v_lshl_add_u32 v0, s34, 3, v1
	s_movk_i32 s0, 0x1600
	v_cmp_gt_i32_e32 vcc, s0, v0
	s_and_saveexec_b64 s[0:1], vcc
	s_cbranch_execz .LBB0_432
	s_waitcnt vmcnt(0)
	v_lshlrev_b32_e32 v3, 2, v128
	v_and_b32_e32 v8, 0x7c, v3
	v_lshlrev_b32_e32 v3, 3, v128
	s_movk_i32 s4, 0x2200
	v_bfe_u32 v5, v128, 3, 3
	v_and_b32_e32 v3, 56, v3
	v_mad_u32_u24 v1, v1, s4, 0
	v_mul_u32_u24_e32 v6, 0x84, v3
	v_lshlrev_b32_e32 v7, 2, v5
	v_mov_b32_e32 v9, 0
	v_add_u32_e32 v4, v1, v8
	v_add3_u32 v18, v1, v6, v7
	v_lshl_add_u64 v[6:7], s[42:43], 0, v[8:9]
	v_lshlrev_b32_e32 v8, 1, v3
	v_bfe_u32 v2, v128, 5, 1
	v_lshl_add_u64 v[8:9], s[50:51], 0, v[8:9]
	s_mov_b64 s[4:5], 0x8404000
	s_lshl_b32 s6, s94, 3
	s_movk_i32 s7, 0x84
	v_or_b32_e32 v19, 8, v5
	v_or_b32_e32 v20, 16, v5
	v_or_b32_e32 v21, 24, v5
	v_lshl_add_u64 v[8:9], v[8:9], 0, s[4:5]
	v_mov_b32_e32 v1, v2
	s_mov_b64 s[4:5], 0
	s_mov_b32 s8, 0x2e8ba2e9
	s_movk_i32 s9, 0xff50
	s_movk_i32 s10, 0x5800
	s_movk_i32 s11, 0x60
	s_movk_i32 s12, 0x15ff

.LBB0_432:
	s_or_b64 exec, exec, s[0:1]
.LBB0_433:
	s_cmp_lt_i32 s92, 5
	s_cselect_b64 s[0:1], -1, 0
	s_cmp_gt_i32 s93, 4
	s_cselect_b64 s[4:5], -1, 0
	s_and_b64 s[4:5], s[0:1], s[4:5]
	s_andn2_b64 vcc, exec, s[4:5]
	s_cbranch_vccnz .LBB0_680
	s_andn2_b64 vcc, exec, s[2:3]
	s_cbranch_vccnz .LBB0_488
	s_waitcnt vmcnt(0)
	s_waitcnt vmcnt(0)
	s_barrier
	s_mov_b64 s[2:3], exec
	v_readlane_b32 s4, v235, 17
	v_readlane_b32 s5, v235, 18
	s_and_b64 s[4:5], s[2:3], s[4:5]
	s_mov_b64 exec, s[4:5]
	s_cbranch_execz .LBB0_487
	s_add_i32 s4, 0, 0x23ff0
	v_mov_b32_e32 v0, s4
	s_waitcnt vmcnt(0) expcnt(0) lgkmcnt(0)
	ds_read_b32 v2, v0
	s_add_i32 s4, 0, 0x23ff4
	v_mov_b32_e32 v0, s4
	ds_read_b32 v0, v0
	s_waitcnt lgkmcnt(1)
	v_cmp_ne_u32_e32 vcc, 0, v2
	s_cbranch_vccnz .LBB0_451
	v_readlane_b32 s4, v235, 0
	s_mul_i32 s28, s95, s4
	s_add_u32 s4, s50, 0x1000
	s_addc_u32 s5, s51, 0
	s_add_u32 s6, s50, 0x1100
	s_addc_u32 s7, s51, 0
	s_add_u32 s8, s50, 0x1200
	s_addc_u32 s9, s51, 0
	s_add_u32 s10, s50, 0x1300
	s_mul_i32 s28, s28, s94
	s_addc_u32 s11, s51, 0
	s_mov_b32 s29, 1
	v_mov_b32_e32 v16, 0
	s_branch .LBB0_439

.LBB0_508:
	s_abs_i32 s4, s94
	v_cvt_f32_u32_e32 v0, s4
	s_sub_i32 s5, 0, s4
	v_rcp_iflag_f32_e32 v0, v0
	s_nop 0
	v_mul_f32_e32 v0, 0x4f7ffffe, v0
	v_cvt_u32_f32_e32 v0, v0
	s_nop 0
	v_readfirstlane_b32 s6, v0
	s_mul_i32 s5, s5, s6
	s_mul_hi_u32 s5, s6, s5
	s_add_i32 s6, s6, s5
	s_mul_hi_u32 s5, s6, 0x480
	s_mul_i32 s5, s5, s4
	s_sub_i32 s5, 0x480, s5
	s_sub_i32 s6, s5, s4
	s_cmp_ge_u32 s5, s4
	s_cselect_b32 s5, s6, s5
	s_sub_i32 s6, s5, s4
	s_cmp_ge_u32 s5, s4
	s_cselect_b32 s33, s6, s5
	s_cmp_lg_u32 s33, 0
	s_cselect_b64 s[4:5], -1, 0
	s_and_b64 vcc, exec, s[4:5]
	s_cbranch_vccz .LBB0_596
	s_cmp_lt_i32 s34, s33
	s_cbranch_scc1 .LBB0_584
	s_sub_i32 s6, s34, s33
	v_lshrrev_b32_e32 v0, 6, v128
	v_lshl_add_u32 v5, s6, 3, v0
	s_movk_i32 s6, 0x1400
	v_cmp_gt_i32_e32 vcc, s6, v5
	s_and_saveexec_b64 s[6:7], vcc
	s_cbranch_execz .LBB0_583
	s_sub_i32 s8, s94, s33
	s_lshl_b32 s35, s8, 3
	s_movk_i32 s8, 0x2200
	v_mad_u32_u24 v1, v0, s8, 0
	s_add_u32 s8, s50, 0x8404000
	s_addc_u32 s9, s51, 0
	s_add_u32 s10, s50, 0x7c04000
	s_addc_u32 s11, s51, 0
	s_add_u32 s12, s50, 0x7404000
	s_addc_u32 s13, s51, 0
	s_add_u32 s14, s50, 0x7004000
	s_addc_u32 s15, s51, 0
	s_add_u32 s26, s50, 0x4204000
	s_addc_u32 s27, s51, 0
	s_add_u32 s28, s50, 0x4000
	s_waitcnt vmcnt(0)
	v_lshlrev_b32_e32 v2, 3, v128
	s_addc_u32 s29, s51, 0
	v_bfe_u32 v9, v128, 3, 3
	v_and_b32_e32 v2, 56, v2
	s_add_u32 s30, s50, 0xb004000
	v_bfe_u32 v4, v128, 5, 1
	v_and_b32_e32 v0, 31, v128
	v_mul_u32_u24_e32 v3, 0x84, v2
	v_lshlrev_b32_e32 v6, 2, v9
	s_addc_u32 s31, s51, 0
	v_mov_b32_e32 v7, 0
	v_lshl_add_u32 v8, v0, 2, v1
	s_movk_i32 s68, 0x84
	v_add3_u32 v20, v1, v3, v6
	v_or_b32_e32 v21, 8, v9
	v_or_b32_e32 v22, 16, v9
	v_or_b32_e32 v23, 24, v9
	v_mov_b32_e32 v1, v4
	s_mov_b64 s[52:53], 0
	s_movk_i32 s69, 0x3ff
	s_movk_i32 s70, 0xfc00
	s_movk_i32 s71, 0xf7ff
	v_lshlrev_b32_e32 v6, 2, v0
	v_lshlrev_b32_e32 v10, 1, v2
	s_movk_i32 s72, 0x13ff
.LBB0_512:
	v_cmp_lt_i32_e32 vcc, s69, v5
	v_mov_b32_e32 v16, 4
	v_mov_b32_e32 v11, v5
	s_and_saveexec_b64 s[54:55], vcc
	s_cbranch_execz .LBB0_538
	v_add_u32_e32 v11, 0xfffffc00, v5
	v_mov_b32_e32 v16, 5
	s_mov_b64 s[56:57], 0
	s_branch .LBB0_517
.LBB0_514:
	s_or_b64 exec, exec, s[64:65]
.LBB0_515:
	s_or_b64 exec, exec, s[60:61]
	v_add_u32_e32 v11, v0, v11
	v_add_u32_e32 v16, 1, v16
	s_xor_b64 s[60:61], exec, -1
.LBB0_516:
	s_or_b64 exec, exec, s[58:59]
	s_and_b64 s[58:59], exec, s[60:61]
	s_or_b64 s[56:57], s[58:59], s[56:57]
	s_andn2_b64 exec, exec, s[56:57]
	s_cbranch_execz .LBB0_537
.LBB0_517:
	v_cmp_lt_i32_e32 vcc, 2, v16
	v_mov_b32_e32 v0, 0x1600
	s_and_saveexec_b64 s[58:59], vcc
	s_cbranch_execz .LBB0_524
	v_cmp_lt_i32_e32 vcc, 6, v16
	s_mov_b64 s[60:61], 0
	s_mov_b64 s[62:63], 0
	s_and_saveexec_b64 s[64:65], vcc
	s_xor_b64 s[64:65], exec, s[64:65]
	s_cbranch_execnz .LBB0_530
	s_andn2_saveexec_b64 s[64:65], s[64:65]
	s_cbranch_execnz .LBB0_531
.LBB0_520:
	s_or_b64 exec, exec, s[64:65]
	v_mov_b32_e32 v0, 0x1600
	s_and_saveexec_b64 s[64:65], s[62:63]
	s_cbranch_execnz .LBB0_532
.LBB0_521:
	s_or_b64 exec, exec, s[64:65]
	s_and_saveexec_b64 s[62:63], s[60:61]
.LBB0_522:
	v_mov_b32_e32 v0, 0x2e00

.LBB0_524:
	s_or_b64 exec, exec, s[58:59]
	v_cmp_ge_i32_e32 vcc, v11, v0
	s_mov_b64 s[60:61], -1
	s_and_saveexec_b64 s[58:59], vcc
	s_cbranch_execz .LBB0_516
	v_cmp_lt_i32_e32 vcc, 2, v16
	v_mov_b32_e32 v0, 0xffffea00
	s_and_saveexec_b64 s[60:61], vcc
	s_cbranch_execz .LBB0_515
	v_cmp_lt_i32_e32 vcc, 6, v16
	s_mov_b64 s[62:63], 0
	s_mov_b64 s[64:65], 0
	s_and_saveexec_b64 s[66:67], vcc
	s_xor_b64 s[66:67], exec, s[66:67]
	s_cbranch_execnz .LBB0_533
	s_andn2_saveexec_b64 s[66:67], s[66:67]
	s_cbranch_execnz .LBB0_534
.LBB0_528:
	s_or_b64 exec, exec, s[66:67]
	v_mov_b32_e32 v0, 0xffffea00
	s_and_saveexec_b64 s[66:67], s[64:65]
	s_cbranch_execnz .LBB0_535
.LBB0_529:
	s_or_b64 exec, exec, s[66:67]
	s_and_saveexec_b64 s[64:65], s[62:63]
	s_cbranch_execz .LBB0_514
	s_branch .LBB0_536
.LBB0_530:
	v_cmp_lt_i32_e32 vcc, 9, v16
	s_and_b64 s[62:63], vcc, exec
	s_andn2_saveexec_b64 s[64:65], s[64:65]
	s_cbranch_execz .LBB0_520
.LBB0_531:
	v_cmp_ne_u32_e32 vcc, 3, v16
	s_andn2_b64 s[62:63], s[62:63], exec
	s_and_b64 s[66:67], vcc, exec
	s_mov_b64 s[60:61], exec
	s_or_b64 s[62:63], s[62:63], s[66:67]
	s_or_b64 exec, exec, s[64:65]
	v_mov_b32_e32 v0, 0x1600
	s_and_saveexec_b64 s[64:65], s[62:63]
	s_cbranch_execz .LBB0_521
.LBB0_532:
	v_mov_b32_e32 v0, 0x800
	s_andn2_b64 s[60:61], s[60:61], exec
	s_or_b64 exec, exec, s[64:65]
	s_and_saveexec_b64 s[62:63], s[60:61]
	s_cbranch_execnz .LBB0_522
	s_branch .LBB0_523
.LBB0_533:
	v_cmp_lt_i32_e32 vcc, 9, v16
	s_and_b64 s[64:65], vcc, exec
	s_andn2_saveexec_b64 s[66:67], s[66:67]
	s_cbranch_execz .LBB0_528
.LBB0_534:
	v_cmp_ne_u32_e32 vcc, 3, v16
	s_andn2_b64 s[64:65], s[64:65], exec
	s_and_b64 s[74:75], vcc, exec
	s_mov_b64 s[62:63], exec
	s_or_b64 s[64:65], s[64:65], s[74:75]
	s_or_b64 exec, exec, s[66:67]
	v_mov_b32_e32 v0, 0xffffea00
	s_and_saveexec_b64 s[66:67], s[64:65]
	s_cbranch_execz .LBB0_529
.LBB0_535:
	v_mov_b32_e32 v0, 0xfffff800
	s_andn2_b64 s[62:63], s[62:63], exec
	s_or_b64 exec, exec, s[66:67]
	s_and_saveexec_b64 s[64:65], s[62:63]
	s_cbranch_execz .LBB0_514
.LBB0_536:
	v_mov_b32_e32 v0, 0xffffd200
	s_branch .LBB0_514

.LBB0_538:
	s_or_b64 exec, exec, s[54:55]
	v_cmp_lt_i32_e32 vcc, 3, v16
	s_and_saveexec_b64 s[56:57], vcc
	s_xor_b64 s[56:57], exec, s[56:57]
	s_cbranch_execz .LBB0_560
	v_cmp_lt_i32_e32 vcc, 5, v16
	s_and_saveexec_b64 s[58:59], vcc
	s_xor_b64 s[58:59], exec, s[58:59]
	s_cbranch_execz .LBB0_553
	v_readlane_b32 s76, v235, 1
	v_readlane_b32 s90, v235, 15
	v_readlane_b32 s91, v235, 16
	v_cmp_lt_i32_e32 vcc, 6, v16
	v_readlane_b32 s77, v235, 2
	v_mov_b64_e32 v[2:3], s[90:91]
	v_readlane_b32 s78, v235, 3
	v_readlane_b32 s79, v235, 4
	v_readlane_b32 s80, v235, 5
	v_readlane_b32 s81, v235, 6
	v_readlane_b32 s82, v235, 7
	v_readlane_b32 s83, v235, 8
	v_readlane_b32 s84, v235, 9
	v_readlane_b32 s85, v235, 10
	v_readlane_b32 s86, v235, 11
	v_readlane_b32 s87, v235, 12
	v_readlane_b32 s88, v235, 13
	v_readlane_b32 s89, v235, 14
	s_and_saveexec_b64 s[60:61], vcc
	s_xor_b64 s[60:61], exec, s[60:61]
	s_cbranch_execz .LBB0_550
	v_cmp_lt_i32_e32 vcc, 7, v16
	v_mov_b64_e32 v[2:3], s[42:43]
	s_and_saveexec_b64 s[62:63], vcc
	s_xor_b64 s[62:63], exec, s[62:63]
	s_cbranch_execz .LBB0_547
	v_cmp_ne_u32_e32 vcc, 8, v16
	v_mov_b64_e32 v[2:3], s[44:45]
	s_and_saveexec_b64 s[54:55], vcc
	s_xor_b64 s[54:55], exec, s[54:55]
	v_mov_b64_e32 v[2:3], s[46:47]
	s_or_saveexec_b64 s[64:65], s[54:55]
	v_mov_b64_e32 v[12:13], 0x1600
	v_mov_b32_e32 v0, 0x800
	s_mov_b64 s[54:55], -1
	v_mov_b32_e32 v17, 0
	v_mov_b64_e32 v[14:15], s[30:31]
	s_xor_b64 exec, exec, s[64:65]
	v_mov_b64_e32 v[12:13], 0x800
	v_mov_b32_e32 v0, 0x1600
	v_mov_b32_e32 v17, 0x80
	v_mov_b64_e32 v[14:15], s[8:9]
	s_xor_b64 s[54:55], exec, -1
	s_or_b64 exec, exec, s[64:65]
.LBB0_547:
	s_andn2_saveexec_b64 s[62:63], s[62:63]
	v_mov_b64_e32 v[12:13], 0x800
	v_mov_b32_e32 v0, 0x1600
	v_mov_b32_e32 v17, 0
	v_mov_b64_e32 v[14:15], s[8:9]
	s_andn2_b64 s[54:55], s[54:55], exec
	s_or_b64 exec, exec, s[62:63]
.LBB0_550:
	s_andn2_saveexec_b64 s[60:61], s[60:61]
	v_mov_b64_e32 v[12:13], 0x800
	v_mov_b32_e32 v0, 0x800
	v_mov_b32_e32 v17, 0
	v_mov_b64_e32 v[14:15], s[10:11]
	s_or_b64 s[54:55], s[54:55], exec
	s_or_b64 exec, exec, s[60:61]
.LBB0_553:
	s_andn2_saveexec_b64 s[58:59], s[58:59]
	s_cbranch_execz .LBB0_559
	v_readlane_b32 s76, v235, 1
	v_readlane_b32 s86, v235, 11
	v_readlane_b32 s87, v235, 12
	v_cmp_lt_i32_e32 vcc, 4, v16
	v_readlane_b32 s77, v235, 2
	v_mov_b64_e32 v[2:3], s[86:87]
	v_readlane_b32 s78, v235, 3
	v_readlane_b32 s79, v235, 4
	v_readlane_b32 s80, v235, 5
	v_readlane_b32 s81, v235, 6
	v_readlane_b32 s82, v235, 7
	v_readlane_b32 s83, v235, 8
	v_readlane_b32 s84, v235, 9
	v_readlane_b32 s85, v235, 10
	v_readlane_b32 s88, v235, 13
	v_readlane_b32 s89, v235, 14
	v_readlane_b32 s90, v235, 15
	v_readlane_b32 s91, v235, 16
	s_and_saveexec_b64 s[60:61], vcc
	s_xor_b64 s[60:61], exec, s[60:61]
	s_cbranch_execz .LBB0_556
	v_readlane_b32 s76, v235, 1
	v_readlane_b32 s88, v235, 13
	v_readlane_b32 s89, v235, 14
	v_readlane_b32 s77, v235, 2
	v_readlane_b32 s78, v235, 3
	v_readlane_b32 s79, v235, 4
	v_readlane_b32 s80, v235, 5
	v_readlane_b32 s81, v235, 6
	v_readlane_b32 s82, v235, 7
	v_readlane_b32 s83, v235, 8
	v_readlane_b32 s84, v235, 9
	v_readlane_b32 s85, v235, 10
	v_readlane_b32 s86, v235, 11
	v_readlane_b32 s87, v235, 12
	v_readlane_b32 s90, v235, 15
	v_readlane_b32 s91, v235, 16
	v_mov_b64_e32 v[2:3], s[88:89]
.LBB0_556:
	s_or_saveexec_b64 s[60:61], s[60:61]
	v_mov_b64_e32 v[12:13], 0x800
	v_mov_b64_e32 v[14:15], s[12:13]
	s_xor_b64 exec, exec, s[60:61]
	v_mov_b64_e32 v[12:13], 0x400
	v_mov_b64_e32 v[14:15], s[14:15]
	s_or_b64 exec, exec, s[60:61]
	v_mov_b32_e32 v0, 0x800
	v_mov_b32_e32 v17, 0
	s_or_b64 s[54:55], s[54:55], exec

.LBB0_560:
	s_or_saveexec_b64 s[56:57], s[56:57]
	s_mov_b64 s[58:59], 0
	s_xor_b64 exec, exec, s[56:57]
	s_cbranch_execz .LBB0_572
	v_cmp_lt_i32_e32 vcc, 1, v16
	s_and_saveexec_b64 s[62:63], vcc
	s_xor_b64 s[62:63], exec, s[62:63]
	s_cbranch_execz .LBB0_567
	v_cmp_lt_i32_e32 vcc, 2, v16
	v_mov_b64_e32 v[2:3], s[40:41]
	s_and_saveexec_b64 s[58:59], vcc
	s_xor_b64 s[58:59], exec, s[58:59]
	s_cbranch_execz .LBB0_564
	v_readlane_b32 s76, v235, 1
	v_readlane_b32 s82, v235, 7
	v_readlane_b32 s83, v235, 8
	v_readlane_b32 s77, v235, 2
	v_readlane_b32 s78, v235, 3
	v_readlane_b32 s79, v235, 4
	v_readlane_b32 s80, v235, 5
	v_readlane_b32 s81, v235, 6
	v_readlane_b32 s84, v235, 9
	v_readlane_b32 s85, v235, 10
	v_readlane_b32 s86, v235, 11
	v_readlane_b32 s87, v235, 12
	v_readlane_b32 s88, v235, 13
	v_readlane_b32 s89, v235, 14
	v_readlane_b32 s90, v235, 15
	v_readlane_b32 s91, v235, 16
	v_mov_b64_e32 v[2:3], s[82:83]
.LBB0_564:
	s_or_saveexec_b64 s[64:65], s[58:59]
	v_mov_b64_e32 v[12:13], 0x800
	v_mov_b32_e32 v0, 0x2e00
	s_mov_b64 s[58:59], 0
	s_mov_b64 s[60:61], -1
	v_mov_b64_e32 v[14:15], s[26:27]
	s_xor_b64 exec, exec, s[64:65]
	s_mov_b64 s[58:59], exec
	v_mov_b64_e32 v[12:13], 0x1600
	v_mov_b32_e32 v0, 0x800
	v_mov_b64_e32 v[14:15], s[2:3]
	s_xor_b64 s[60:61], exec, -1
	s_or_b64 exec, exec, s[64:65]
.LBB0_567:
	s_or_saveexec_b64 s[62:63], s[62:63]
	v_mov_b32_e32 v17, 0
	s_xor_b64 exec, exec, s[62:63]
	s_cbranch_execz .LBB0_571
	v_cmp_lt_i32_e32 vcc, 0, v16
	v_mov_b64_e32 v[2:3], s[36:37]
	s_and_saveexec_b64 s[64:65], vcc
	v_mov_b32_e32 v16, 0x80
	v_mov_b64_e32 v[2:3], s[38:39]
	s_or_b64 exec, exec, s[64:65]
	v_mov_b64_e32 v[12:13], 0x800
	v_mov_b32_e32 v0, 0x1600
	v_mov_b64_e32 v[14:15], s[28:29]
	s_andn2_b64 s[60:61], s[60:61], exec
	s_andn2_b64 s[58:59], s[58:59], exec
	v_mov_b32_e32 v17, v16

.LBB0_572:
	s_or_b64 exec, exec, s[56:57]
	v_lshrrev_b32_e32 v18, 5, v0
	v_cvt_f32_u32_e32 v16, v18
	v_sub_u32_e32 v25, 0, v18
	v_sub_u32_e32 v24, 0, v11
	v_max_i32_e32 v24, v11, v24
	v_rcp_iflag_f32_e32 v16, v16
	v_ashrrev_i32_e32 v19, 31, v11
	s_xor_b64 s[56:57], s[54:55], -1
	v_mul_f32_e32 v16, 0x4f7ffffe, v16
	v_cvt_u32_f32_e32 v16, v16
	v_mul_lo_u32 v25, v25, v16
	v_mul_hi_u32 v25, v16, v25
	v_add_u32_e32 v16, v16, v25
	v_mul_hi_u32 v16, v24, v16
	v_mul_lo_u32 v25, v16, v18
	v_sub_u32_e32 v24, v24, v25
	v_add_u32_e32 v26, 1, v16
	v_cmp_ge_u32_e32 vcc, v24, v18
	v_sub_u32_e32 v25, v24, v18
	s_nop 0
	v_cndmask_b32_e32 v16, v16, v26, vcc
	v_cndmask_b32_e32 v24, v24, v25, vcc
	v_add_u32_e32 v25, 1, v16
	v_cmp_ge_u32_e32 vcc, v24, v18
	s_nop 1
	v_cndmask_b32_e32 v16, v16, v25, vcc
	v_xor_b32_e32 v16, v16, v19
	v_sub_u32_e32 v16, v16, v19
	v_mul_lo_u32 v18, v16, v18
	v_sub_u32_e32 v11, v11, v18
	v_lshlrev_b32_e32 v18, 5, v11
	v_mov_b32_e32 v24, v18
	s_and_saveexec_b64 s[54:55], s[56:57]
	s_cbranch_execz .LBB0_580
	s_xor_b64 s[56:57], s[58:59], -1
	s_and_saveexec_b64 s[58:59], s[56:57]
	s_xor_b64 s[56:57], exec, s[58:59]
	v_lshlrev_b32_e32 v11, 6, v11
	v_and_b32_e32 v11, 0xffffff00, v11
	v_and_b32_e32 v19, 0x60, v18
	v_or3_b32 v24, v19, v17, v11
	s_andn2_saveexec_b64 s[56:57], s[56:57]
	s_cbranch_execz .LBB0_579
	v_add_u32_e32 v17, 0xfffff200, v18
	v_cmp_lt_u32_e32 vcc, s71, v17
	v_mov_b32_e32 v24, v18
	s_and_saveexec_b64 s[58:59], vcc
	s_cbranch_execz .LBB0_578
	v_lshlrev_b32_e32 v11, 6, v11
	v_and_b32_e32 v11, 0x80, v11
	v_add_u32_e32 v17, 0xfffffa00, v18
	v_lshrrev_b32_e32 v24, 1, v18
	v_and_or_b32 v11, v18, 32, v11
	v_and_b32_e32 v19, 0x300, v17
	v_and_b32_e32 v24, 64, v24
	v_and_or_b32 v11, v17, s70, v11
	v_or3_b32 v11, v11, v19, v24
	v_add_u32_e32 v24, 0x600, v11

.LBB0_581:
	s_lshl_b32 s57, s54, 1
	s_lshl_b32 s58, s55, 1
	v_or_b32_e32 v11, s57, v1
	v_or_b32_e32 v17, s58, v4
	s_add_i32 s59, s57, 4
	s_add_i32 s60, s58, 4
	s_add_i32 s61, s57, 8
	s_add_i32 s62, s58, 8
	s_add_i32 s63, s57, 12
	s_add_i32 s64, s58, 12
	s_add_i32 s65, s57, 16
	s_add_i32 s66, s58, 16
	s_add_i32 s67, s57, 20
	s_add_i32 s73, s58, 20
	s_add_i32 s74, s57, 24
	s_add_i32 s75, s58, 24
	s_add_i32 s57, s57, 28
	s_add_i32 s58, s58, 28
	v_add_u32_e32 v25, v11, v3
	v_add_u32_e32 v28, v17, v16
	v_or_b32_e32 v87, s59, v1
	v_or_b32_e32 v89, s60, v4
	v_or_b32_e32 v90, s61, v1
	v_or_b32_e32 v91, s62, v4
	v_or_b32_e32 v92, s63, v1
	v_or_b32_e32 v93, s64, v4
	v_or_b32_e32 v94, s65, v1
	v_or_b32_e32 v95, s66, v4
	v_or_b32_e32 v96, s67, v1
	v_or_b32_e32 v97, s73, v4
	v_or_b32_e32 v98, s74, v1
	v_or_b32_e32 v99, s75, v4
	v_or_b32_e32 v100, s57, v1
	v_or_b32_e32 v101, s58, v4
	v_ashrrev_i32_e32 v33, 31, v28
	v_ashrrev_i32_e32 v31, 31, v25
	v_mad_u64_u32 v[26:27], s[58:59], v2, v25, 0
	v_mad_u64_u32 v[28:29], s[58:59], v0, v28, 0
	v_add_u32_e32 v25, v87, v3
	v_add_u32_e32 v36, v89, v16
	v_add_u32_e32 v38, v90, v3
	v_add_u32_e32 v40, v91, v16
	v_add_u32_e32 v42, v92, v3
	v_add_u32_e32 v44, v93, v16
	v_add_u32_e32 v46, v94, v3
	v_add_u32_e32 v48, v95, v16
	v_add_u32_e32 v50, v96, v3
	v_add_u32_e32 v52, v97, v16
	v_add_u32_e32 v54, v98, v3
	v_add_u32_e32 v56, v99, v16
	v_add_u32_e32 v58, v100, v3
	v_add_u32_e32 v60, v101, v16
	v_mov_b32_e32 v30, v27
	v_mov_b32_e32 v32, v29
	v_ashrrev_i32_e32 v63, 31, v36
	v_ashrrev_i32_e32 v65, 31, v25
	v_mad_u64_u32 v[34:35], s[58:59], v2, v25, 0
	v_mad_u64_u32 v[36:37], s[58:59], v0, v36, 0
	v_ashrrev_i32_e32 v25, 31, v40
	v_ashrrev_i32_e32 v67, 31, v38
	v_mad_u64_u32 v[38:39], s[58:59], v2, v38, 0
	v_mad_u64_u32 v[40:41], s[58:59], v0, v40, 0
	v_ashrrev_i32_e32 v69, 31, v44
	v_ashrrev_i32_e32 v71, 31, v42
	v_mad_u64_u32 v[42:43], s[58:59], v2, v42, 0
	v_mad_u64_u32 v[44:45], s[58:59], v0, v44, 0
	v_ashrrev_i32_e32 v73, 31, v48
	v_ashrrev_i32_e32 v75, 31, v46
	v_mad_u64_u32 v[46:47], s[58:59], v2, v46, 0
	v_mad_u64_u32 v[48:49], s[58:59], v0, v48, 0
	v_ashrrev_i32_e32 v77, 31, v52
	v_ashrrev_i32_e32 v79, 31, v50
	v_mad_u64_u32 v[50:51], s[58:59], v2, v50, 0
	v_mad_u64_u32 v[52:53], s[58:59], v0, v52, 0
	v_ashrrev_i32_e32 v81, 31, v56
	v_ashrrev_i32_e32 v83, 31, v54
	v_mad_u64_u32 v[54:55], s[58:59], v2, v54, 0
	v_mad_u64_u32 v[56:57], s[58:59], v0, v56, 0
	v_ashrrev_i32_e32 v85, 31, v60
	v_ashrrev_i32_e32 v102, 31, v58
	v_mad_u64_u32 v[58:59], s[58:59], v2, v58, 0
	v_mad_u64_u32 v[60:61], s[58:59], v0, v60, 0
	v_mad_u64_u32 v[30:31], s[58:59], v2, v31, v[30:31]
	v_mad_u64_u32 v[32:33], s[58:59], v0, v33, v[32:33]
	v_mov_b32_e32 v62, v35
	v_mov_b32_e32 v64, v37
	v_mov_b32_e32 v66, v39
	v_mov_b32_e32 v68, v41
	v_mov_b32_e32 v70, v43
	v_mov_b32_e32 v72, v45
	v_mov_b32_e32 v74, v47
	v_mov_b32_e32 v76, v49
	v_mov_b32_e32 v78, v51
	v_mov_b32_e32 v80, v53
	v_mov_b32_e32 v82, v55
	v_mov_b32_e32 v84, v57
	v_mov_b32_e32 v86, v59
	v_mov_b32_e32 v88, v61
	v_mov_b32_e32 v27, v30
	v_mov_b32_e32 v29, v32
	v_mad_u64_u32 v[30:31], s[58:59], v2, v65, v[62:63]
	v_mad_u64_u32 v[32:33], s[58:59], v0, v63, v[64:65]
	v_mad_u64_u32 v[62:63], s[58:59], v2, v67, v[66:67]
	v_mad_u64_u32 v[64:65], s[58:59], v0, v25, v[68:69]
	v_mad_u64_u32 v[66:67], s[58:59], v2, v71, v[70:71]
	v_mad_u64_u32 v[68:69], s[58:59], v0, v69, v[72:73]
	v_mad_u64_u32 v[70:71], s[58:59], v2, v75, v[74:75]
	v_mad_u64_u32 v[72:73], s[58:59], v0, v73, v[76:77]
	v_mad_u64_u32 v[74:75], s[58:59], v2, v79, v[78:79]
	v_mad_u64_u32 v[76:77], s[58:59], v0, v77, v[80:81]
	v_mad_u64_u32 v[78:79], s[58:59], v2, v83, v[82:83]
	v_mad_u64_u32 v[80:81], s[58:59], v0, v81, v[84:85]
	v_mad_u64_u32 v[82:83], s[58:59], v2, v102, v[86:87]
	v_mad_u64_u32 v[84:85], s[58:59], v0, v85, v[88:89]
	v_lshl_add_u64 v[28:29], v[28:29], 2, v[18:19]
	v_mov_b32_e32 v35, v30
	v_mov_b32_e32 v37, v32
	v_mov_b32_e32 v39, v62
	v_mov_b32_e32 v41, v64
	v_mov_b32_e32 v43, v66
	v_mov_b32_e32 v45, v68
	v_mov_b32_e32 v47, v70
	v_mov_b32_e32 v49, v72
	v_mov_b32_e32 v51, v74
	v_mov_b32_e32 v53, v76
	v_mov_b32_e32 v55, v78
	v_mov_b32_e32 v57, v80
	v_mov_b32_e32 v59, v82
	v_mov_b32_e32 v61, v84
	v_lshl_add_u64 v[26:27], v[26:27], 2, v[18:19]
	v_lshl_add_u64 v[30:31], v[36:37], 2, v[18:19]
	v_lshl_add_u64 v[32:33], v[34:35], 2, v[18:19]
	v_lshl_add_u64 v[34:35], v[40:41], 2, v[18:19]
	v_lshl_add_u64 v[36:37], v[38:39], 2, v[18:19]
	v_lshl_add_u64 v[38:39], v[44:45], 2, v[18:19]
	v_lshl_add_u64 v[40:41], v[42:43], 2, v[18:19]
	v_lshl_add_u64 v[42:43], v[48:49], 2, v[18:19]
	v_lshl_add_u64 v[44:45], v[46:47], 2, v[18:19]
	v_lshl_add_u64 v[46:47], v[52:53], 2, v[18:19]
	v_lshl_add_u64 v[48:49], v[50:51], 2, v[18:19]
	v_lshl_add_u64 v[50:51], v[56:57], 2, v[18:19]
	v_lshl_add_u64 v[52:53], v[54:55], 2, v[18:19]
	v_lshl_add_u64 v[54:55], v[60:61], 2, v[18:19]
	v_lshl_add_u64 v[56:57], v[58:59], 2, v[18:19]
	global_load_dword v25, v[28:29], off
	global_load_dword v58, v[26:27], off
	global_load_dword v59, v[30:31], off
	global_load_dword v60, v[32:33], off
	global_load_dword v61, v[34:35], off
	global_load_dword v62, v[36:37], off
	global_load_dword v63, v[38:39], off
	global_load_dword v64, v[40:41], off
	global_load_dword v65, v[42:43], off
	global_load_dword v66, v[44:45], off
	global_load_dword v67, v[46:47], off
	global_load_dword v68, v[48:49], off
	global_load_dword v69, v[50:51], off
	global_load_dword v70, v[52:53], off
	global_load_dword v71, v[54:55], off
	global_load_dword v72, v[56:57], off
	s_add_i32 s55, s55, 16
	s_add_i32 s54, s54, 16
	s_add_i32 s56, s56, -16
	v_mad_u64_u32 v[26:27], s[58:59], v17, s68, v[8:9]
	s_cmp_lg_u32 s56, 0
	v_mad_u64_u32 v[28:29], s[58:59], v11, s68, v[8:9]
	v_mad_u64_u32 v[30:31], s[58:59], v89, s68, v[8:9]
	v_mad_u64_u32 v[32:33], s[58:59], v87, s68, v[8:9]
	v_mad_u64_u32 v[34:35], s[58:59], v91, s68, v[8:9]
	v_mad_u64_u32 v[36:37], s[58:59], v90, s68, v[8:9]
	v_mad_u64_u32 v[38:39], s[58:59], v93, s68, v[8:9]
	v_mad_u64_u32 v[40:41], s[58:59], v92, s68, v[8:9]
	v_mad_u64_u32 v[42:43], s[58:59], v95, s68, v[8:9]
	v_mad_u64_u32 v[44:45], s[58:59], v94, s68, v[8:9]
	v_mad_u64_u32 v[46:47], s[58:59], v97, s68, v[8:9]
	v_mad_u64_u32 v[48:49], s[58:59], v96, s68, v[8:9]
	v_mad_u64_u32 v[50:51], s[58:59], v99, s68, v[8:9]
	v_mad_u64_u32 v[52:53], s[58:59], v98, s68, v[8:9]
	v_mad_u64_u32 v[54:55], s[58:59], v101, s68, v[8:9]
	v_mad_u64_u32 v[56:57], s[58:59], v100, s68, v[8:9]
	s_waitcnt vmcnt(15)
	ds_write_b32 v26, v25
	s_waitcnt vmcnt(14)
	ds_write_b32 v28, v58
	s_waitcnt vmcnt(13)
	ds_write_b32 v30, v59
	s_waitcnt vmcnt(12)
	ds_write_b32 v32, v60
	s_waitcnt vmcnt(11)
	ds_write_b32 v34, v61
	s_waitcnt vmcnt(10)
	ds_write_b32 v36, v62
	s_waitcnt vmcnt(9)
	ds_write_b32 v38, v63
	s_waitcnt vmcnt(8)
	ds_write_b32 v40, v64
	s_waitcnt vmcnt(7)
	ds_write_b32 v42, v65
	s_waitcnt vmcnt(6)
	ds_write_b32 v44, v66
	s_waitcnt vmcnt(5)
	ds_write_b32 v46, v67
	s_waitcnt vmcnt(4)
	ds_write_b32 v48, v68
	s_waitcnt vmcnt(3)
	ds_write_b32 v50, v69
	s_waitcnt vmcnt(2)
	ds_write_b32 v52, v70
	s_waitcnt vmcnt(1)
	ds_write_b32 v54, v71
	s_waitcnt vmcnt(0)
	ds_write_b32 v56, v72
	s_cbranch_scc1 .LBB0_581
	s_waitcnt lgkmcnt(0)
	v_ashrrev_i32_e32 v17, 31, v16
	ds_read2_b32 v[18:19], v20 offset0:33 offset1:41
	ds_read2_b32 v[26:27], v20 offset1:8
	ds_read2_b32 v[28:29], v20 offset0:66 offset1:74
	ds_read2_b32 v[30:31], v20 offset0:99 offset1:107
	ds_read2_b32 v[32:33], v20 offset0:132 offset1:140
	ds_read2_b32 v[34:35], v20 offset0:165 offset1:173
	ds_read2_b32 v[36:37], v20 offset0:198 offset1:206
	ds_read2_b32 v[38:39], v20 offset0:231 offset1:239
	v_lshl_add_u64 v[2:3], v[16:17], 1, v[14:15]
	v_mov_b32_e32 v11, v7
	v_add_u32_e32 v0, v24, v9
	v_lshl_add_u64 v[2:3], v[2:3], 0, v[10:11]
	v_ashrrev_i32_e32 v11, 31, v0
	s_waitcnt lgkmcnt(6)
	v_cvt_pk_bf16_f32 v14, v26, v18
	v_mul_lo_u32 v11, v12, v11
	v_mul_lo_u32 v18, v13, v0
	v_mad_u64_u32 v[40:41], s[54:55], v12, v0, 0
	v_add3_u32 v41, v41, v11, v18
	s_waitcnt lgkmcnt(4)
	v_cvt_pk_bf16_f32 v15, v28, v30
	s_waitcnt lgkmcnt(2)
	v_cvt_pk_bf16_f32 v16, v32, v34
	s_waitcnt lgkmcnt(0)
	v_cvt_pk_bf16_f32 v17, v36, v38
	v_lshl_add_u64 v[40:41], v[40:41], 1, v[2:3]
	v_add_u32_e32 v0, v24, v21
	global_store_dwordx4 v[40:41], v[14:17], off
	v_ashrrev_i32_e32 v11, 31, v0
	v_mul_lo_u32 v11, v12, v11
	v_cvt_pk_bf16_f32 v14, v27, v19
	v_cvt_pk_bf16_f32 v15, v29, v31
	v_cvt_pk_bf16_f32 v16, v33, v35
	v_cvt_pk_bf16_f32 v17, v37, v39
	v_mul_lo_u32 v25, v13, v0
	v_mad_u64_u32 v[18:19], s[54:55], v12, v0, 0
	ds_read2_b32 v[26:27], v20 offset0:16 offset1:24
	ds_read2_b32 v[28:29], v20 offset0:49 offset1:57
	ds_read2_b32 v[30:31], v20 offset0:82 offset1:90
	ds_read2_b32 v[32:33], v20 offset0:115 offset1:123
	ds_read2_b32 v[34:35], v20 offset0:148 offset1:156
	ds_read2_b32 v[36:37], v20 offset0:181 offset1:189
	ds_read2_b32 v[38:39], v20 offset0:214 offset1:222
	ds_read2_b32 v[40:41], v20 offset0:247 offset1:255
	v_add3_u32 v19, v19, v11, v25
	v_add_u32_e32 v0, v24, v22
	v_lshl_add_u64 v[18:19], v[18:19], 1, v[2:3]
	v_ashrrev_i32_e32 v11, 31, v0
	global_store_dwordx4 v[18:19], v[14:17], off
	v_mul_lo_u32 v11, v12, v11
	v_mul_lo_u32 v25, v13, v0
	v_mad_u64_u32 v[18:19], s[54:55], v12, v0, 0
	v_add3_u32 v19, v19, v11, v25
	v_add_u32_e32 v0, v24, v23
	s_waitcnt lgkmcnt(6)
	v_cvt_pk_bf16_f32 v14, v26, v28
	s_waitcnt lgkmcnt(4)
	v_cvt_pk_bf16_f32 v15, v30, v32
	s_waitcnt lgkmcnt(2)
	v_cvt_pk_bf16_f32 v16, v34, v36
	s_waitcnt lgkmcnt(0)
	v_cvt_pk_bf16_f32 v17, v38, v40
	v_lshl_add_u64 v[18:19], v[18:19], 1, v[2:3]
	v_ashrrev_i32_e32 v11, 31, v0
	global_store_dwordx4 v[18:19], v[14:17], off
	v_mul_lo_u32 v11, v12, v11
	v_mul_lo_u32 v18, v13, v0
	v_mad_u64_u32 v[12:13], s[54:55], v12, v0, 0
	v_add3_u32 v13, v13, v11, v18
	v_cvt_pk_bf16_f32 v14, v27, v29
	v_cvt_pk_bf16_f32 v15, v31, v33
	v_cvt_pk_bf16_f32 v16, v35, v37
	v_cvt_pk_bf16_f32 v17, v39, v41
	v_lshl_add_u64 v[2:3], v[12:13], 1, v[2:3]
	global_store_dwordx4 v[2:3], v[14:17], off
	v_add_u32_e32 v5, s35, v5
	s_waitcnt lgkmcnt(0)
	v_cmp_lt_i32_e32 vcc, s72, v5
	s_or_b64 s[52:53], vcc, s[52:53]
	s_andn2_b64 exec, exec, s[52:53]
	s_cbranch_execnz .LBB0_512

.LBB0_584:
	s_cbranch_execz .LBB0_597
	s_and_b64 vcc, exec, s[4:5]
	s_cbranch_vccz .LBB0_671
.LBB0_586:
	s_cmp_lt_i32 s34, s33
	s_cbranch_scc1 .LBB0_595
	s_sub_i32 s2, s34, s33
	v_lshrrev_b32_e32 v0, 6, v128
	v_lshl_add_u32 v1, s2, 3, v0
	v_add_u32_e32 v12, 0x2280, v1
	s_movk_i32 s2, 0x2e00
	v_cmp_gt_i32_e32 vcc, s2, v12
	s_and_saveexec_b64 s[2:3], vcc
	s_cbranch_execz .LBB0_594
	s_sub_i32 s4, s94, s33
	s_waitcnt vmcnt(0)
	v_lshlrev_b32_e32 v3, 3, v128
	s_lshl_b32 s8, s4, 3
	s_movk_i32 s4, 0x2200
	v_lshlrev_b32_e32 v2, 2, v128
	v_bfe_u32 v13, v128, 3, 3
	v_and_b32_e32 v3, 56, v3
	v_readlane_b32 s52, v235, 1
	v_mad_u32_u24 v1, v0, s4, 0
	v_and_b32_e32 v6, 0x7c, v2
	v_mul_u32_u24_e32 v4, 0x84, v3
	v_lshlrev_b32_e32 v5, 2, v13
	v_mov_b32_e32 v7, 0
	v_readlane_b32 s58, v235, 7
	v_readlane_b32 s59, v235, 8
	v_add_u32_e32 v2, v1, v6
	v_add3_u32 v14, v1, v4, v5
	v_lshl_add_u64 v[4:5], s[58:59], 0, v[6:7]
	v_lshlrev_b32_e32 v6, 1, v3
	v_bfe_u32 v0, v128, 5, 1
	v_lshl_add_u64 v[6:7], s[50:51], 0, v[6:7]
	s_mov_b64 s[4:5], 0x4204000
	s_movk_i32 s9, 0x84
	v_or_b32_e32 v15, 8, v13
	v_or_b32_e32 v16, 16, v13
	v_or_b32_e32 v17, 24, v13
	v_mov_b32_e32 v1, v0
	v_lshl_add_u64 v[6:7], v[6:7], 0, s[4:5]
	s_mov_b64 s[4:5], 0
	s_mov_b32 s10, 0xb21642c9
	s_movk_i32 s11, 0xfe90
	s_movk_i32 s12, 0xf7ff
	s_movk_i32 s13, 0xfc00
	s_mov_b32 s14, 0xb800
	s_movk_i32 s15, 0x2dff
	v_readlane_b32 s53, v235, 2
	v_readlane_b32 s54, v235, 3
	v_readlane_b32 s55, v235, 4
	v_readlane_b32 s56, v235, 5
	v_readlane_b32 s57, v235, 6
	v_readlane_b32 s60, v235, 9
	v_readlane_b32 s61, v235, 10
	v_readlane_b32 s62, v235, 11
	v_readlane_b32 s63, v235, 12
	v_readlane_b32 s64, v235, 13
	v_readlane_b32 s65, v235, 14
	v_readlane_b32 s66, v235, 15
	v_readlane_b32 s67, v235, 16

.LBB0_591:
	s_or_b64 exec, exec, s[6:7]
	v_lshlrev_b32_e32 v8, 6, v3
	v_ashrrev_i32_e32 v11, 31, v10
	v_lshl_add_u64 v[10:11], v[10:11], 2, v[4:5]
	v_mov_b32_e32 v3, v8
	s_mov_b32 s6, 1
	s_mov_b32 s7, 0
	s_mov_b32 s26, 32
.LBB0_592:
	s_lshl_b32 s27, s6, 1
	s_lshl_b32 s28, s7, 1
	v_or_b32_e32 v9, s27, v1
	v_or_b32_e32 v19, s28, v0
	s_add_i32 s29, s27, 4
	s_add_i32 s30, s28, 4
	s_add_i32 s31, s27, 8
	s_add_i32 s33, s28, 8
	s_add_i32 s35, s27, 12
	s_add_i32 s52, s28, 12
	s_add_i32 s53, s27, 16
	s_add_i32 s54, s28, 16
	s_add_i32 s55, s27, 20
	s_add_i32 s56, s28, 20
	s_add_i32 s57, s27, 24
	s_add_i32 s58, s28, 24
	s_add_i32 s27, s27, 28
	s_add_i32 s28, s28, 28
	v_add_u32_e32 v20, v19, v8
	v_or_b32_e32 v52, s29, v1
	v_or_b32_e32 v53, s30, v0
	v_or_b32_e32 v54, s31, v1
	v_or_b32_e32 v55, s33, v0
	v_or_b32_e32 v56, s35, v1
	v_or_b32_e32 v57, s52, v0
	v_or_b32_e32 v58, s53, v1
	v_or_b32_e32 v59, s54, v0
	v_or_b32_e32 v60, s55, v1
	v_or_b32_e32 v61, s56, v0
	v_or_b32_e32 v62, s57, v1
	v_or_b32_e32 v63, s58, v0
	v_or_b32_e32 v64, s27, v1
	v_or_b32_e32 v65, s28, v0
	v_add_u32_e32 v22, v9, v3
	v_mad_i64_i32 v[20:21], s[28:29], v20, s14, v[10:11]
	v_add_u32_e32 v26, v52, v3
	v_add_u32_e32 v24, v53, v8
	v_add_u32_e32 v30, v54, v3
	v_add_u32_e32 v28, v55, v8
	v_add_u32_e32 v34, v56, v3
	v_add_u32_e32 v32, v57, v8
	v_add_u32_e32 v38, v58, v3
	v_add_u32_e32 v36, v59, v8
	v_add_u32_e32 v42, v60, v3
	v_add_u32_e32 v40, v61, v8
	v_add_u32_e32 v46, v62, v3
	v_add_u32_e32 v44, v63, v8
	v_add_u32_e32 v50, v64, v3
	v_add_u32_e32 v48, v65, v8
	v_mad_i64_i32 v[22:23], s[28:29], v22, s14, v[10:11]
	v_mad_i64_i32 v[24:25], s[28:29], v24, s14, v[10:11]
	v_mad_i64_i32 v[26:27], s[28:29], v26, s14, v[10:11]
	v_mad_i64_i32 v[28:29], s[28:29], v28, s14, v[10:11]
	v_mad_i64_i32 v[30:31], s[28:29], v30, s14, v[10:11]
	v_mad_i64_i32 v[32:33], s[28:29], v32, s14, v[10:11]
	v_mad_i64_i32 v[34:35], s[28:29], v34, s14, v[10:11]
	v_mad_i64_i32 v[36:37], s[28:29], v36, s14, v[10:11]
	v_mad_i64_i32 v[38:39], s[28:29], v38, s14, v[10:11]
	v_mad_i64_i32 v[40:41], s[28:29], v40, s14, v[10:11]
	v_mad_i64_i32 v[42:43], s[28:29], v42, s14, v[10:11]
	v_mad_i64_i32 v[44:45], s[28:29], v44, s14, v[10:11]
	v_mad_i64_i32 v[46:47], s[28:29], v46, s14, v[10:11]
	v_mad_i64_i32 v[48:49], s[28:29], v48, s14, v[10:11]
	v_mad_i64_i32 v[50:51], s[28:29], v50, s14, v[10:11]
	global_load_dword v66, v[20:21], off
	global_load_dword v67, v[22:23], off
	global_load_dword v68, v[24:25], off
	global_load_dword v69, v[26:27], off
	global_load_dword v70, v[28:29], off
	global_load_dword v71, v[30:31], off
	global_load_dword v72, v[32:33], off
	global_load_dword v73, v[34:35], off
	global_load_dword v74, v[36:37], off
	global_load_dword v75, v[38:39], off
	global_load_dword v76, v[40:41], off
	global_load_dword v77, v[42:43], off
	global_load_dword v78, v[44:45], off
	global_load_dword v79, v[46:47], off
	global_load_dword v80, v[48:49], off
	global_load_dword v81, v[50:51], off
	s_add_i32 s7, s7, 16
	s_add_i32 s6, s6, 16
	s_add_i32 s26, s26, -16
	v_mad_u64_u32 v[20:21], s[28:29], v19, s9, v[2:3]
	s_cmp_lg_u32 s26, 0
	v_mad_u64_u32 v[22:23], s[28:29], v9, s9, v[2:3]
	v_mad_u64_u32 v[24:25], s[28:29], v53, s9, v[2:3]
	v_mad_u64_u32 v[26:27], s[28:29], v52, s9, v[2:3]
	v_mad_u64_u32 v[28:29], s[28:29], v55, s9, v[2:3]
	v_mad_u64_u32 v[30:31], s[28:29], v54, s9, v[2:3]
	v_mad_u64_u32 v[32:33], s[28:29], v57, s9, v[2:3]
	v_mad_u64_u32 v[34:35], s[28:29], v56, s9, v[2:3]
	v_mad_u64_u32 v[36:37], s[28:29], v59, s9, v[2:3]
	v_mad_u64_u32 v[38:39], s[28:29], v58, s9, v[2:3]
	v_mad_u64_u32 v[40:41], s[28:29], v61, s9, v[2:3]
	v_mad_u64_u32 v[42:43], s[28:29], v60, s9, v[2:3]
	v_mad_u64_u32 v[44:45], s[28:29], v63, s9, v[2:3]
	v_mad_u64_u32 v[46:47], s[28:29], v62, s9, v[2:3]
	v_mad_u64_u32 v[48:49], s[28:29], v65, s9, v[2:3]
	v_mad_u64_u32 v[50:51], s[28:29], v64, s9, v[2:3]
	s_waitcnt vmcnt(15)
	ds_write_b32 v20, v66
	s_waitcnt vmcnt(14)
	ds_write_b32 v22, v67
	s_waitcnt vmcnt(13)
	ds_write_b32 v24, v68
	s_waitcnt vmcnt(12)
	ds_write_b32 v26, v69
	s_waitcnt vmcnt(11)
	ds_write_b32 v28, v70
	s_waitcnt vmcnt(10)
	ds_write_b32 v30, v71
	s_waitcnt vmcnt(9)
	ds_write_b32 v32, v72
	s_waitcnt vmcnt(8)
	ds_write_b32 v34, v73
	s_waitcnt vmcnt(7)
	ds_write_b32 v36, v74
	s_waitcnt vmcnt(6)
	ds_write_b32 v38, v75
	s_waitcnt vmcnt(5)
	ds_write_b32 v40, v76
	s_waitcnt vmcnt(4)
	ds_write_b32 v42, v77
	s_waitcnt vmcnt(3)
	ds_write_b32 v44, v78
	s_waitcnt vmcnt(2)
	ds_write_b32 v46, v79
	s_waitcnt vmcnt(1)
	ds_write_b32 v48, v80
	s_waitcnt vmcnt(0)
	ds_write_b32 v50, v81
	s_cbranch_scc1 .LBB0_592
	s_waitcnt lgkmcnt(0)
	ds_read2_b32 v[20:21], v14 offset0:33 offset1:41
	ds_read2_b32 v[22:23], v14 offset1:8
	ds_read2_b32 v[24:25], v14 offset0:66 offset1:74
	ds_read2_b32 v[26:27], v14 offset0:99 offset1:107
	ds_read2_b32 v[28:29], v14 offset0:132 offset1:140
	ds_read2_b32 v[30:31], v14 offset0:165 offset1:173
	ds_read2_b32 v[32:33], v14 offset0:198 offset1:206
	ds_read2_b32 v[34:35], v14 offset0:231 offset1:239
	v_add_u32_e32 v38, v18, v13
	v_ashrrev_i32_e32 v9, 31, v8
	v_ashrrev_i32_e32 v39, 31, v38
	v_lshl_add_u64 v[36:37], v[8:9], 1, v[6:7]
	v_lshlrev_b64 v[38:39], 12, v[38:39]
	s_waitcnt lgkmcnt(6)
	v_cvt_pk_bf16_f32 v8, v22, v20
	s_waitcnt lgkmcnt(4)
	v_cvt_pk_bf16_f32 v9, v24, v26
	s_waitcnt lgkmcnt(2)
	v_cvt_pk_bf16_f32 v10, v28, v30
	s_waitcnt lgkmcnt(0)
	v_cvt_pk_bf16_f32 v11, v32, v34
	v_lshl_add_u64 v[38:39], v[36:37], 0, v[38:39]
	v_add_u32_e32 v20, v18, v15
	global_store_dwordx4 v[38:39], v[8:11], off
	v_add_u32_e32 v12, s8, v12
	v_cmp_lt_i32_e32 vcc, s15, v12
	v_cvt_pk_bf16_f32 v8, v23, v21
	v_ashrrev_i32_e32 v21, 31, v20
	v_cvt_pk_bf16_f32 v9, v25, v27
	v_cvt_pk_bf16_f32 v10, v29, v31
	v_cvt_pk_bf16_f32 v11, v33, v35
	v_lshlrev_b64 v[20:21], 12, v[20:21]
	ds_read2_b32 v[22:23], v14 offset0:49 offset1:57
	ds_read2_b32 v[24:25], v14 offset0:16 offset1:24
	ds_read2_b32 v[26:27], v14 offset0:82 offset1:90
	ds_read2_b32 v[28:29], v14 offset0:115 offset1:123
	ds_read2_b32 v[30:31], v14 offset0:148 offset1:156
	ds_read2_b32 v[32:33], v14 offset0:181 offset1:189
	ds_read2_b32 v[34:35], v14 offset0:214 offset1:222
	ds_read2_b32 v[38:39], v14 offset0:247 offset1:255
	v_lshl_add_u64 v[20:21], v[36:37], 0, v[20:21]
	global_store_dwordx4 v[20:21], v[8:11], off
	v_add_u32_e32 v20, v18, v16
	v_ashrrev_i32_e32 v21, 31, v20
	v_add_u32_e32 v18, v18, v17
	v_lshlrev_b64 v[20:21], 12, v[20:21]
	v_ashrrev_i32_e32 v19, 31, v18
	s_waitcnt lgkmcnt(6)
	v_cvt_pk_bf16_f32 v8, v24, v22
	s_waitcnt lgkmcnt(4)
	v_cvt_pk_bf16_f32 v9, v26, v28
	s_waitcnt lgkmcnt(2)
	v_cvt_pk_bf16_f32 v10, v30, v32
	s_waitcnt lgkmcnt(0)
	v_cvt_pk_bf16_f32 v11, v34, v38
	v_lshl_add_u64 v[20:21], v[36:37], 0, v[20:21]
	v_lshlrev_b64 v[18:19], 12, v[18:19]
	global_store_dwordx4 v[20:21], v[8:11], off
	v_lshl_add_u64 v[18:19], v[36:37], 0, v[18:19]
	s_or_b64 s[4:5], vcc, s[4:5]
	v_cvt_pk_bf16_f32 v8, v25, v23
	v_cvt_pk_bf16_f32 v9, v27, v29
	v_cvt_pk_bf16_f32 v10, v31, v33
	v_cvt_pk_bf16_f32 v11, v35, v39
	global_store_dwordx4 v[18:19], v[8:11], off
	s_waitcnt lgkmcnt(0)
	s_andn2_b64 exec, exec, s[4:5]
	s_cbranch_execnz .LBB0_589

.LBB0_596:
.LBB0_597:
	v_lshrrev_b32_e32 v0, 6, v128
	v_lshl_add_u32 v5, s34, 3, v0
	s_movk_i32 s6, 0x1400
	v_cmp_gt_i32_e32 vcc, s6, v5
	s_and_saveexec_b64 s[6:7], vcc
	s_cbranch_execz .LBB0_670
	s_lshl_b32 s35, s94, 3
	s_movk_i32 s8, 0x2200
	v_mad_u32_u24 v1, v0, s8, 0
	s_add_u32 s8, s50, 0x8404000
	s_addc_u32 s9, s51, 0
	s_add_u32 s10, s50, 0x7c04000
	s_addc_u32 s11, s51, 0
	s_add_u32 s12, s50, 0x7404000
	s_addc_u32 s13, s51, 0
	s_add_u32 s14, s50, 0x7004000
	s_addc_u32 s15, s51, 0
	s_add_u32 s26, s50, 0x4204000
	s_addc_u32 s27, s51, 0
	s_add_u32 s28, s50, 0x4000
	s_waitcnt vmcnt(0)
	v_lshlrev_b32_e32 v2, 3, v128
	s_addc_u32 s29, s51, 0
	v_bfe_u32 v9, v128, 3, 3
	v_and_b32_e32 v2, 56, v2
	s_add_u32 s30, s50, 0xb004000
	v_bfe_u32 v4, v128, 5, 1
	v_and_b32_e32 v0, 31, v128
	v_mul_u32_u24_e32 v3, 0x84, v2
	v_lshlrev_b32_e32 v6, 2, v9
	s_addc_u32 s31, s51, 0
	v_mov_b32_e32 v7, 0
	v_lshl_add_u32 v8, v0, 2, v1
	s_movk_i32 s68, 0x84
	v_add3_u32 v20, v1, v3, v6
	v_or_b32_e32 v21, 8, v9
	v_or_b32_e32 v22, 16, v9
	v_or_b32_e32 v23, 24, v9
	v_mov_b32_e32 v1, v4
	s_mov_b64 s[52:53], 0
	s_movk_i32 s69, 0x3ff
	s_movk_i32 s70, 0xfc00
	s_movk_i32 s71, 0xf7ff
	v_lshlrev_b32_e32 v6, 2, v0
	v_lshlrev_b32_e32 v10, 1, v2
	s_movk_i32 s72, 0x13ff

.LBB0_670:
	s_or_b64 exec, exec, s[6:7]
	s_and_b64 vcc, exec, s[4:5]
	s_cbranch_vccnz .LBB0_586
.LBB0_671:
.LBB0_672:
	v_lshrrev_b32_e32 v0, 6, v128
	v_lshl_add_u32 v1, s34, 3, v0
	v_add_u32_e32 v12, 0x2280, v1
	s_movk_i32 s2, 0x2e00
	v_cmp_gt_i32_e32 vcc, s2, v12
	s_and_saveexec_b64 s[2:3], vcc
	s_cbranch_execz .LBB0_679
	s_waitcnt vmcnt(0)
	v_lshlrev_b32_e32 v3, 3, v128
	s_movk_i32 s4, 0x2200
	v_lshlrev_b32_e32 v2, 2, v128
	v_bfe_u32 v13, v128, 3, 3
	v_and_b32_e32 v3, 56, v3
	v_readlane_b32 s52, v235, 1
	v_mad_u32_u24 v1, v0, s4, 0
	v_and_b32_e32 v6, 0x7c, v2
	v_mul_u32_u24_e32 v4, 0x84, v3
	v_lshlrev_b32_e32 v5, 2, v13
	v_mov_b32_e32 v7, 0
	v_readlane_b32 s58, v235, 7
	v_readlane_b32 s59, v235, 8
	v_add_u32_e32 v2, v1, v6
	v_add3_u32 v14, v1, v4, v5
	v_lshl_add_u64 v[4:5], s[58:59], 0, v[6:7]
	v_lshlrev_b32_e32 v6, 1, v3
	v_bfe_u32 v0, v128, 5, 1
	v_lshl_add_u64 v[6:7], s[50:51], 0, v[6:7]
	s_mov_b64 s[4:5], 0x4204000
	s_lshl_b32 s8, s94, 3
	s_movk_i32 s9, 0x84
	v_or_b32_e32 v15, 8, v13
	v_or_b32_e32 v16, 16, v13
	v_or_b32_e32 v17, 24, v13
	v_lshl_add_u64 v[6:7], v[6:7], 0, s[4:5]
	v_mov_b32_e32 v1, v0
	s_mov_b64 s[4:5], 0
	s_mov_b32 s10, 0xb21642c9
	s_movk_i32 s11, 0xfe90
	s_movk_i32 s12, 0xf7ff
	s_movk_i32 s13, 0xfc00
	s_mov_b32 s14, 0xb800
	s_movk_i32 s15, 0x2dff
	v_readlane_b32 s53, v235, 2
	v_readlane_b32 s54, v235, 3
	v_readlane_b32 s55, v235, 4
	v_readlane_b32 s56, v235, 5
	v_readlane_b32 s57, v235, 6
	v_readlane_b32 s60, v235, 9
	v_readlane_b32 s61, v235, 10
	v_readlane_b32 s62, v235, 11
	v_readlane_b32 s63, v235, 12
	v_readlane_b32 s64, v235, 13
	v_readlane_b32 s65, v235, 14
	v_readlane_b32 s66, v235, 15
	v_readlane_b32 s67, v235, 16

.LBB0_679:
	s_or_b64 exec, exec, s[2:3]
.LBB0_680:
	s_cmp_lt_i32 s92, 6
	s_cselect_b64 s[2:3], -1, 0
	s_cmp_gt_i32 s93, 5
	s_cselect_b64 s[4:5], -1, 0
	s_and_b64 s[4:5], s[2:3], s[4:5]
	s_andn2_b64 vcc, exec, s[4:5]
	s_cbranch_vccnz .LBB0_743
	s_andn2_b64 vcc, exec, s[0:1]
	s_cbranch_vccnz .LBB0_735
	s_waitcnt vmcnt(0)
	s_waitcnt vmcnt(0)
	s_barrier
	s_mov_b64 s[0:1], exec
	v_readlane_b32 s4, v235, 17
	v_readlane_b32 s5, v235, 18
	s_and_b64 s[4:5], s[0:1], s[4:5]
	s_mov_b64 exec, s[4:5]
	s_cbranch_execz .LBB0_734
	s_add_i32 s4, 0, 0x23ff0
	v_mov_b32_e32 v0, s4
	s_waitcnt vmcnt(0) expcnt(0) lgkmcnt(0)
	ds_read_b32 v2, v0
	s_add_i32 s4, 0, 0x23ff4
	v_mov_b32_e32 v0, s4
	ds_read_b32 v0, v0
	s_waitcnt lgkmcnt(1)
	v_cmp_ne_u32_e32 vcc, 0, v2
	s_cbranch_vccnz .LBB0_698
	v_readlane_b32 s4, v235, 0
	s_mul_i32 s28, s95, s4
	s_add_u32 s4, s50, 0x1000
	s_addc_u32 s5, s51, 0
	s_add_u32 s6, s50, 0x1100
	s_addc_u32 s7, s51, 0
	s_add_u32 s8, s50, 0x1200
	s_addc_u32 s9, s51, 0
	s_add_u32 s10, s50, 0x1300
	s_mul_i32 s28, s28, s94
	s_addc_u32 s11, s51, 0
	s_mov_b32 s29, 1
	v_mov_b32_e32 v16, 0
	s_branch .LBB0_686

.LBB0_900:
	s_abs_i32 s0, s94
	v_cvt_f32_u32_e32 v0, s0
	s_sub_i32 s1, 0, s0
	v_rcp_iflag_f32_e32 v0, v0
	s_nop 0
	v_mul_f32_e32 v0, 0x4f7ffffe, v0
	v_cvt_u32_f32_e32 v0, v0
	s_nop 0
	v_readfirstlane_b32 s2, v0
	s_mul_i32 s1, s1, s2
	s_mul_hi_u32 s1, s2, s1
	s_add_i32 s2, s2, s1
	s_mul_hi_u32 s1, s2, 0x678
	s_mul_i32 s1, s1, s0
	s_sub_i32 s1, 0x678, s1
	s_sub_i32 s2, s1, s0
	s_cmp_ge_u32 s1, s0
	s_cselect_b32 s1, s2, s1
	s_sub_i32 s2, s1, s0
	s_cmp_ge_u32 s1, s0
	s_cselect_b32 s2, s2, s1
	s_cmp_lg_u32 s2, 0
	s_cbranch_scc0 .LBB0_909
	s_cmp_lt_i32 s34, s2
	s_cbranch_scc1 .LBB0_908
	v_lshrrev_b32_e32 v1, 6, v128
	s_sub_i32 s0, s34, s2
	v_lshl_add_u32 v0, s0, 3, v1
	s_movk_i32 s0, 0x1600
	v_cmp_gt_i32_e32 vcc, s0, v0
	s_and_saveexec_b64 s[0:1], vcc
	s_cbranch_execz .LBB0_907
	s_waitcnt vmcnt(0)
	v_lshlrev_b32_e32 v3, 2, v128
	s_sub_i32 s2, s94, s2
	v_and_b32_e32 v8, 0x7c, v3
	v_lshlrev_b32_e32 v3, 3, v128
	s_lshl_b32 s4, s2, 3
	s_movk_i32 s2, 0x2200
	v_bfe_u32 v5, v128, 3, 3
	v_and_b32_e32 v3, 56, v3
	v_mad_u32_u24 v1, v1, s2, 0
	v_mul_u32_u24_e32 v6, 0x84, v3
	v_lshlrev_b32_e32 v7, 2, v5
	v_mov_b32_e32 v9, 0
	v_add_u32_e32 v4, v1, v8
	v_add3_u32 v18, v1, v6, v7
	v_lshl_add_u64 v[6:7], s[44:45], 0, v[8:9]
	v_lshlrev_b32_e32 v8, 1, v3
	v_bfe_u32 v2, v128, 5, 1
	v_lshl_add_u64 v[8:9], s[50:51], 0, v[8:9]
	s_mov_b64 s[2:3], 0x8404000
	s_movk_i32 s5, 0x84
	v_or_b32_e32 v19, 8, v5
	v_or_b32_e32 v20, 16, v5
	v_or_b32_e32 v21, 24, v5
	v_lshl_add_u64 v[8:9], v[8:9], 0, s[2:3]
	v_mov_b32_e32 v1, v2
	s_mov_b64 s[2:3], 0
	s_mov_b32 s8, 0x2e8ba2e9
	s_movk_i32 s9, 0xff50
	s_movk_i32 s10, 0x5800
	s_movk_i32 s11, 0x80
	s_movk_i32 s12, 0x15ff

.LBB0_905:
	s_lshl_b32 s16, s15, 1
	s_lshl_b32 s17, s14, 1
	v_or_b32_e32 v11, s16, v1
	v_or_b32_e32 v13, s17, v2
	s_add_i32 s18, s16, 4
	s_add_i32 s19, s17, 4
	s_add_i32 s26, s16, 8
	s_add_i32 s27, s17, 8
	s_add_i32 s28, s16, 12
	s_add_i32 s29, s17, 12
	s_add_i32 s30, s16, 16
	s_add_i32 s31, s17, 16
	s_add_i32 s33, s16, 20
	s_add_i32 s35, s17, 20
	s_add_i32 s52, s16, 24
	s_add_i32 s53, s17, 24
	s_add_i32 s16, s16, 28
	s_add_i32 s17, s17, 28
	v_add_u32_e32 v15, v11, v3
	v_add_u32_e32 v22, v13, v10
	v_or_b32_e32 v54, s18, v1
	v_or_b32_e32 v55, s19, v2
	v_or_b32_e32 v56, s26, v1
	v_or_b32_e32 v57, s27, v2
	v_or_b32_e32 v58, s28, v1
	v_or_b32_e32 v59, s29, v2
	v_or_b32_e32 v60, s30, v1
	v_or_b32_e32 v61, s31, v2
	v_or_b32_e32 v62, s33, v1
	v_or_b32_e32 v63, s35, v2
	v_or_b32_e32 v64, s52, v1
	v_or_b32_e32 v65, s53, v2
	v_or_b32_e32 v66, s16, v1
	v_or_b32_e32 v67, s17, v2
	v_mad_i64_i32 v[22:23], s[16:17], v22, s10, v[16:17]
	v_mad_i64_i32 v[24:25], s[16:17], v15, s10, v[16:17]
	v_add_u32_e32 v15, v54, v3
	v_add_u32_e32 v26, v55, v10
	v_add_u32_e32 v32, v56, v3
	v_add_u32_e32 v30, v57, v10
	v_add_u32_e32 v36, v58, v3
	v_add_u32_e32 v34, v59, v10
	v_add_u32_e32 v40, v60, v3
	v_add_u32_e32 v38, v61, v10
	v_add_u32_e32 v44, v62, v3
	v_add_u32_e32 v42, v63, v10
	v_add_u32_e32 v48, v64, v3
	v_add_u32_e32 v46, v65, v10
	v_add_u32_e32 v52, v66, v3
	v_add_u32_e32 v50, v67, v10
	v_mad_i64_i32 v[26:27], s[16:17], v26, s10, v[16:17]
	v_mad_i64_i32 v[28:29], s[16:17], v15, s10, v[16:17]
	v_mad_i64_i32 v[30:31], s[16:17], v30, s10, v[16:17]
	v_mad_i64_i32 v[32:33], s[16:17], v32, s10, v[16:17]
	v_mad_i64_i32 v[34:35], s[16:17], v34, s10, v[16:17]
	v_mad_i64_i32 v[36:37], s[16:17], v36, s10, v[16:17]
	v_mad_i64_i32 v[38:39], s[16:17], v38, s10, v[16:17]
	v_mad_i64_i32 v[40:41], s[16:17], v40, s10, v[16:17]
	v_mad_i64_i32 v[42:43], s[16:17], v42, s10, v[16:17]
	v_mad_i64_i32 v[44:45], s[16:17], v44, s10, v[16:17]
	v_mad_i64_i32 v[46:47], s[16:17], v46, s10, v[16:17]
	v_mad_i64_i32 v[48:49], s[16:17], v48, s10, v[16:17]
	v_mad_i64_i32 v[50:51], s[16:17], v50, s10, v[16:17]
	v_mad_i64_i32 v[52:53], s[16:17], v52, s10, v[16:17]
	global_load_dword v15, v[22:23], off
	global_load_dword v68, v[24:25], off
	global_load_dword v69, v[26:27], off
	global_load_dword v70, v[28:29], off
	global_load_dword v71, v[30:31], off
	global_load_dword v72, v[32:33], off
	global_load_dword v73, v[34:35], off
	global_load_dword v74, v[36:37], off
	global_load_dword v75, v[38:39], off
	global_load_dword v76, v[40:41], off
	global_load_dword v77, v[42:43], off
	global_load_dword v78, v[44:45], off
	global_load_dword v79, v[46:47], off
	global_load_dword v80, v[48:49], off
	global_load_dword v81, v[50:51], off
	global_load_dword v82, v[52:53], off
	s_add_i32 s14, s14, 16
	s_add_i32 s15, s15, 16
	s_add_i32 s13, s13, -16
	v_mad_u64_u32 v[22:23], s[16:17], v13, s5, v[4:5]
	s_cmp_lg_u32 s13, 0
	v_mad_u64_u32 v[24:25], s[16:17], v11, s5, v[4:5]
	v_mad_u64_u32 v[26:27], s[16:17], v55, s5, v[4:5]
	v_mad_u64_u32 v[28:29], s[16:17], v54, s5, v[4:5]
	v_mad_u64_u32 v[30:31], s[16:17], v57, s5, v[4:5]
	v_mad_u64_u32 v[32:33], s[16:17], v56, s5, v[4:5]
	v_mad_u64_u32 v[34:35], s[16:17], v59, s5, v[4:5]
	v_mad_u64_u32 v[36:37], s[16:17], v58, s5, v[4:5]
	v_mad_u64_u32 v[38:39], s[16:17], v61, s5, v[4:5]
	v_mad_u64_u32 v[40:41], s[16:17], v60, s5, v[4:5]
	v_mad_u64_u32 v[42:43], s[16:17], v63, s5, v[4:5]
	v_mad_u64_u32 v[44:45], s[16:17], v62, s5, v[4:5]
	v_mad_u64_u32 v[46:47], s[16:17], v65, s5, v[4:5]
	v_mad_u64_u32 v[48:49], s[16:17], v64, s5, v[4:5]
	v_mad_u64_u32 v[50:51], s[16:17], v67, s5, v[4:5]
	v_mad_u64_u32 v[52:53], s[16:17], v66, s5, v[4:5]
	s_waitcnt vmcnt(15)
	ds_write_b32 v22, v15
	s_waitcnt vmcnt(14)
	ds_write_b32 v24, v68
	s_waitcnt vmcnt(13)
	ds_write_b32 v26, v69
	s_waitcnt vmcnt(12)
	ds_write_b32 v28, v70
	s_waitcnt vmcnt(11)
	ds_write_b32 v30, v71
	s_waitcnt vmcnt(10)
	ds_write_b32 v32, v72
	s_waitcnt vmcnt(9)
	ds_write_b32 v34, v73
	s_waitcnt vmcnt(8)
	ds_write_b32 v36, v74
	s_waitcnt vmcnt(7)
	ds_write_b32 v38, v75
	s_waitcnt vmcnt(6)
	ds_write_b32 v40, v76
	s_waitcnt vmcnt(5)
	ds_write_b32 v42, v77
	s_waitcnt vmcnt(4)
	ds_write_b32 v44, v78
	s_waitcnt vmcnt(3)
	ds_write_b32 v46, v79
	s_waitcnt vmcnt(2)
	ds_write_b32 v48, v80
	s_waitcnt vmcnt(1)
	ds_write_b32 v50, v81
	s_waitcnt vmcnt(0)
	ds_write_b32 v52, v82
	s_cbranch_scc1 .LBB0_905
	v_lshlrev_b32_e32 v3, 6, v12
	s_waitcnt lgkmcnt(0)
	v_and_b32_e32 v3, 0xffffff00, v3
	v_and_b32_e32 v11, 0x60, v14
	ds_read2_b32 v[14:15], v18 offset0:33 offset1:41
	ds_read2_b32 v[16:17], v18 offset1:8
	ds_read2_b32 v[22:23], v18 offset0:66 offset1:74
	ds_read2_b32 v[24:25], v18 offset0:99 offset1:107
	ds_read2_b32 v[26:27], v18 offset0:132 offset1:140
	ds_read2_b32 v[28:29], v18 offset0:165 offset1:173
	ds_read2_b32 v[30:31], v18 offset0:198 offset1:206
	ds_read2_b32 v[32:33], v18 offset0:231 offset1:239
	v_or3_b32 v3, v11, v3, s11
	v_or_b32_e32 v36, v3, v5
	v_ashrrev_i32_e32 v11, 31, v10
	v_ashrrev_i32_e32 v37, 31, v36
	v_lshl_add_u64 v[34:35], v[10:11], 1, v[8:9]
	v_lshlrev_b64 v[36:37], 12, v[36:37]
	s_waitcnt lgkmcnt(6)
	v_cvt_pk_bf16_f32 v10, v16, v14
	s_waitcnt lgkmcnt(4)
	v_cvt_pk_bf16_f32 v11, v22, v24
	s_waitcnt lgkmcnt(2)
	v_cvt_pk_bf16_f32 v12, v26, v28
	s_waitcnt lgkmcnt(0)
	v_cvt_pk_bf16_f32 v13, v30, v32
	v_lshl_add_u64 v[36:37], v[34:35], 0, v[36:37]
	v_or_b32_e32 v14, v3, v19
	global_store_dwordx4 v[36:37], v[10:13], off
	v_add_u32_e32 v0, s4, v0
	v_cmp_lt_i32_e32 vcc, s12, v0
	v_cvt_pk_bf16_f32 v10, v17, v15
	v_ashrrev_i32_e32 v15, 31, v14
	v_cvt_pk_bf16_f32 v11, v23, v25
	v_cvt_pk_bf16_f32 v12, v27, v29
	v_cvt_pk_bf16_f32 v13, v31, v33
	v_lshlrev_b64 v[14:15], 12, v[14:15]
	ds_read2_b32 v[16:17], v18 offset0:49 offset1:57
	ds_read2_b32 v[22:23], v18 offset0:16 offset1:24
	ds_read2_b32 v[24:25], v18 offset0:82 offset1:90
	ds_read2_b32 v[26:27], v18 offset0:115 offset1:123
	ds_read2_b32 v[28:29], v18 offset0:148 offset1:156
	ds_read2_b32 v[30:31], v18 offset0:181 offset1:189
	ds_read2_b32 v[32:33], v18 offset0:214 offset1:222
	ds_read2_b32 v[36:37], v18 offset0:247 offset1:255
	v_lshl_add_u64 v[14:15], v[34:35], 0, v[14:15]
	global_store_dwordx4 v[14:15], v[10:13], off
	v_or_b32_e32 v14, v3, v20
	v_ashrrev_i32_e32 v15, 31, v14
	v_lshlrev_b64 v[14:15], 12, v[14:15]
	s_waitcnt lgkmcnt(6)
	v_cvt_pk_bf16_f32 v10, v22, v16
	s_waitcnt lgkmcnt(4)
	v_cvt_pk_bf16_f32 v11, v24, v26
	s_waitcnt lgkmcnt(2)
	v_cvt_pk_bf16_f32 v12, v28, v30
	s_waitcnt lgkmcnt(0)
	v_cvt_pk_bf16_f32 v13, v32, v36
	v_lshl_add_u64 v[14:15], v[34:35], 0, v[14:15]
	global_store_dwordx4 v[14:15], v[10:13], off
	v_or_b32_e32 v14, v3, v21
	v_ashrrev_i32_e32 v15, 31, v14
	v_lshlrev_b64 v[14:15], 12, v[14:15]
	v_cvt_pk_bf16_f32 v10, v23, v17
	v_cvt_pk_bf16_f32 v11, v25, v27
	v_cvt_pk_bf16_f32 v12, v29, v31
	v_cvt_pk_bf16_f32 v13, v33, v37
	v_lshl_add_u64 v[14:15], v[34:35], 0, v[14:15]
	global_store_dwordx4 v[14:15], v[10:13], off
	s_waitcnt lgkmcnt(0)
	s_or_b64 s[2:3], vcc, s[2:3]
	s_andn2_b64 exec, exec, s[2:3]
	s_cbranch_execnz .LBB0_904

.LBB0_909:
.LBB0_910:
	v_lshrrev_b32_e32 v1, 6, v128
	v_lshl_add_u32 v0, s34, 3, v1
	s_movk_i32 s0, 0x1600
	v_cmp_gt_i32_e32 vcc, s0, v0
	s_and_saveexec_b64 s[0:1], vcc
	s_cbranch_execz .LBB0_915
	s_waitcnt vmcnt(0)
	v_lshlrev_b32_e32 v3, 2, v128
	v_and_b32_e32 v8, 0x7c, v3
	v_lshlrev_b32_e32 v3, 3, v128
	s_movk_i32 s2, 0x2200
	v_bfe_u32 v5, v128, 3, 3
	v_and_b32_e32 v3, 56, v3
	v_mad_u32_u24 v1, v1, s2, 0
	v_mul_u32_u24_e32 v6, 0x84, v3
	v_lshlrev_b32_e32 v7, 2, v5
	v_mov_b32_e32 v9, 0
	v_add_u32_e32 v4, v1, v8
	v_add3_u32 v18, v1, v6, v7
	v_lshl_add_u64 v[6:7], s[44:45], 0, v[8:9]
	v_lshlrev_b32_e32 v8, 1, v3
	v_bfe_u32 v2, v128, 5, 1
	v_lshl_add_u64 v[8:9], s[50:51], 0, v[8:9]
	s_mov_b64 s[2:3], 0x8404000
	s_lshl_b32 s4, s94, 3
	s_movk_i32 s5, 0x84
	v_or_b32_e32 v19, 8, v5
	v_or_b32_e32 v20, 16, v5
	v_or_b32_e32 v21, 24, v5
	v_lshl_add_u64 v[8:9], v[8:9], 0, s[2:3]
	v_mov_b32_e32 v1, v2
	s_mov_b64 s[2:3], 0
	s_mov_b32 s8, 0x2e8ba2e9
	s_movk_i32 s9, 0xff50
	s_movk_i32 s10, 0x5800
	s_movk_i32 s11, 0x80
	s_movk_i32 s12, 0x15ff

.LBB0_915:
	s_or_b64 exec, exec, s[0:1]
.LBB0_916:
	s_cmp_lt_i32 s92, 8
	s_cselect_b64 s[0:1], -1, 0
	s_cmp_gt_i32 s93, 7
	s_cselect_b64 s[2:3], -1, 0
	s_and_b64 s[2:3], s[0:1], s[2:3]
	s_andn2_b64 vcc, exec, s[2:3]
	s_cbranch_vccnz .LBB0_1098
	s_andn2_b64 vcc, exec, s[6:7]
	s_cbranch_vccnz .LBB0_971
	s_waitcnt vmcnt(0)
	s_waitcnt vmcnt(0)
	s_barrier
	s_mov_b64 s[2:3], exec
	v_readlane_b32 s4, v235, 17
	v_readlane_b32 s5, v235, 18
	s_and_b64 s[4:5], s[2:3], s[4:5]
	s_mov_b64 exec, s[4:5]
	s_cbranch_execz .LBB0_970
	s_add_i32 s4, 0, 0x23ff0
	v_mov_b32_e32 v0, s4
	s_waitcnt vmcnt(0) expcnt(0) lgkmcnt(0)
	ds_read_b32 v2, v0
	s_add_i32 s4, 0, 0x23ff4
	v_mov_b32_e32 v0, s4
	ds_read_b32 v0, v0
	s_waitcnt lgkmcnt(1)
	v_cmp_ne_u32_e32 vcc, 0, v2
	s_cbranch_vccnz .LBB0_934
	v_readlane_b32 s4, v235, 0
	s_mul_i32 s18, s95, s4
	s_add_u32 s4, s50, 0x1000
	s_addc_u32 s5, s51, 0
	s_add_u32 s6, s50, 0x1100
	s_addc_u32 s7, s51, 0
	s_add_u32 s8, s50, 0x1200
	s_addc_u32 s9, s51, 0
	s_add_u32 s10, s50, 0x1300
	s_mul_i32 s18, s18, s94
	s_addc_u32 s11, s51, 0
	s_mov_b32 s19, 1
	v_mov_b32_e32 v16, 0
	s_branch .LBB0_922

.LBB0_987:
	s_andn2_b64 vcc, exec, s[2:3]
	s_cbranch_vccnz .LBB0_1014
	v_and_b32_e32 v0, 63, v128
	v_lshrrev_b32_e32 v129, 6, v128
	s_waitcnt vmcnt(0)
	v_lshlrev_b32_e32 v3, 2, v0
	s_movk_i32 s2, 0x104
	v_or_b32_e32 v2, 0x80, v129
	v_add_u32_e32 v177, 0, v3
	v_mad_u32_u24 v178, v2, s2, v177
	v_lshlrev_b32_e32 v2, 2, v2
	v_sub_u32_e32 v179, v178, v2
	v_mbcnt_lo_u32_b32 v2, -1, 0
	v_mbcnt_hi_u32_b32 v2, -1, v2
	v_and_b32_e32 v10, 64, v2
	v_add_u32_e32 v10, 64, v10
	v_xor_b32_e32 v11, 1, v2
	v_cmp_lt_i32_e32 vcc, v11, v10
	v_lshlrev_b32_e32 v1, 2, v128
	v_and_b32_e32 v66, 60, v1
	v_cndmask_b32_e32 v11, v2, v11, vcc
	v_lshlrev_b32_e32 v181, 2, v11
	v_xor_b32_e32 v11, 2, v2
	v_cmp_lt_i32_e32 vcc, v11, v10
	v_add_u32_e32 v1, 0x200, v128
	v_lshrrev_b32_e32 v65, 4, v1
	v_cndmask_b32_e32 v11, v2, v11, vcc
	v_lshlrev_b32_e32 v182, 2, v11
	v_xor_b32_e32 v11, 4, v2
	v_cmp_lt_i32_e32 vcc, v11, v10
	v_add_u32_e32 v1, 0x600, v128
	v_lshrrev_b32_e32 v97, 4, v1
	v_cndmask_b32_e32 v11, v2, v11, vcc
	v_lshlrev_b32_e32 v183, 2, v11
	v_xor_b32_e32 v11, 8, v2
	v_cmp_lt_i32_e32 vcc, v11, v10
	v_lshlrev_b32_e32 v1, 2, v66
	v_lshlrev_b32_e32 v176, 8, v64
	v_cndmask_b32_e32 v11, v2, v11, vcc
	v_lshlrev_b32_e32 v184, 2, v11
	v_xor_b32_e32 v11, 16, v2
	v_cmp_lt_i32_e32 vcc, v11, v10
	s_add_i32 s12, 0, 0x11220
	v_add_u32_e32 v175, 0, v1
	v_cndmask_b32_e32 v11, v2, v11, vcc
	v_lshlrev_b32_e32 v185, 2, v11
	v_xor_b32_e32 v11, 32, v2
	v_add3_u32 v180, s12, v176, v1
	v_lshlrev_b32_e32 v1, 2, v129
	v_cmp_lt_i32_e32 vcc, v11, v10
	v_and_b32_e32 v187, 4, v1
	s_movk_i32 s18, 0x81
	v_cndmask_b32_e32 v2, v2, v11, vcc
	v_lshlrev_b32_e32 v186, 2, v2
	v_or_b32_e32 v2, 0x80, v187
	v_sub_u32_e32 v10, v2, v0
	v_cmp_gt_u32_e64 s[4:5], s18, v10
	v_cvt_f32_ubyte0_e32 v71, v10
	v_or_b32_e32 v10, 64, v0
	v_bitop3_b32 v194, v1, 5, 1 bitop3:0xc8
	v_sub_u32_e32 v2, v2, v10
	v_or_b32_e32 v12, 0x80, v194
	v_cvt_f32_ubyte0_e32 v73, v2
	v_or_b32_e32 v2, 0x80, v0
	s_movk_i32 s6, 0x88
	v_sub_u32_e32 v13, v12, v0
	v_sub_u32_e32 v12, v12, v10
	v_mad_u32_u24 v189, v0, s2, 0
	v_mad_u32_u24 v190, v10, s2, 0
	v_cmp_gt_u32_e64 s[6:7], s6, v2
	v_mad_u32_u24 v191, v2, s2, 0
	v_sub_u32_e32 v2, v187, v0
	s_add_i32 s2, 0, 0x13220
	v_cvt_f32_ubyte0_e32 v79, v12
	v_sub_u32_e32 v12, v194, v0
	v_bitop3_b32 v198, v1, 6, 2 bitop3:0xc8
	v_cmp_gt_u32_e32 vcc, s18, v2
	v_cvt_f32_u32_e32 v75, v2
	s_movk_i32 s8, 0x880
	v_mov_b32_e32 v2, s2
	v_or_b32_e32 v11, 1, v1
	v_cmp_gt_u32_e64 s[14:15], s18, v12
	v_cvt_f32_u32_e32 v81, v12
	s_movk_i32 s2, 0x220
	v_or_b32_e32 v12, 0x80, v198
	v_mad_u32_u24 v192, v129, s8, v2
	v_lshl_add_u32 v195, v11, 8, s12
	v_cmp_gt_u32_e64 s[8:9], s18, v13
	v_cvt_f32_ubyte0_e32 v77, v13
	v_mad_u32_u24 v196, v11, s2, v2
	v_or_b32_e32 v11, 2, v1
	v_sub_u32_e32 v13, v12, v0
	v_sub_u32_e32 v12, v12, v10
	v_bitop3_b32 v202, v1, 7, 3 bitop3:0xc8
	v_lshl_add_u32 v199, v11, 8, s12
	v_cvt_f32_ubyte0_e32 v85, v12
	v_sub_u32_e32 v12, v198, v0
	v_mad_u32_u24 v200, v11, s2, v2
	v_or_b32_e32 v11, 3, v1
	v_or_b32_e32 v1, 0x80, v202
	v_cmp_gt_u32_e64 s[16:17], s18, v12
	v_cvt_f32_u32_e32 v87, v12
	v_sub_u32_e32 v12, v1, v0
	v_sub_u32_e32 v1, v1, v10
	v_cvt_f32_ubyte0_e32 v91, v1
	v_sub_u32_e32 v1, v202, v0
	v_lshl_add_u32 v188, v129, 10, s12
	v_cmp_gt_u32_e64 s[10:11], s18, v13
	v_lshl_add_u32 v203, v11, 8, s12
	v_cmp_gt_u32_e64 s[12:13], s18, v12
	v_cmp_gt_u32_e64 s[18:19], s18, v1
	v_cvt_f32_u32_e32 v93, v1
	v_or_b32_e32 v67, 64, v64
	v_mov_b32_e32 v69, 0
	v_mad_u32_u24 v204, v11, s2, v2
	s_and_b64 s[26:27], s[6:7], vcc
	s_and_b64 s[14:15], s[6:7], s[14:15]
	s_and_b64 s[16:17], s[6:7], s[16:17]
	s_and_b64 s[18:19], s[6:7], s[18:19]
	v_lshlrev_b32_e32 v68, 1, v0
	v_mul_u32_u24_e32 v4, 0x104, v64
	v_mul_u32_u24_e32 v5, 0x104, v65
	v_lshlrev_b32_e32 v6, 8, v65
	v_lshlrev_b32_e32 v7, 8, v67
	v_mul_u32_u24_e32 v8, 0x104, v97
	v_lshlrev_b32_e32 v9, 8, v97
	v_add_u32_e32 v193, v192, v3
	v_add_u32_e32 v197, v196, v3
	v_add_u32_e32 v201, v200, v3
	v_add_u32_e32 v205, v204, v3
	s_add_u32 s28, s50, 0x14705000
	v_lshl_add_u64 v[2:3], s[50:51], 0, v[68:69]
	s_mov_b64 s[30:31], 0x21605000
	v_mov_b32_e32 v92, 0x3e000000
	v_bfe_u32 v174, v128, 4, 3
	s_mov_b32 s3, 0
	v_cvt_f32_ubyte0_e32 v83, v13
	v_cvt_f32_ubyte0_e32 v89, v12
	v_add_u32_e32 v206, 0x8a20, v177
	s_addc_u32 s29, s51, 0
	v_lshl_add_u64 v[94:95], v[2:3], 0, s[30:31]
	v_mov_b32_e32 v90, v92
	v_mov_b32_e32 v88, v92
	v_mov_b32_e32 v86, v92
	v_mov_b32_e32 v84, v92
	v_mov_b32_e32 v82, v92
	v_mov_b32_e32 v80, v92
	v_mov_b32_e32 v78, v92
	v_mov_b32_e32 v76, v92
	v_mov_b32_e32 v74, v92
	v_mov_b32_e32 v72, v92
	v_mov_b32_e32 v70, v92
	s_movk_i32 s33, 0x5c00
	v_lshlrev_b32_e32 v68, 1, v0
	v_add_u32_e32 v207, v175, v4
	v_add_u32_e32 v208, v175, v5
	v_add_u32_e32 v209, v175, v6
	v_add_u32_e32 v210, v175, v7
	v_add_u32_e32 v211, v175, v8
	v_add_u32_e32 v212, v175, v9
	s_mov_b32 s35, 0xc2fc0000
	v_mov_b32_e32 v213, 0x42800000
	v_not_b32_e32 v214, 63
	s_mov_b32 s52, s34
	s_branch .LBB0_990
.LBB0_989:
	s_or_b64 exec, exec, s[30:31]
	v_sub_f32_e32 v2, v107, v115
	v_mul_f32_e32 v2, 0x3fb8aa3b, v2
	v_exp_f32_e32 v2, v2
	v_add_f32_e32 v4, v116, v117
	v_sub_f32_e32 v6, v107, v112
	v_mul_f32_e32 v6, 0x3fb8aa3b, v6
	v_add_f32_e32 v2, v2, v4
	v_div_scale_f32 v4, s[30:31], v2, v2, 1.0
	v_rcp_f32_e32 v5, v4
	v_div_scale_f32 v7, vcc, 1.0, v2, 1.0
	v_exp_f32_e32 v6, v6
	v_fma_f32 v8, -v4, v5, 1.0
	v_fmac_f32_e32 v5, v8, v5
	v_mul_f32_e32 v8, v7, v5
	v_fma_f32 v9, -v4, v8, v7
	v_fmac_f32_e32 v8, v9, v5
	v_fma_f32 v4, -v4, v8, v7
	v_add_f32_e32 v7, v113, v114
	v_div_fmas_f32 v4, v4, v5, v8
	v_add_f32_e32 v6, v6, v7
	v_div_fixup_f32 v216, v4, v2, 1.0
	ds_bpermute_b32 v4, v181, v1
	v_div_scale_f32 v7, s[30:31], v6, v6, 1.0
	v_rcp_f32_e32 v9, v7
	v_sub_f32_e32 v0, v107, v0
	s_waitcnt lgkmcnt(0)
	v_add_f32_e32 v1, v1, v4
	ds_bpermute_b32 v4, v182, v1
	v_fma_f32 v2, -v7, v9, 1.0
	v_fmac_f32_e32 v9, v2, v9
	v_div_scale_f32 v2, vcc, 1.0, v6, 1.0
	v_mul_f32_e32 v5, v2, v9
	v_fma_f32 v8, -v7, v5, v2
	v_fmac_f32_e32 v5, v8, v9
	v_fma_f32 v2, -v7, v5, v2
	v_sub_f32_e32 v7, v107, v108
	s_waitcnt lgkmcnt(0)
	v_add_f32_e32 v1, v1, v4
	v_mul_f32_e32 v7, 0x3fb8aa3b, v7
	ds_bpermute_b32 v4, v183, v1
	v_exp_f32_e32 v7, v7
	v_add_f32_e32 v8, v109, v110
	v_div_fmas_f32 v2, v2, v9, v5
	v_div_fixup_f32 v217, v2, v6, 1.0
	v_add_f32_e32 v7, v7, v8
	s_waitcnt lgkmcnt(0)
	v_add_f32_e32 v1, v1, v4
	v_div_scale_f32 v8, s[30:31], v7, v7, 1.0
	ds_bpermute_b32 v4, v184, v1
	v_rcp_f32_e32 v10, v8
	v_mul_f32_e32 v0, 0x3fb8aa3b, v0
	v_exp_f32_e32 v0, v0
	s_waitcnt lgkmcnt(0)
	v_fma_f32 v2, -v8, v10, 1.0
	v_add_f32_e32 v1, v1, v4
	v_fmac_f32_e32 v10, v2, v10
	ds_bpermute_b32 v2, v185, v1
	v_div_scale_f32 v4, vcc, 1.0, v7, 1.0
	v_mul_f32_e32 v5, v4, v10
	v_fma_f32 v6, -v8, v5, v4
	s_waitcnt lgkmcnt(0)
	v_add_f32_e32 v1, v1, v2
	ds_bpermute_b32 v2, v186, v1
	v_fmac_f32_e32 v5, v6, v10
	v_fma_f32 v4, -v8, v5, v4
	v_div_fmas_f32 v4, v4, v10, v5
	v_div_fixup_f32 v218, v4, v7, 1.0
	s_waitcnt lgkmcnt(0)
	v_add_f32_e32 v1, v1, v2
	v_add_f32_e32 v0, v0, v1
	v_div_scale_f32 v1, s[30:31], v0, v0, 1.0
	v_rcp_f32_e32 v2, v1
	s_barrier
	ds_read_b128 v[10:13], v192
	ds_read_b128 v[14:17], v192 offset:16
	v_fma_f32 v4, -v1, v2, 1.0
	v_fmac_f32_e32 v2, v4, v2
	v_div_scale_f32 v4, vcc, 1.0, v0, 1.0
	v_mul_f32_e32 v5, v4, v2
	v_fma_f32 v6, -v1, v5, v4
	v_fmac_f32_e32 v5, v6, v2
	v_fma_f32 v1, -v1, v5, v4
	v_lshlrev_b32_e32 v3, 6, v106
	v_div_fmas_f32 v1, v1, v2, v5
	v_add_u32_e32 v156, 32, v177
	v_div_fixup_f32 v215, v1, v0, 1.0
	v_lshlrev_b32_e32 v0, 1, v3
	ds_read2st64_b32 v[2:3], v156 offset0:138 offset1:139
	ds_read_b128 v[20:23], v192 offset:32
	ds_read_b128 v[24:27], v192 offset:48
	ds_read2st64_b32 v[4:5], v156 offset0:140 offset1:141
	ds_read2st64_b32 v[6:7], v156 offset0:142 offset1:143
	ds_read2st64_b32 v[8:9], v156 offset0:144 offset1:145
	s_waitcnt lgkmcnt(5)
	v_fma_f32 v219, v10, v2, 0
	v_fmac_f32_e32 v219, v11, v3
	s_waitcnt lgkmcnt(2)
	v_fmac_f32_e32 v219, v12, v4
	v_fmac_f32_e32 v219, v13, v5
	ds_read2st64_b32 v[12:13], v156 offset0:146 offset1:147
	s_waitcnt lgkmcnt(2)
	v_fmac_f32_e32 v219, v14, v6
	v_fmac_f32_e32 v219, v15, v7
	s_waitcnt lgkmcnt(1)
	v_fmac_f32_e32 v219, v16, v8
	v_fmac_f32_e32 v219, v17, v9
	ds_read2st64_b32 v[18:19], v156 offset0:148 offset1:149
	ds_read2st64_b32 v[10:11], v156 offset0:150 offset1:151
	ds_read2st64_b32 v[14:15], v156 offset0:152 offset1:153
	s_waitcnt lgkmcnt(3)
	v_fmac_f32_e32 v219, v20, v12
	v_fmac_f32_e32 v219, v21, v13
	s_waitcnt lgkmcnt(2)
	v_fmac_f32_e32 v219, v22, v18
	v_fmac_f32_e32 v219, v23, v19
	s_waitcnt lgkmcnt(1)
	v_fmac_f32_e32 v219, v24, v10
	v_fmac_f32_e32 v219, v25, v11
	s_waitcnt lgkmcnt(0)
	v_fmac_f32_e32 v219, v26, v14
	v_fmac_f32_e32 v219, v27, v15
	ds_read2st64_b32 v[16:17], v156 offset0:154 offset1:155
	ds_read_b128 v[24:27], v192 offset:64
	ds_read_b128 v[32:35], v192 offset:80
	ds_read2st64_b32 v[30:31], v156 offset0:156 offset1:157
	ds_read2st64_b32 v[20:21], v156 offset0:158 offset1:159
	ds_read2st64_b32 v[22:23], v156 offset0:160 offset1:161
	s_waitcnt lgkmcnt(4)
	v_fmac_f32_e32 v219, v24, v16
	v_fmac_f32_e32 v219, v25, v17
	s_waitcnt lgkmcnt(2)
	v_fmac_f32_e32 v219, v26, v30
	v_fmac_f32_e32 v219, v27, v31
	s_waitcnt lgkmcnt(1)
	v_fmac_f32_e32 v219, v32, v20
	v_fmac_f32_e32 v219, v33, v21
	s_waitcnt lgkmcnt(0)
	v_fmac_f32_e32 v219, v34, v22
	v_fmac_f32_e32 v219, v35, v23
	ds_read2st64_b32 v[24:25], v156 offset0:162 offset1:163
	ds_read_b128 v[32:35], v192 offset:96
	ds_read_b128 v[40:43], v192 offset:112
	ds_read2st64_b32 v[38:39], v156 offset0:164 offset1:165
	ds_read2st64_b32 v[26:27], v156 offset0:166 offset1:167
	ds_read2st64_b32 v[28:29], v156 offset0:168 offset1:169
	s_waitcnt lgkmcnt(4)
	v_fmac_f32_e32 v219, v32, v24
	v_fmac_f32_e32 v219, v33, v25
	s_waitcnt lgkmcnt(2)
	v_fmac_f32_e32 v219, v34, v38
	v_fmac_f32_e32 v219, v35, v39
	s_waitcnt lgkmcnt(1)
	v_fmac_f32_e32 v219, v40, v26
	v_fmac_f32_e32 v219, v41, v27
	s_waitcnt lgkmcnt(0)
	v_fmac_f32_e32 v219, v42, v28
	v_fmac_f32_e32 v219, v43, v29
	ds_read2st64_b32 v[32:33], v156 offset0:170 offset1:171
	ds_read_b128 v[40:43], v192 offset:128
	ds_read_b128 v[48:51], v192 offset:144
	ds_read2st64_b32 v[46:47], v156 offset0:172 offset1:173
	ds_read2st64_b32 v[34:35], v156 offset0:174 offset1:175
	ds_read2st64_b32 v[36:37], v156 offset0:176 offset1:177
	s_waitcnt lgkmcnt(4)
	v_fmac_f32_e32 v219, v40, v32
	v_fmac_f32_e32 v219, v41, v33
	s_waitcnt lgkmcnt(2)
	v_fmac_f32_e32 v219, v42, v46
	v_fmac_f32_e32 v219, v43, v47
	s_waitcnt lgkmcnt(1)
	v_fmac_f32_e32 v219, v48, v34
	v_fmac_f32_e32 v219, v49, v35
	s_waitcnt lgkmcnt(0)
	v_fmac_f32_e32 v219, v50, v36
	v_fmac_f32_e32 v219, v51, v37
	ds_read2st64_b32 v[40:41], v156 offset0:178 offset1:179
	ds_read_b128 v[48:51], v192 offset:160
	ds_read_b128 v[56:59], v192 offset:176
	ds_read2st64_b32 v[54:55], v156 offset0:180 offset1:181
	ds_read2st64_b32 v[42:43], v156 offset0:182 offset1:183
	ds_read2st64_b32 v[44:45], v156 offset0:184 offset1:185
	s_waitcnt lgkmcnt(4)
	v_fmac_f32_e32 v219, v48, v40
	v_fmac_f32_e32 v219, v49, v41
	s_waitcnt lgkmcnt(2)
	v_fmac_f32_e32 v219, v50, v54
	v_fmac_f32_e32 v219, v51, v55
	s_waitcnt lgkmcnt(1)
	v_fmac_f32_e32 v219, v56, v42
	v_fmac_f32_e32 v219, v57, v43
	s_waitcnt lgkmcnt(0)
	v_fmac_f32_e32 v219, v58, v44
	v_fmac_f32_e32 v219, v59, v45
	ds_read2st64_b32 v[48:49], v156 offset0:186 offset1:187
	ds_read_b128 v[56:59], v192 offset:192
	ds_read_b128 v[98:101], v192 offset:208
	ds_read2st64_b32 v[62:63], v156 offset0:188 offset1:189
	ds_read2st64_b32 v[50:51], v156 offset0:190 offset1:191
	ds_read2st64_b32 v[52:53], v156 offset0:192 offset1:193
	s_waitcnt lgkmcnt(4)
	v_fmac_f32_e32 v219, v56, v48
	v_fmac_f32_e32 v219, v57, v49
	s_waitcnt lgkmcnt(2)
	v_fmac_f32_e32 v219, v58, v62
	v_fmac_f32_e32 v219, v59, v63
	s_waitcnt lgkmcnt(1)
	v_fmac_f32_e32 v219, v98, v50
	v_fmac_f32_e32 v219, v99, v51
	s_waitcnt lgkmcnt(0)
	v_fmac_f32_e32 v219, v100, v52
	v_fmac_f32_e32 v219, v101, v53
	ds_read2st64_b32 v[56:57], v156 offset0:194 offset1:195
	ds_read_b128 v[98:101], v192 offset:224
	ds_read_b128 v[106:109], v192 offset:240
	ds_read2st64_b32 v[104:105], v156 offset0:196 offset1:197
	ds_read2st64_b32 v[58:59], v156 offset0:198 offset1:199
	ds_read2st64_b32 v[60:61], v156 offset0:200 offset1:201
	s_waitcnt lgkmcnt(4)
	v_fmac_f32_e32 v219, v98, v56
	v_fmac_f32_e32 v219, v99, v57
	s_waitcnt lgkmcnt(2)
	v_fmac_f32_e32 v219, v100, v104
	v_fmac_f32_e32 v219, v101, v105
	s_waitcnt lgkmcnt(1)
	v_fmac_f32_e32 v219, v106, v58
	v_fmac_f32_e32 v219, v107, v59
	s_waitcnt lgkmcnt(0)
	v_fmac_f32_e32 v219, v108, v60
	v_fmac_f32_e32 v219, v109, v61
	ds_read2st64_b32 v[98:99], v156 offset0:202 offset1:203
	ds_read_b128 v[106:109], v192 offset:256
	ds_read_b128 v[114:117], v192 offset:272
	ds_read2st64_b32 v[112:113], v156 offset0:204 offset1:205
	ds_read2st64_b32 v[100:101], v156 offset0:206 offset1:207
	ds_read2st64_b32 v[102:103], v156 offset0:208 offset1:209
	s_waitcnt lgkmcnt(4)
	v_fmac_f32_e32 v219, v106, v98
	v_fmac_f32_e32 v219, v107, v99
	s_waitcnt lgkmcnt(2)
	v_fmac_f32_e32 v219, v108, v112
	v_fmac_f32_e32 v219, v109, v113
	s_waitcnt lgkmcnt(1)
	v_fmac_f32_e32 v219, v114, v100
	v_fmac_f32_e32 v219, v115, v101
	s_waitcnt lgkmcnt(0)
	v_fmac_f32_e32 v219, v116, v102
	v_fmac_f32_e32 v219, v117, v103
	ds_read2st64_b32 v[106:107], v156 offset0:210 offset1:211
	ds_read_b128 v[114:117], v192 offset:288
	ds_read_b128 v[122:125], v192 offset:304
	ds_read2st64_b32 v[120:121], v156 offset0:212 offset1:213
	ds_read2st64_b32 v[108:109], v156 offset0:214 offset1:215
	ds_read2st64_b32 v[110:111], v156 offset0:216 offset1:217
	s_waitcnt lgkmcnt(4)
	v_fmac_f32_e32 v219, v114, v106
	v_fmac_f32_e32 v219, v115, v107
	s_waitcnt lgkmcnt(2)
	v_fmac_f32_e32 v219, v116, v120
	v_fmac_f32_e32 v219, v117, v121
	s_waitcnt lgkmcnt(1)
	v_fmac_f32_e32 v219, v122, v108
	v_fmac_f32_e32 v219, v123, v109
	s_waitcnt lgkmcnt(0)
	v_fmac_f32_e32 v219, v124, v110
	v_fmac_f32_e32 v219, v125, v111
	ds_read2st64_b32 v[114:115], v156 offset0:218 offset1:219
	ds_read_b128 v[122:125], v192 offset:320
	ds_read_b128 v[132:135], v192 offset:336
	ds_read2st64_b32 v[130:131], v156 offset0:220 offset1:221
	ds_read2st64_b32 v[116:117], v156 offset0:222 offset1:223
	ds_read2st64_b32 v[118:119], v156 offset0:224 offset1:225
	s_waitcnt lgkmcnt(4)
	v_fmac_f32_e32 v219, v122, v114
	v_fmac_f32_e32 v219, v123, v115
	s_waitcnt lgkmcnt(2)
	v_fmac_f32_e32 v219, v124, v130
	v_fmac_f32_e32 v219, v125, v131
	s_waitcnt lgkmcnt(1)
	v_fmac_f32_e32 v219, v132, v116
	v_fmac_f32_e32 v219, v133, v117
	s_waitcnt lgkmcnt(0)
	v_fmac_f32_e32 v219, v134, v118
	v_fmac_f32_e32 v219, v135, v119
	ds_read2st64_b32 v[122:123], v156 offset0:226 offset1:227
	ds_read_b128 v[132:135], v192 offset:352
	ds_read_b128 v[140:143], v192 offset:368
	ds_read2st64_b32 v[138:139], v156 offset0:228 offset1:229
	ds_read2st64_b32 v[124:125], v156 offset0:230 offset1:231
	ds_read2st64_b32 v[126:127], v156 offset0:232 offset1:233
	s_waitcnt lgkmcnt(4)
	v_fmac_f32_e32 v219, v132, v122
	v_fmac_f32_e32 v219, v133, v123
	s_waitcnt lgkmcnt(2)
	v_fmac_f32_e32 v219, v134, v138
	v_fmac_f32_e32 v219, v135, v139
	s_waitcnt lgkmcnt(1)
	v_fmac_f32_e32 v219, v140, v124
	v_fmac_f32_e32 v219, v141, v125
	s_waitcnt lgkmcnt(0)
	v_fmac_f32_e32 v219, v142, v126
	v_fmac_f32_e32 v219, v143, v127
	ds_read2st64_b32 v[132:133], v156 offset0:234 offset1:235
	ds_read_b128 v[140:143], v192 offset:384
	ds_read_b128 v[148:151], v192 offset:400
	ds_read2st64_b32 v[146:147], v156 offset0:236 offset1:237
	ds_read2st64_b32 v[134:135], v156 offset0:238 offset1:239
	ds_read2st64_b32 v[136:137], v156 offset0:240 offset1:241
	s_waitcnt lgkmcnt(4)
	v_fmac_f32_e32 v219, v140, v132
	v_fmac_f32_e32 v219, v141, v133
	s_waitcnt lgkmcnt(2)
	v_fmac_f32_e32 v219, v142, v146
	v_fmac_f32_e32 v219, v143, v147
	s_waitcnt lgkmcnt(1)
	v_fmac_f32_e32 v219, v148, v134
	v_fmac_f32_e32 v219, v149, v135
	s_waitcnt lgkmcnt(0)
	v_fmac_f32_e32 v219, v150, v136
	v_fmac_f32_e32 v219, v151, v137
	ds_read2st64_b32 v[140:141], v156 offset0:242 offset1:243
	ds_read_b128 v[148:151], v192 offset:416
	ds_read_b128 v[152:155], v192 offset:432
	ds_read2st64_b32 v[158:159], v156 offset0:244 offset1:245
	ds_read2st64_b32 v[142:143], v156 offset0:246 offset1:247
	ds_read2st64_b32 v[144:145], v156 offset0:248 offset1:249
	s_waitcnt lgkmcnt(4)
	v_fmac_f32_e32 v219, v148, v140
	v_fmac_f32_e32 v219, v149, v141
	s_waitcnt lgkmcnt(2)
	v_fmac_f32_e32 v219, v150, v158
	v_fmac_f32_e32 v219, v151, v159
	s_waitcnt lgkmcnt(1)
	v_fmac_f32_e32 v219, v152, v142
	v_fmac_f32_e32 v219, v153, v143
	s_waitcnt lgkmcnt(0)
	v_fmac_f32_e32 v219, v154, v144
	v_fmac_f32_e32 v219, v155, v145
	ds_read_b128 v[152:155], v192 offset:448
	ds_read2st64_b32 v[148:149], v156 offset0:250 offset1:251
	ds_read2st64_b32 v[156:157], v156 offset0:252 offset1:253
	ds_read_b128 v[160:163], v192 offset:464
	v_add_u32_e32 v150, 0x8020, v177
	ds_read2st64_b32 v[150:151], v150 offset0:126 offset1:127
	s_waitcnt lgkmcnt(3)
	v_fmac_f32_e32 v219, v152, v148
	v_fmac_f32_e32 v219, v153, v149
	s_waitcnt lgkmcnt(2)
	v_fmac_f32_e32 v219, v154, v156
	v_fmac_f32_e32 v219, v155, v157
	s_waitcnt lgkmcnt(0)
	v_fmac_f32_e32 v219, v160, v150
	v_fmac_f32_e32 v219, v161, v151
	ds_read2st64_b32 v[164:165], v206 offset0:118 offset1:119
	ds_read_b128 v[166:169], v192 offset:480
	ds_read2st64_b32 v[154:155], v206 offset0:120 offset1:121
	ds_read2st64_b32 v[160:161], v206 offset0:122 offset1:123
	ds_read2st64_b32 v[152:153], v206 offset0:124 offset1:125
	s_waitcnt lgkmcnt(4)
	v_fmac_f32_e32 v219, v162, v164
	v_fmac_f32_e32 v219, v163, v165
	ds_read_b128 v[170:173], v192 offset:496
	s_waitcnt lgkmcnt(3)
	v_fmac_f32_e32 v219, v166, v154
	v_fmac_f32_e32 v219, v167, v155
	s_waitcnt lgkmcnt(2)
	v_fmac_f32_e32 v219, v168, v160
	v_fmac_f32_e32 v219, v169, v161
	s_waitcnt lgkmcnt(0)
	v_fmac_f32_e32 v219, v170, v152
	v_fmac_f32_e32 v219, v171, v153
	ds_read2st64_b32 v[168:169], v206 offset0:126 offset1:127
	ds_read_b128 v[220:223], v192 offset:512
	ds_read2st64_b32 v[162:163], v206 offset0:128 offset1:129
	ds_read2st64_b32 v[166:167], v206 offset0:130 offset1:131
	ds_read2st64_b32 v[170:171], v206 offset0:132 offset1:133
	s_waitcnt lgkmcnt(4)
	v_fmac_f32_e32 v219, v172, v168
	v_fmac_f32_e32 v219, v173, v169
	ds_read_b128 v[224:227], v192 offset:528
	s_waitcnt lgkmcnt(3)
	v_fmac_f32_e32 v219, v220, v162
	v_fmac_f32_e32 v219, v221, v163
	ds_read2st64_b32 v[172:173], v206 offset0:134 offset1:135
	s_waitcnt lgkmcnt(3)
	v_fmac_f32_e32 v219, v222, v166
	v_fmac_f32_e32 v219, v223, v167
	s_waitcnt lgkmcnt(1)
	v_fmac_f32_e32 v219, v224, v170
	v_fmac_f32_e32 v219, v225, v171
	s_waitcnt lgkmcnt(0)
	v_fmac_f32_e32 v219, v226, v172
	v_fmac_f32_e32 v219, v227, v173
	v_mul_f32_e32 v218, v218, v219
	v_cvt_pk_bf16_f32 v224, v218, s0
	v_or_b32_e32 v218, s53, v187
	v_mov_b32_e32 v1, v69
	v_ashrrev_i32_e32 v219, 31, v218
	v_lshl_add_u64 v[0:1], v[94:95], 0, v[0:1]
	v_lshlrev_b64 v[218:219], 11, v[218:219]
	v_lshl_add_u64 v[222:223], v[0:1], 0, v[218:219]
	ds_read_b128 v[218:221], v196
	global_store_short v[222:223], v224, off
	ds_read_b128 v[222:225], v196 offset:16
	ds_read_b128 v[226:229], v196 offset:32
	ds_read_b128 v[230:233], v196 offset:48
	s_add_i32 s52, s52, s94
	s_cmpk_gt_i32 s52, 0x1ff
	s_waitcnt lgkmcnt(3)
	v_fma_f32 v234, v2, v218, 0
	v_fmac_f32_e32 v234, v3, v219
	v_fmac_f32_e32 v234, v4, v220
	v_fmac_f32_e32 v234, v5, v221
	s_waitcnt lgkmcnt(2)
	v_fmac_f32_e32 v234, v6, v222
	v_fmac_f32_e32 v234, v7, v223
	v_fmac_f32_e32 v234, v8, v224
	v_fmac_f32_e32 v234, v9, v225
	s_waitcnt lgkmcnt(1)
	v_fmac_f32_e32 v234, v12, v226
	v_fmac_f32_e32 v234, v13, v227
	v_fmac_f32_e32 v234, v18, v228
	v_fmac_f32_e32 v234, v19, v229
	ds_read_b128 v[218:221], v196 offset:64
	ds_read_b128 v[222:225], v196 offset:80
	s_waitcnt lgkmcnt(2)
	v_fmac_f32_e32 v234, v10, v230
	v_fmac_f32_e32 v234, v11, v231
	v_fmac_f32_e32 v234, v14, v232
	v_fmac_f32_e32 v234, v15, v233
	s_waitcnt lgkmcnt(1)
	v_fmac_f32_e32 v234, v16, v218
	v_fmac_f32_e32 v234, v17, v219
	v_fmac_f32_e32 v234, v30, v220
	v_fmac_f32_e32 v234, v31, v221
	ds_read_b128 v[218:221], v196 offset:96
	s_waitcnt lgkmcnt(1)
	v_fmac_f32_e32 v234, v20, v222
	v_fmac_f32_e32 v234, v21, v223
	v_fmac_f32_e32 v234, v22, v224
	v_fmac_f32_e32 v234, v23, v225
	ds_read_b128 v[222:225], v196 offset:112
	s_waitcnt lgkmcnt(1)
	v_fmac_f32_e32 v234, v24, v218
	v_fmac_f32_e32 v234, v25, v219
	v_fmac_f32_e32 v234, v38, v220
	v_fmac_f32_e32 v234, v39, v221
	ds_read_b128 v[218:221], v196 offset:128
	s_waitcnt lgkmcnt(1)
	v_fmac_f32_e32 v234, v26, v222
	v_fmac_f32_e32 v234, v27, v223
	v_fmac_f32_e32 v234, v28, v224
	v_fmac_f32_e32 v234, v29, v225
	ds_read_b128 v[222:225], v196 offset:144
	s_waitcnt lgkmcnt(1)
	v_fmac_f32_e32 v234, v32, v218
	v_fmac_f32_e32 v234, v33, v219
	v_fmac_f32_e32 v234, v46, v220
	v_fmac_f32_e32 v234, v47, v221
	ds_read_b128 v[218:221], v196 offset:160
	s_waitcnt lgkmcnt(1)
	v_fmac_f32_e32 v234, v34, v222
	v_fmac_f32_e32 v234, v35, v223
	v_fmac_f32_e32 v234, v36, v224
	v_fmac_f32_e32 v234, v37, v225
	ds_read_b128 v[222:225], v196 offset:176
	s_waitcnt lgkmcnt(1)
	v_fmac_f32_e32 v234, v40, v218
	v_fmac_f32_e32 v234, v41, v219
	v_fmac_f32_e32 v234, v54, v220
	v_fmac_f32_e32 v234, v55, v221
	ds_read_b128 v[218:221], v196 offset:192
	s_waitcnt lgkmcnt(1)
	v_fmac_f32_e32 v234, v42, v222
	v_fmac_f32_e32 v234, v43, v223
	v_fmac_f32_e32 v234, v44, v224
	v_fmac_f32_e32 v234, v45, v225
	ds_read_b128 v[222:225], v196 offset:208
	s_waitcnt lgkmcnt(1)
	v_fmac_f32_e32 v234, v48, v218
	v_fmac_f32_e32 v234, v49, v219
	v_fmac_f32_e32 v234, v62, v220
	v_fmac_f32_e32 v234, v63, v221
	ds_read_b128 v[218:221], v196 offset:224
	s_waitcnt lgkmcnt(1)
	v_fmac_f32_e32 v234, v50, v222
	v_fmac_f32_e32 v234, v51, v223
	v_fmac_f32_e32 v234, v52, v224
	v_fmac_f32_e32 v234, v53, v225
	ds_read_b128 v[222:225], v196 offset:240
	s_waitcnt lgkmcnt(1)
	v_fmac_f32_e32 v234, v56, v218
	v_fmac_f32_e32 v234, v57, v219
	v_fmac_f32_e32 v234, v104, v220
	v_fmac_f32_e32 v234, v105, v221
	ds_read_b128 v[218:221], v196 offset:256
	s_waitcnt lgkmcnt(1)
	v_fmac_f32_e32 v234, v58, v222
	v_fmac_f32_e32 v234, v59, v223
	v_fmac_f32_e32 v234, v60, v224
	v_fmac_f32_e32 v234, v61, v225
	ds_read_b128 v[222:225], v196 offset:272
	s_waitcnt lgkmcnt(1)
	v_fmac_f32_e32 v234, v98, v218
	v_fmac_f32_e32 v234, v99, v219
	v_fmac_f32_e32 v234, v112, v220
	v_fmac_f32_e32 v234, v113, v221
	ds_read_b128 v[218:221], v196 offset:288
	s_waitcnt lgkmcnt(1)
	v_fmac_f32_e32 v234, v100, v222
	v_fmac_f32_e32 v234, v101, v223
	v_fmac_f32_e32 v234, v102, v224
	v_fmac_f32_e32 v234, v103, v225
	ds_read_b128 v[222:225], v196 offset:304
	s_waitcnt lgkmcnt(1)
	v_fmac_f32_e32 v234, v106, v218
	v_fmac_f32_e32 v234, v107, v219
	v_fmac_f32_e32 v234, v120, v220
	v_fmac_f32_e32 v234, v121, v221
	ds_read_b128 v[218:221], v196 offset:320
	s_waitcnt lgkmcnt(1)
	v_fmac_f32_e32 v234, v108, v222
	v_fmac_f32_e32 v234, v109, v223
	v_fmac_f32_e32 v234, v110, v224
	v_fmac_f32_e32 v234, v111, v225
	ds_read_b128 v[222:225], v196 offset:336
	s_waitcnt lgkmcnt(1)
	v_fmac_f32_e32 v234, v114, v218
	v_fmac_f32_e32 v234, v115, v219
	v_fmac_f32_e32 v234, v130, v220
	v_fmac_f32_e32 v234, v131, v221
	ds_read_b128 v[218:221], v196 offset:352
	s_waitcnt lgkmcnt(1)
	v_fmac_f32_e32 v234, v116, v222
	v_fmac_f32_e32 v234, v117, v223
	v_fmac_f32_e32 v234, v118, v224
	v_fmac_f32_e32 v234, v119, v225
	ds_read_b128 v[222:225], v196 offset:368
	s_waitcnt lgkmcnt(1)
	v_fmac_f32_e32 v234, v122, v218
	v_fmac_f32_e32 v234, v123, v219
	v_fmac_f32_e32 v234, v138, v220
	v_fmac_f32_e32 v234, v139, v221
	ds_read_b128 v[218:221], v196 offset:384
	s_waitcnt lgkmcnt(1)
	v_fmac_f32_e32 v234, v124, v222
	v_fmac_f32_e32 v234, v125, v223
	v_fmac_f32_e32 v234, v126, v224
	v_fmac_f32_e32 v234, v127, v225
	ds_read_b128 v[222:225], v196 offset:400
	s_waitcnt lgkmcnt(1)
	v_fmac_f32_e32 v234, v132, v218
	v_fmac_f32_e32 v234, v133, v219
	v_fmac_f32_e32 v234, v146, v220
	v_fmac_f32_e32 v234, v147, v221
	ds_read_b128 v[218:221], v196 offset:416
	s_waitcnt lgkmcnt(1)
	v_fmac_f32_e32 v234, v134, v222
	v_fmac_f32_e32 v234, v135, v223
	v_fmac_f32_e32 v234, v136, v224
	v_fmac_f32_e32 v234, v137, v225
	ds_read_b128 v[222:225], v196 offset:432
	s_waitcnt lgkmcnt(1)
	v_fmac_f32_e32 v234, v140, v218
	v_fmac_f32_e32 v234, v141, v219
	v_fmac_f32_e32 v234, v158, v220
	v_fmac_f32_e32 v234, v159, v221
	ds_read_b128 v[218:221], v196 offset:448
	s_waitcnt lgkmcnt(1)
	v_fmac_f32_e32 v234, v142, v222
	v_fmac_f32_e32 v234, v143, v223
	v_fmac_f32_e32 v234, v144, v224
	v_fmac_f32_e32 v234, v145, v225
	ds_read_b128 v[222:225], v196 offset:464
	s_waitcnt lgkmcnt(1)
	v_fmac_f32_e32 v234, v148, v218
	v_fmac_f32_e32 v234, v149, v219
	v_fmac_f32_e32 v234, v156, v220
	v_fmac_f32_e32 v234, v157, v221
	ds_read_b128 v[218:221], v196 offset:480
	s_waitcnt lgkmcnt(1)
	v_fmac_f32_e32 v234, v150, v222
	v_fmac_f32_e32 v234, v151, v223
	v_fmac_f32_e32 v234, v164, v224
	v_fmac_f32_e32 v234, v165, v225
	ds_read_b128 v[222:225], v196 offset:496
	s_waitcnt lgkmcnt(1)
	v_fmac_f32_e32 v234, v154, v218
	v_fmac_f32_e32 v234, v155, v219
	v_fmac_f32_e32 v234, v160, v220
	v_fmac_f32_e32 v234, v161, v221
	ds_read_b128 v[218:221], v196 offset:512
	s_waitcnt lgkmcnt(1)
	v_fmac_f32_e32 v234, v152, v222
	v_fmac_f32_e32 v234, v153, v223
	v_fmac_f32_e32 v234, v168, v224
	v_fmac_f32_e32 v234, v169, v225
	ds_read_b128 v[222:225], v196 offset:528
	s_waitcnt lgkmcnt(1)
	v_fmac_f32_e32 v234, v162, v218
	v_fmac_f32_e32 v234, v163, v219
	v_fmac_f32_e32 v234, v166, v220
	v_or_b32_e32 v218, s53, v194
	v_fmac_f32_e32 v234, v167, v221
	v_ashrrev_i32_e32 v219, 31, v218
	s_waitcnt lgkmcnt(0)
	v_fmac_f32_e32 v234, v170, v222
	v_lshlrev_b64 v[218:219], 11, v[218:219]
	v_fmac_f32_e32 v234, v171, v223
	v_lshl_add_u64 v[222:223], v[0:1], 0, v[218:219]
	ds_read_b128 v[218:221], v200
	v_fmac_f32_e32 v234, v172, v224
	v_fmac_f32_e32 v234, v173, v225
	v_mul_f32_e32 v217, v217, v234
	v_cvt_pk_bf16_f32 v217, v217, s0
	global_store_short v[222:223], v217, off
	s_waitcnt lgkmcnt(0)
	v_fma_f32 v217, v2, v218, 0
	ds_read_b128 v[222:225], v200 offset:16
	ds_read_b128 v[226:229], v200 offset:32
	ds_read_b128 v[230:233], v200 offset:48
	v_fmac_f32_e32 v217, v3, v219
	v_fmac_f32_e32 v217, v4, v220
	v_fmac_f32_e32 v217, v5, v221
	s_waitcnt lgkmcnt(2)
	v_fmac_f32_e32 v217, v6, v222
	v_fmac_f32_e32 v217, v7, v223
	v_fmac_f32_e32 v217, v8, v224
	v_fmac_f32_e32 v217, v9, v225
	s_waitcnt lgkmcnt(1)
	v_fmac_f32_e32 v217, v12, v226
	v_fmac_f32_e32 v217, v13, v227
	v_fmac_f32_e32 v217, v18, v228
	v_fmac_f32_e32 v217, v19, v229
	ds_read_b128 v[218:221], v200 offset:64
	ds_read_b128 v[222:225], v200 offset:80
	s_waitcnt lgkmcnt(2)
	v_fmac_f32_e32 v217, v10, v230
	v_fmac_f32_e32 v217, v11, v231
	v_fmac_f32_e32 v217, v14, v232
	v_fmac_f32_e32 v217, v15, v233
	s_waitcnt lgkmcnt(1)
	v_fmac_f32_e32 v217, v16, v218
	v_fmac_f32_e32 v217, v17, v219
	v_fmac_f32_e32 v217, v30, v220
	v_fmac_f32_e32 v217, v31, v221
	ds_read_b128 v[218:221], v200 offset:96
	s_waitcnt lgkmcnt(1)
	v_fmac_f32_e32 v217, v20, v222
	v_fmac_f32_e32 v217, v21, v223
	v_fmac_f32_e32 v217, v22, v224
	v_fmac_f32_e32 v217, v23, v225
	ds_read_b128 v[222:225], v200 offset:112
	s_waitcnt lgkmcnt(1)
	v_fmac_f32_e32 v217, v24, v218
	v_fmac_f32_e32 v217, v25, v219
	v_fmac_f32_e32 v217, v38, v220
	v_fmac_f32_e32 v217, v39, v221
	ds_read_b128 v[218:221], v200 offset:128
	s_waitcnt lgkmcnt(1)
	v_fmac_f32_e32 v217, v26, v222
	v_fmac_f32_e32 v217, v27, v223
	v_fmac_f32_e32 v217, v28, v224
	v_fmac_f32_e32 v217, v29, v225
	ds_read_b128 v[222:225], v200 offset:144
	s_waitcnt lgkmcnt(1)
	v_fmac_f32_e32 v217, v32, v218
	v_fmac_f32_e32 v217, v33, v219
	v_fmac_f32_e32 v217, v46, v220
	v_fmac_f32_e32 v217, v47, v221
	ds_read_b128 v[218:221], v200 offset:160
	s_waitcnt lgkmcnt(1)
	v_fmac_f32_e32 v217, v34, v222
	v_fmac_f32_e32 v217, v35, v223
	v_fmac_f32_e32 v217, v36, v224
	v_fmac_f32_e32 v217, v37, v225
	ds_read_b128 v[222:225], v200 offset:176
	s_waitcnt lgkmcnt(1)
	v_fmac_f32_e32 v217, v40, v218
	v_fmac_f32_e32 v217, v41, v219
	v_fmac_f32_e32 v217, v54, v220
	v_fmac_f32_e32 v217, v55, v221
	ds_read_b128 v[218:221], v200 offset:192
	s_waitcnt lgkmcnt(1)
	v_fmac_f32_e32 v217, v42, v222
	v_fmac_f32_e32 v217, v43, v223
	v_fmac_f32_e32 v217, v44, v224
	v_fmac_f32_e32 v217, v45, v225
	ds_read_b128 v[222:225], v200 offset:208
	s_waitcnt lgkmcnt(1)
	v_fmac_f32_e32 v217, v48, v218
	v_fmac_f32_e32 v217, v49, v219
	v_fmac_f32_e32 v217, v62, v220
	v_fmac_f32_e32 v217, v63, v221
	ds_read_b128 v[218:221], v200 offset:224
	s_waitcnt lgkmcnt(1)
	v_fmac_f32_e32 v217, v50, v222
	v_fmac_f32_e32 v217, v51, v223
	v_fmac_f32_e32 v217, v52, v224
	v_fmac_f32_e32 v217, v53, v225
	ds_read_b128 v[222:225], v200 offset:240
	s_waitcnt lgkmcnt(1)
	v_fmac_f32_e32 v217, v56, v218
	v_fmac_f32_e32 v217, v57, v219
	v_fmac_f32_e32 v217, v104, v220
	v_fmac_f32_e32 v217, v105, v221
	ds_read_b128 v[218:221], v200 offset:256
	s_waitcnt lgkmcnt(1)
	v_fmac_f32_e32 v217, v58, v222
	v_fmac_f32_e32 v217, v59, v223
	v_fmac_f32_e32 v217, v60, v224
	v_fmac_f32_e32 v217, v61, v225
	ds_read_b128 v[222:225], v200 offset:272
	s_waitcnt lgkmcnt(1)
	v_fmac_f32_e32 v217, v98, v218
	v_fmac_f32_e32 v217, v99, v219
	v_fmac_f32_e32 v217, v112, v220
	v_fmac_f32_e32 v217, v113, v221
	ds_read_b128 v[218:221], v200 offset:288
	s_waitcnt lgkmcnt(1)
	v_fmac_f32_e32 v217, v100, v222
	v_fmac_f32_e32 v217, v101, v223
	v_fmac_f32_e32 v217, v102, v224
	v_fmac_f32_e32 v217, v103, v225
	ds_read_b128 v[222:225], v200 offset:304
	s_waitcnt lgkmcnt(1)
	v_fmac_f32_e32 v217, v106, v218
	v_fmac_f32_e32 v217, v107, v219
	v_fmac_f32_e32 v217, v120, v220
	v_fmac_f32_e32 v217, v121, v221
	ds_read_b128 v[218:221], v200 offset:320
	s_waitcnt lgkmcnt(1)
	v_fmac_f32_e32 v217, v108, v222
	v_fmac_f32_e32 v217, v109, v223
	v_fmac_f32_e32 v217, v110, v224
	v_fmac_f32_e32 v217, v111, v225
	ds_read_b128 v[222:225], v200 offset:336
	s_waitcnt lgkmcnt(1)
	v_fmac_f32_e32 v217, v114, v218
	v_fmac_f32_e32 v217, v115, v219
	v_fmac_f32_e32 v217, v130, v220
	v_fmac_f32_e32 v217, v131, v221
	ds_read_b128 v[218:221], v200 offset:352
	s_waitcnt lgkmcnt(1)
	v_fmac_f32_e32 v217, v116, v222
	v_fmac_f32_e32 v217, v117, v223
	v_fmac_f32_e32 v217, v118, v224
	v_fmac_f32_e32 v217, v119, v225
	ds_read_b128 v[222:225], v200 offset:368
	s_waitcnt lgkmcnt(1)
	v_fmac_f32_e32 v217, v122, v218
	v_fmac_f32_e32 v217, v123, v219
	v_fmac_f32_e32 v217, v138, v220
	v_fmac_f32_e32 v217, v139, v221
	ds_read_b128 v[218:221], v200 offset:384
	s_waitcnt lgkmcnt(1)
	v_fmac_f32_e32 v217, v124, v222
	v_fmac_f32_e32 v217, v125, v223
	v_fmac_f32_e32 v217, v126, v224
	v_fmac_f32_e32 v217, v127, v225
	ds_read_b128 v[222:225], v200 offset:400
	s_waitcnt lgkmcnt(1)
	v_fmac_f32_e32 v217, v132, v218
	v_fmac_f32_e32 v217, v133, v219
	v_fmac_f32_e32 v217, v146, v220
	v_fmac_f32_e32 v217, v147, v221
	ds_read_b128 v[218:221], v200 offset:416
	s_waitcnt lgkmcnt(1)
	v_fmac_f32_e32 v217, v134, v222
	v_fmac_f32_e32 v217, v135, v223
	v_fmac_f32_e32 v217, v136, v224
	v_fmac_f32_e32 v217, v137, v225
	ds_read_b128 v[222:225], v200 offset:432
	s_waitcnt lgkmcnt(1)
	v_fmac_f32_e32 v217, v140, v218
	v_fmac_f32_e32 v217, v141, v219
	v_fmac_f32_e32 v217, v158, v220
	v_fmac_f32_e32 v217, v159, v221
	ds_read_b128 v[218:221], v200 offset:448
	s_waitcnt lgkmcnt(1)
	v_fmac_f32_e32 v217, v142, v222
	v_fmac_f32_e32 v217, v143, v223
	v_fmac_f32_e32 v217, v144, v224
	v_fmac_f32_e32 v217, v145, v225
	ds_read_b128 v[222:225], v200 offset:464
	s_waitcnt lgkmcnt(1)
	v_fmac_f32_e32 v217, v148, v218
	v_fmac_f32_e32 v217, v149, v219
	v_fmac_f32_e32 v217, v156, v220
	v_fmac_f32_e32 v217, v157, v221
	ds_read_b128 v[218:221], v200 offset:480
	s_waitcnt lgkmcnt(1)
	v_fmac_f32_e32 v217, v150, v222
	v_fmac_f32_e32 v217, v151, v223
	v_fmac_f32_e32 v217, v164, v224
	v_fmac_f32_e32 v217, v165, v225
	ds_read_b128 v[222:225], v200 offset:496
	s_waitcnt lgkmcnt(1)
	v_fmac_f32_e32 v217, v154, v218
	v_fmac_f32_e32 v217, v155, v219
	v_fmac_f32_e32 v217, v160, v220
	v_fmac_f32_e32 v217, v161, v221
	ds_read_b128 v[218:221], v200 offset:512
	s_waitcnt lgkmcnt(1)
	v_fmac_f32_e32 v217, v152, v222
	v_fmac_f32_e32 v217, v153, v223
	v_fmac_f32_e32 v217, v168, v224
	v_fmac_f32_e32 v217, v169, v225
	ds_read_b128 v[222:225], v200 offset:528
	s_waitcnt lgkmcnt(1)
	v_fmac_f32_e32 v217, v162, v218
	v_fmac_f32_e32 v217, v163, v219
	v_fmac_f32_e32 v217, v166, v220
	v_fmac_f32_e32 v217, v167, v221
	s_waitcnt lgkmcnt(0)
	v_fmac_f32_e32 v217, v170, v222
	v_fmac_f32_e32 v217, v171, v223
	v_fmac_f32_e32 v217, v172, v224
	v_fmac_f32_e32 v217, v173, v225
	v_mul_f32_e32 v216, v216, v217
	v_cvt_pk_bf16_f32 v222, v216, s0
	v_or_b32_e32 v216, s53, v198
	v_ashrrev_i32_e32 v217, 31, v216
	v_lshlrev_b64 v[216:217], 11, v[216:217]
	v_lshl_add_u64 v[220:221], v[0:1], 0, v[216:217]
	ds_read_b128 v[216:219], v204
	global_store_short v[220:221], v222, off
	ds_read_b128 v[220:223], v204 offset:16
	ds_read_b128 v[224:227], v204 offset:32
	ds_read_b128 v[228:231], v204 offset:48
	s_waitcnt lgkmcnt(3)
	v_fma_f32 v216, v2, v216, 0
	v_fmac_f32_e32 v216, v3, v217
	v_fmac_f32_e32 v216, v4, v218
	v_fmac_f32_e32 v216, v5, v219
	s_waitcnt lgkmcnt(2)
	v_fmac_f32_e32 v216, v6, v220
	v_fmac_f32_e32 v216, v7, v221
	v_fmac_f32_e32 v216, v8, v222
	v_fmac_f32_e32 v216, v9, v223
	s_waitcnt lgkmcnt(1)
	v_fmac_f32_e32 v216, v12, v224
	v_fmac_f32_e32 v216, v13, v225
	v_fmac_f32_e32 v216, v18, v226
	v_fmac_f32_e32 v216, v19, v227
	ds_read_b128 v[2:5], v204 offset:64
	ds_read_b128 v[6:9], v204 offset:80
	s_waitcnt lgkmcnt(2)
	v_fmac_f32_e32 v216, v10, v228
	v_fmac_f32_e32 v216, v11, v229
	v_fmac_f32_e32 v216, v14, v230
	v_fmac_f32_e32 v216, v15, v231
	s_waitcnt lgkmcnt(1)
	v_fmac_f32_e32 v216, v16, v2
	v_fmac_f32_e32 v216, v17, v3
	v_fmac_f32_e32 v216, v30, v4
	v_fmac_f32_e32 v216, v31, v5
	ds_read_b128 v[2:5], v204 offset:96
	s_waitcnt lgkmcnt(1)
	v_fmac_f32_e32 v216, v20, v6
	v_fmac_f32_e32 v216, v21, v7
	v_fmac_f32_e32 v216, v22, v8
	v_fmac_f32_e32 v216, v23, v9
	ds_read_b128 v[6:9], v204 offset:112
	s_waitcnt lgkmcnt(1)
	v_fmac_f32_e32 v216, v24, v2
	v_fmac_f32_e32 v216, v25, v3
	v_fmac_f32_e32 v216, v38, v4
	v_fmac_f32_e32 v216, v39, v5
	ds_read_b128 v[2:5], v204 offset:128
	s_waitcnt lgkmcnt(1)
	v_fmac_f32_e32 v216, v26, v6
	v_fmac_f32_e32 v216, v27, v7
	v_fmac_f32_e32 v216, v28, v8
	v_fmac_f32_e32 v216, v29, v9
	ds_read_b128 v[6:9], v204 offset:144
	s_waitcnt lgkmcnt(1)
	v_fmac_f32_e32 v216, v32, v2
	v_fmac_f32_e32 v216, v33, v3
	v_fmac_f32_e32 v216, v46, v4
	v_fmac_f32_e32 v216, v47, v5
	ds_read_b128 v[2:5], v204 offset:160
	s_waitcnt lgkmcnt(1)
	v_fmac_f32_e32 v216, v34, v6
	v_fmac_f32_e32 v216, v35, v7
	v_fmac_f32_e32 v216, v36, v8
	v_fmac_f32_e32 v216, v37, v9
	ds_read_b128 v[6:9], v204 offset:176
	s_waitcnt lgkmcnt(1)
	v_fmac_f32_e32 v216, v40, v2
	v_fmac_f32_e32 v216, v41, v3
	v_fmac_f32_e32 v216, v54, v4
	v_fmac_f32_e32 v216, v55, v5
	ds_read_b128 v[2:5], v204 offset:192
	s_waitcnt lgkmcnt(1)
	v_fmac_f32_e32 v216, v42, v6
	v_fmac_f32_e32 v216, v43, v7
	v_fmac_f32_e32 v216, v44, v8
	v_fmac_f32_e32 v216, v45, v9
	ds_read_b128 v[6:9], v204 offset:208
	s_waitcnt lgkmcnt(1)
	v_fmac_f32_e32 v216, v48, v2
	v_fmac_f32_e32 v216, v49, v3
	v_fmac_f32_e32 v216, v62, v4
	v_fmac_f32_e32 v216, v63, v5
	ds_read_b128 v[2:5], v204 offset:224
	s_waitcnt lgkmcnt(1)
	v_fmac_f32_e32 v216, v50, v6
	v_fmac_f32_e32 v216, v51, v7
	v_fmac_f32_e32 v216, v52, v8
	v_fmac_f32_e32 v216, v53, v9
	ds_read_b128 v[6:9], v204 offset:240
	s_waitcnt lgkmcnt(1)
	v_fmac_f32_e32 v216, v56, v2
	v_fmac_f32_e32 v216, v57, v3
	v_fmac_f32_e32 v216, v104, v4
	v_fmac_f32_e32 v216, v105, v5
	ds_read_b128 v[2:5], v204 offset:256
	s_waitcnt lgkmcnt(1)
	v_fmac_f32_e32 v216, v58, v6
	v_fmac_f32_e32 v216, v59, v7
	v_fmac_f32_e32 v216, v60, v8
	v_fmac_f32_e32 v216, v61, v9
	ds_read_b128 v[6:9], v204 offset:272
	s_waitcnt lgkmcnt(1)
	v_fmac_f32_e32 v216, v98, v2
	v_fmac_f32_e32 v216, v99, v3
	v_fmac_f32_e32 v216, v112, v4
	v_fmac_f32_e32 v216, v113, v5
	ds_read_b128 v[2:5], v204 offset:288
	s_waitcnt lgkmcnt(1)
	v_fmac_f32_e32 v216, v100, v6
	v_fmac_f32_e32 v216, v101, v7
	v_fmac_f32_e32 v216, v102, v8
	v_fmac_f32_e32 v216, v103, v9
	ds_read_b128 v[6:9], v204 offset:304
	s_waitcnt lgkmcnt(1)
	v_fmac_f32_e32 v216, v106, v2
	v_fmac_f32_e32 v216, v107, v3
	v_fmac_f32_e32 v216, v120, v4
	v_fmac_f32_e32 v216, v121, v5
	ds_read_b128 v[2:5], v204 offset:320
	s_waitcnt lgkmcnt(1)
	v_fmac_f32_e32 v216, v108, v6
	v_fmac_f32_e32 v216, v109, v7
	v_fmac_f32_e32 v216, v110, v8
	v_fmac_f32_e32 v216, v111, v9
	ds_read_b128 v[6:9], v204 offset:336
	s_waitcnt lgkmcnt(1)
	v_fmac_f32_e32 v216, v114, v2
	v_fmac_f32_e32 v216, v115, v3
	v_fmac_f32_e32 v216, v130, v4
	v_fmac_f32_e32 v216, v131, v5
	ds_read_b128 v[2:5], v204 offset:352
	s_waitcnt lgkmcnt(1)
	v_fmac_f32_e32 v216, v116, v6
	v_fmac_f32_e32 v216, v117, v7
	v_fmac_f32_e32 v216, v118, v8
	v_fmac_f32_e32 v216, v119, v9
	ds_read_b128 v[6:9], v204 offset:368
	s_waitcnt lgkmcnt(1)
	v_fmac_f32_e32 v216, v122, v2
	v_fmac_f32_e32 v216, v123, v3
	v_fmac_f32_e32 v216, v138, v4
	v_fmac_f32_e32 v216, v139, v5
	ds_read_b128 v[2:5], v204 offset:384
	s_waitcnt lgkmcnt(1)
	v_fmac_f32_e32 v216, v124, v6
	v_fmac_f32_e32 v216, v125, v7
	v_fmac_f32_e32 v216, v126, v8
	v_fmac_f32_e32 v216, v127, v9
	ds_read_b128 v[6:9], v204 offset:400
	s_waitcnt lgkmcnt(1)
	v_fmac_f32_e32 v216, v132, v2
	v_fmac_f32_e32 v216, v133, v3
	v_fmac_f32_e32 v216, v146, v4
	v_fmac_f32_e32 v216, v147, v5
	ds_read_b128 v[2:5], v204 offset:416
	s_waitcnt lgkmcnt(1)
	v_fmac_f32_e32 v216, v134, v6
	v_fmac_f32_e32 v216, v135, v7
	v_fmac_f32_e32 v216, v136, v8
	v_fmac_f32_e32 v216, v137, v9
	ds_read_b128 v[6:9], v204 offset:432
	s_waitcnt lgkmcnt(1)
	v_fmac_f32_e32 v216, v140, v2
	v_fmac_f32_e32 v216, v141, v3
	v_fmac_f32_e32 v216, v158, v4
	v_fmac_f32_e32 v216, v159, v5
	ds_read_b128 v[2:5], v204 offset:448
	s_waitcnt lgkmcnt(1)
	v_fmac_f32_e32 v216, v142, v6
	v_fmac_f32_e32 v216, v143, v7
	v_fmac_f32_e32 v216, v144, v8
	v_fmac_f32_e32 v216, v145, v9
	ds_read_b128 v[6:9], v204 offset:464
	s_waitcnt lgkmcnt(1)
	v_fmac_f32_e32 v216, v148, v2
	v_fmac_f32_e32 v216, v149, v3
	v_fmac_f32_e32 v216, v156, v4
	v_fmac_f32_e32 v216, v157, v5
	ds_read_b128 v[2:5], v204 offset:480
	s_waitcnt lgkmcnt(1)
	v_fmac_f32_e32 v216, v150, v6
	v_fmac_f32_e32 v216, v151, v7
	v_fmac_f32_e32 v216, v164, v8
	v_fmac_f32_e32 v216, v165, v9
	ds_read_b128 v[6:9], v204 offset:496
	s_waitcnt lgkmcnt(1)
	v_fmac_f32_e32 v216, v154, v2
	v_fmac_f32_e32 v216, v155, v3
	v_fmac_f32_e32 v216, v160, v4
	v_fmac_f32_e32 v216, v161, v5
	ds_read_b128 v[2:5], v204 offset:512
	s_waitcnt lgkmcnt(1)
	v_fmac_f32_e32 v216, v152, v6
	v_fmac_f32_e32 v216, v153, v7
	v_fmac_f32_e32 v216, v168, v8
	v_fmac_f32_e32 v216, v169, v9
	ds_read_b128 v[6:9], v204 offset:528
	s_waitcnt lgkmcnt(1)
	v_fmac_f32_e32 v216, v162, v2
	v_fmac_f32_e32 v216, v163, v3
	v_fmac_f32_e32 v216, v166, v4
	v_fmac_f32_e32 v216, v167, v5
	s_waitcnt lgkmcnt(0)
	v_fmac_f32_e32 v216, v170, v6
	v_fmac_f32_e32 v216, v171, v7
	v_fmac_f32_e32 v216, v172, v8
	v_fmac_f32_e32 v216, v173, v9
	v_mul_f32_e32 v2, v215, v216
	v_cvt_pk_bf16_f32 v4, v2, s0
	v_or_b32_e32 v2, s53, v202
	v_ashrrev_i32_e32 v3, 31, v2
	v_lshlrev_b64 v[2:3], 11, v[2:3]
	v_lshl_add_u64 v[0:1], v[0:1], 0, v[2:3]
	global_store_short v[0:1], v4, off
	s_barrier
	s_cbranch_scc1 .LBB0_1014

.LBB0_1212:
	s_cmpk_gt_i32 s34, 0x1ff
	s_cbranch_scc1 .LBB0_1326
	v_and_b32_e32 v0, 63, v128
	v_and_b32_e32 v1, 15, v0
	v_lshrrev_b32_e32 v2, 4, v0
	v_readfirstlane_b32 s65, v128
	s_lshr_b32 s65, s65, 6
	s_and_b32 s80, s65, 3
	s_lshl_b32 s80, s80, 2
	v_add_u32_e32 v4, s80, v2
	v_xor_b32_e32 v4, v1, v4
	v_lshlrev_b32_e32 v4, 4, v4
	v_lshl_add_u32 v18, v2, 8, v4
	v_mov_b32_e32 v19, 0
	s_movk_i32 s81, 0x5c00
	v_mul_u32_u24_e32 v5, s81, v2
	v_add_u32_e32 v138, v5, v4
	v_mov_b32_e32 v139, 0
	v_lshlrev_b32_e32 v5, 8, v1
	v_add_u32_e32 v6, 0, v2
	v_xor_b32_e32 v6, v6, v1
	v_lshl_add_u32 v142, v6, 4, v5
	v_add_u32_e32 v146, 0x10000, v142
	v_add_u32_e32 v6, 4, v2
	v_xor_b32_e32 v6, v6, v1
	v_lshl_add_u32 v143, v6, 4, v5
	v_add_u32_e32 v147, 0x10000, v143
	v_add_u32_e32 v6, 8, v2
	v_xor_b32_e32 v6, v6, v1
	v_lshl_add_u32 v144, v6, 4, v5
	v_add_u32_e32 v148, 0x10000, v144
	v_add_u32_e32 v6, 12, v2
	v_xor_b32_e32 v6, v6, v1
	v_lshl_add_u32 v145, v6, 4, v5
	v_add_u32_e32 v149, 0x10000, v145
	v_lshrrev_b32_e32 v6, 1, v2
	v_and_b32_e32 v7, 1, v2
	v_lshlrev_b32_e32 v7, 3, v7
	v_add_u32_e32 v7, v7, v5
	v_add_u32_e32 v7, 0x10000, v7
	v_add_u32_e32 v8, 0, v6
	v_xor_b32_e32 v8, v8, v1
	v_lshl_add_u32 v150, v8, 4, v7
	v_add_u32_e32 v8, 2, v6
	v_xor_b32_e32 v8, v8, v1
	v_lshl_add_u32 v154, v8, 4, v7
	v_add_u32_e32 v8, 4, v6
	v_xor_b32_e32 v8, v8, v1
	v_lshl_add_u32 v151, v8, 4, v7
	v_add_u32_e32 v8, 6, v6
	v_xor_b32_e32 v8, v8, v1
	v_lshl_add_u32 v155, v8, 4, v7
	v_add_u32_e32 v8, 8, v6
	v_xor_b32_e32 v8, v8, v1
	v_lshl_add_u32 v152, v8, 4, v7
	v_add_u32_e32 v8, 10, v6
	v_xor_b32_e32 v8, v8, v1
	v_lshl_add_u32 v156, v8, 4, v7
	v_add_u32_e32 v8, 12, v6
	v_xor_b32_e32 v8, v8, v1
	v_lshl_add_u32 v153, v8, 4, v7
	v_add_u32_e32 v8, 14, v6
	v_xor_b32_e32 v8, v8, v1
	v_lshl_add_u32 v157, v8, 4, v7
	v_mul_u32_u24_e32 v6, s81, v1
	s_mul_i32 s82, s65, 0x5c000
	v_lshl_add_u32 v7, v2, 4, v6
	v_add_u32_e32 v9, s82, v7
	v_lshlrev_b32_e32 v5, 3, v2
	v_add3_u32 v140, v6, v5, s82
	s_lshl_b32 s83, s65, 16
	v_lshl_add_u32 v7, v1, 12, v5
	v_add_u32_e32 v124, s83, v7
	s_lshl_b32 s83, s65, 4
	v_lshlrev_b32_e32 v8, 2, v2
	v_sub_u32_e32 v8, v1, v8
	v_add_u32_e32 v8, s83, v8
	v_cvt_f32_i32_e32 v125, v8
	v_add_u32_e32 v8, s83, v1
	v_add_u32_e32 v8, 1, v8
	v_cvt_f32_i32_e32 v129, v8
	v_xor_b32_e32 v8, 16, v0
	v_lshlrev_b32_e32 v127, 2, v8
	v_xor_b32_e32 v8, 32, v0
	v_lshlrev_b32_e32 v11, 2, v8
	s_add_u32 s52, s50, 0x14705000
	s_addc_u32 s53, s51, 0
	s_add_u32 s54, s50, 0x24c05000
	s_addc_u32 s55, s51, 0
	s_add_u32 s56, s50, 0x26c05000
	s_addc_u32 s57, s51, 0
	s_add_u32 s58, s50, 0x22805000
	s_addc_u32 s59, s51, 0
	s_lshl_b32 s67, s65, 10
	s_mov_b32 s64, s34
.LR3_unit:
	s_and_b32 s80, s64, 31
	s_lshr_b32 s81, s64, 5
	s_and_b32 s66, s81, 7
	s_lshr_b32 s81, s81, 3
	s_lshl_b32 s81, s81, 12
	s_lshl_b32 s80, s80, 7
	s_add_u32 s80, s80, s81
	s_mul_i32 s82, s80, 0x5c00
	s_lshl_b32 s83, s66, 8
	s_add_u32 s82, s82, s83
	s_add_u32 s82, s82, 0xc00
	s_add_u32 s68, s52, s82
	s_addc_u32 s69, s53, 0
	s_add_u32 s84, s83, 0x2000
	s_add_u32 s72, s68, s84
	s_addc_u32 s73, s69, 0
	s_lshl_b32 s84, s80, 12
	s_lshl_b32 s85, s66, 9
	s_add_u32 s84, s84, s85
	s_add_u32 s74, s58, s84
	s_addc_u32 s75, s59, 0
	s_mul_i32 s84, s65, 0x17000
	s_add_u32 s84, s84, 0x800
	s_add_u32 s86, s68, s84
	s_addc_u32 s87, s69, 0
	s_add_u32 s88, s67, 0x10000
	s_mov_b32 m0, s88
	v_lshl_add_u64 v[4:5], s[86:87], 0, v[138:139]
	global_load_lds_dwordx4 v[4:5], off
	s_add_u32 s86, s86, 0xb8000
	s_addc_u32 s87, s87, 0
	s_add_u32 s88, s88, 0x2000
	s_mov_b32 m0, s88
	v_lshl_add_u64 v[4:5], s[86:87], 0, v[138:139]
	global_load_lds_dwordx4 v[4:5], off
	s_add_u32 s86, s86, 0xb8000
	s_addc_u32 s87, s87, 0
	s_add_u32 s88, s88, 0x2000
	s_mov_b32 m0, s88
	v_lshl_add_u64 v[4:5], s[86:87], 0, v[138:139]
	global_load_lds_dwordx4 v[4:5], off
	s_add_u32 s86, s86, 0xb8000
	s_addc_u32 s87, s87, 0
	s_add_u32 s88, s88, 0x2000
	s_mov_b32 m0, s88
	v_lshl_add_u64 v[4:5], s[86:87], 0, v[138:139]
	global_load_lds_dwordx4 v[4:5], off
	global_load_dwordx4 v[20:23], v9, s[68:69] offset:0
	global_load_dwordx4 v[24:27], v9, s[68:69] offset:64
	global_load_dwordx4 v[28:31], v9, s[68:69] offset:128
	global_load_dwordx4 v[32:35], v9, s[68:69] offset:192
	s_lshl_b32 s84, s64, 16
	s_add_u32 s84, s84, s67
	s_add_u32 s76, s54, s84
	s_addc_u32 s77, s55, 0
	s_add_u32 s78, s56, s84
	s_addc_u32 s79, s57, 0
	s_mov_b32 s88, s67
	s_mov_b32 m0, s88
	v_lshl_add_u64 v[4:5], s[76:77], 0, v[18:19]
	global_load_lds_dwordx4 v[4:5], off
	s_add_u32 s76, s76, 0x2000
	s_addc_u32 s77, s77, 0
	s_add_u32 s88, s88, 0x2000
	s_mov_b32 m0, s88
	v_lshl_add_u64 v[4:5], s[76:77], 0, v[18:19]
	global_load_lds_dwordx4 v[4:5], off
	s_add_u32 s76, s76, 0x2000
	s_addc_u32 s77, s77, 0
	s_add_u32 s88, s88, 0x2000
	s_mov_b32 m0, s88
	v_lshl_add_u64 v[4:5], s[76:77], 0, v[18:19]
	global_load_lds_dwordx4 v[4:5], off
	s_add_u32 s76, s76, 0x2000
	s_addc_u32 s77, s77, 0
	s_add_u32 s88, s88, 0x2000
	s_mov_b32 m0, s88
	v_lshl_add_u64 v[4:5], s[76:77], 0, v[18:19]
	global_load_lds_dwordx4 v[4:5], off
	s_add_u32 s76, s76, 0x2000
	s_addc_u32 s77, s77, 0
	s_add_u32 s88, s88, 0x2000
	s_mov_b32 m0, s88
	v_lshl_add_u64 v[4:5], s[76:77], 0, v[18:19]
	global_load_lds_dwordx4 v[4:5], off
	s_add_u32 s76, s76, 0x2000
	s_addc_u32 s77, s77, 0
	s_add_u32 s88, s88, 0x2000
	s_mov_b32 m0, s88
	v_lshl_add_u64 v[4:5], s[76:77], 0, v[18:19]
	global_load_lds_dwordx4 v[4:5], off
	s_add_u32 s76, s76, 0x2000
	s_addc_u32 s77, s77, 0
	s_add_u32 s88, s88, 0x2000
	s_mov_b32 m0, s88
	v_lshl_add_u64 v[4:5], s[76:77], 0, v[18:19]
	global_load_lds_dwordx4 v[4:5], off
	s_add_u32 s76, s76, 0x2000
	s_addc_u32 s77, s77, 0
	s_add_u32 s88, s88, 0x2000
	s_mov_b32 m0, s88
	v_lshl_add_u64 v[4:5], s[76:77], 0, v[18:19]
	global_load_lds_dwordx4 v[4:5], off
	s_sub_i32 s85, -5, s66
	v_cvt_f32_i32_e32 v4, s85
	v_exp_f32_e32 v4, v4
	s_nop 0
	v_sub_f32_e32 v4, 1.0, v4
	v_log_f32_e32 v16, v4
	s_nop 0
	v_mul_f32_e32 v126, v129, v16
	v_exp_f32_e32 v126, v126
	s_waitcnt vmcnt(8)
	s_barrier
	ds_read_b128 v[52:55], v146 offset:0
	ds_read_b128 v[56:59], v147 offset:0
	ds_read_b128 v[60:63], v148 offset:0
	ds_read_b128 v[64:67], v149 offset:0
	ds_read_b128 v[68:71], v146 offset:4096
	ds_read_b128 v[72:75], v147 offset:4096
	ds_read_b128 v[76:79], v148 offset:4096
	ds_read_b128 v[80:83], v149 offset:4096
	ds_read_b128 v[84:87], v146 offset:8192
	ds_read_b128 v[88:91], v147 offset:8192
	ds_read_b128 v[92:95], v148 offset:8192
	ds_read_b128 v[96:99], v149 offset:8192
	ds_read_b128 v[100:103], v146 offset:12288
	ds_read_b128 v[104:107], v147 offset:12288
	ds_read_b128 v[108:111], v148 offset:12288
	ds_read_b128 v[112:115], v149 offset:12288
	ds_read_b128 v[158:161], v146 offset:16384
	ds_read_b128 v[162:165], v147 offset:16384
	ds_read_b128 v[166:169], v148 offset:16384
	ds_read_b128 v[170:173], v149 offset:16384
	ds_read_b128 v[174:177], v146 offset:20480
	ds_read_b128 v[178:181], v147 offset:20480
	ds_read_b128 v[182:185], v148 offset:20480
	ds_read_b128 v[186:189], v149 offset:20480
	ds_read_b128 v[190:193], v146 offset:24576
	ds_read_b128 v[194:197], v147 offset:24576
	ds_read_b128 v[198:201], v148 offset:24576
	ds_read_b128 v[202:205], v149 offset:24576
	ds_read_b128 v[206:209], v146 offset:28672
	ds_read_b128 v[210:213], v147 offset:28672
	ds_read_b128 v[214:217], v148 offset:28672
	ds_read_b128 v[218:221], v149 offset:28672
	s_waitcnt lgkmcnt(0)
	s_barrier
	s_add_u32 s88, s67, 0x10000
	s_mov_b32 m0, s88
	v_lshl_add_u64 v[4:5], s[78:79], 0, v[18:19]
	global_load_lds_dwordx4 v[4:5], off
	s_add_u32 s78, s78, 0x2000
	s_addc_u32 s79, s79, 0
	s_add_u32 s88, s88, 0x2000
	s_mov_b32 m0, s88
	v_lshl_add_u64 v[4:5], s[78:79], 0, v[18:19]
	global_load_lds_dwordx4 v[4:5], off
	s_add_u32 s78, s78, 0x2000
	s_addc_u32 s79, s79, 0
	s_add_u32 s88, s88, 0x2000
	s_mov_b32 m0, s88
	v_lshl_add_u64 v[4:5], s[78:79], 0, v[18:19]
	global_load_lds_dwordx4 v[4:5], off
	s_add_u32 s78, s78, 0x2000
	s_addc_u32 s79, s79, 0
	s_add_u32 s88, s88, 0x2000
	s_mov_b32 m0, s88
	v_lshl_add_u64 v[4:5], s[78:79], 0, v[18:19]
	global_load_lds_dwordx4 v[4:5], off
	s_add_u32 s78, s78, 0x2000
	s_addc_u32 s79, s79, 0
	s_add_u32 s88, s88, 0x2000
	s_mov_b32 m0, s88
	v_lshl_add_u64 v[4:5], s[78:79], 0, v[18:19]
	global_load_lds_dwordx4 v[4:5], off
	s_add_u32 s78, s78, 0x2000
	s_addc_u32 s79, s79, 0
	s_add_u32 s88, s88, 0x2000
	s_mov_b32 m0, s88
	v_lshl_add_u64 v[4:5], s[78:79], 0, v[18:19]
	global_load_lds_dwordx4 v[4:5], off
	s_add_u32 s78, s78, 0x2000
	s_addc_u32 s79, s79, 0
	s_add_u32 s88, s88, 0x2000
	s_mov_b32 m0, s88
	v_lshl_add_u64 v[4:5], s[78:79], 0, v[18:19]
	global_load_lds_dwordx4 v[4:5], off
	s_add_u32 s78, s78, 0x2000
	s_addc_u32 s79, s79, 0
	s_add_u32 s88, s88, 0x2000
	s_mov_b32 m0, s88
	v_lshl_add_u64 v[4:5], s[78:79], 0, v[18:19]
	global_load_lds_dwordx4 v[4:5], off
	v_mfma_f32_16x16x32_bf16 v[222:225], v[52:55], v[20:23], 0
	v_mfma_f32_16x16x32_bf16 v[222:225], v[56:59], v[24:27], v[222:225]
	v_mfma_f32_16x16x32_bf16 v[222:225], v[60:63], v[28:31], v[222:225]
	v_mfma_f32_16x16x32_bf16 v[222:225], v[64:67], v[32:35], v[222:225]
	v_mfma_f32_16x16x32_bf16 v[226:229], v[68:71], v[20:23], 0
	v_mfma_f32_16x16x32_bf16 v[226:229], v[72:75], v[24:27], v[226:229]
	v_mfma_f32_16x16x32_bf16 v[226:229], v[76:79], v[28:31], v[226:229]
	v_mfma_f32_16x16x32_bf16 v[226:229], v[80:83], v[32:35], v[226:229]
	v_mfma_f32_16x16x32_bf16 v[230:233], v[84:87], v[20:23], 0
	v_mfma_f32_16x16x32_bf16 v[230:233], v[88:91], v[24:27], v[230:233]
	v_mfma_f32_16x16x32_bf16 v[230:233], v[92:95], v[28:31], v[230:233]
	v_mfma_f32_16x16x32_bf16 v[230:233], v[96:99], v[32:35], v[230:233]
	v_mfma_f32_16x16x32_bf16 v[236:239], v[100:103], v[20:23], 0
	v_mfma_f32_16x16x32_bf16 v[236:239], v[104:107], v[24:27], v[236:239]
	v_mfma_f32_16x16x32_bf16 v[236:239], v[108:111], v[28:31], v[236:239]
	v_mfma_f32_16x16x32_bf16 v[236:239], v[112:115], v[32:35], v[236:239]
	v_mfma_f32_16x16x32_bf16 v[240:243], v[158:161], v[20:23], 0
	v_mfma_f32_16x16x32_bf16 v[240:243], v[162:165], v[24:27], v[240:243]
	v_mfma_f32_16x16x32_bf16 v[240:243], v[166:169], v[28:31], v[240:243]
	v_mfma_f32_16x16x32_bf16 v[240:243], v[170:173], v[32:35], v[240:243]
	v_mfma_f32_16x16x32_bf16 v[244:247], v[174:177], v[20:23], 0
	v_mfma_f32_16x16x32_bf16 v[244:247], v[178:181], v[24:27], v[244:247]
	v_mfma_f32_16x16x32_bf16 v[244:247], v[182:185], v[28:31], v[244:247]
	v_mfma_f32_16x16x32_bf16 v[244:247], v[186:189], v[32:35], v[244:247]
	v_mfma_f32_16x16x32_bf16 v[248:251], v[190:193], v[20:23], 0
	v_mfma_f32_16x16x32_bf16 v[248:251], v[194:197], v[24:27], v[248:251]
	v_mfma_f32_16x16x32_bf16 v[248:251], v[198:201], v[28:31], v[248:251]
	v_mfma_f32_16x16x32_bf16 v[248:251], v[202:205], v[32:35], v[248:251]
	v_mfma_f32_16x16x32_bf16 v[252:255], v[206:209], v[20:23], 0
	v_mfma_f32_16x16x32_bf16 v[252:255], v[210:213], v[24:27], v[252:255]
	v_mfma_f32_16x16x32_bf16 v[252:255], v[214:217], v[28:31], v[252:255]
	v_mfma_f32_16x16x32_bf16 v[252:255], v[218:221], v[32:35], v[252:255]
	v_add_f32_e32 v4, 0x00000000, v125
	v_mul_f32_e32 v4, v4, v16
	v_exp_f32_e32 v4, v4
	s_nop 4
	v_cmp_le_f32_e32 vcc, 0x00000000, v125
	v_add_f32_e32 v5, 0xbf800000, v125
	v_mul_f32_e32 v5, v5, v16
	v_cndmask_b32_e32 v222, 0, v222, vcc
	v_exp_f32_e32 v5, v5
	v_mul_f32_e32 v222, v222, v4
	v_cmp_le_f32_e32 vcc, 0x3f800000, v125
	v_add_f32_e32 v4, 0xc0000000, v125
	v_mul_f32_e32 v4, v4, v16
	v_cndmask_b32_e32 v223, 0, v223, vcc
	v_exp_f32_e32 v4, v4
	v_mul_f32_e32 v223, v223, v5
	v_cmp_le_f32_e32 vcc, 0x40000000, v125
	v_add_f32_e32 v5, 0xc0400000, v125
	v_mul_f32_e32 v5, v5, v16
	v_cndmask_b32_e32 v224, 0, v224, vcc
	v_exp_f32_e32 v5, v5
	v_mul_f32_e32 v224, v224, v4
	v_cmp_le_f32_e32 vcc, 0x40400000, v125
	v_add_f32_e32 v4, 0xc1800000, v125
	v_mul_f32_e32 v4, v4, v16
	v_cndmask_b32_e32 v225, 0, v225, vcc
	v_exp_f32_e32 v4, v4
	v_mul_f32_e32 v225, v225, v5
	v_cmp_le_f32_e32 vcc, 0x41800000, v125
	v_add_f32_e32 v5, 0xc1880000, v125
	v_mul_f32_e32 v5, v5, v16
	v_cndmask_b32_e32 v226, 0, v226, vcc
	v_exp_f32_e32 v5, v5
	v_mul_f32_e32 v226, v226, v4
	v_cmp_le_f32_e32 vcc, 0x41880000, v125
	v_add_f32_e32 v4, 0xc1900000, v125
	v_mul_f32_e32 v4, v4, v16
	v_cndmask_b32_e32 v227, 0, v227, vcc
	v_exp_f32_e32 v4, v4
	v_mul_f32_e32 v227, v227, v5
	v_cmp_le_f32_e32 vcc, 0x41900000, v125
	v_add_f32_e32 v5, 0xc1980000, v125
	v_mul_f32_e32 v5, v5, v16
	v_cndmask_b32_e32 v228, 0, v228, vcc
	v_exp_f32_e32 v5, v5
	v_mul_f32_e32 v228, v228, v4
	v_cmp_le_f32_e32 vcc, 0x41980000, v125
	v_add_f32_e32 v4, 0xc2000000, v125
	v_mul_f32_e32 v4, v4, v16
	v_cndmask_b32_e32 v229, 0, v229, vcc
	v_exp_f32_e32 v4, v4
	v_mul_f32_e32 v229, v229, v5
	v_cmp_le_f32_e32 vcc, 0x42000000, v125
	v_add_f32_e32 v5, 0xc2040000, v125
	v_mul_f32_e32 v5, v5, v16
	v_cndmask_b32_e32 v230, 0, v230, vcc
	v_exp_f32_e32 v5, v5
	v_mul_f32_e32 v230, v230, v4
	v_cmp_le_f32_e32 vcc, 0x42040000, v125
	v_add_f32_e32 v4, 0xc2080000, v125
	v_mul_f32_e32 v4, v4, v16
	v_cndmask_b32_e32 v231, 0, v231, vcc
	v_exp_f32_e32 v4, v4
	v_mul_f32_e32 v231, v231, v5
	v_cmp_le_f32_e32 vcc, 0x42080000, v125
	v_add_f32_e32 v5, 0xc20c0000, v125
	v_mul_f32_e32 v5, v5, v16
	v_cndmask_b32_e32 v232, 0, v232, vcc
	v_exp_f32_e32 v5, v5
	v_mul_f32_e32 v232, v232, v4
	v_cmp_le_f32_e32 vcc, 0x420c0000, v125
	v_add_f32_e32 v4, 0xc2400000, v125
	v_mul_f32_e32 v4, v4, v16
	v_cndmask_b32_e32 v233, 0, v233, vcc
	v_exp_f32_e32 v4, v4
	v_mul_f32_e32 v233, v233, v5
	v_cmp_le_f32_e32 vcc, 0x42400000, v125
	v_add_f32_e32 v5, 0xc2440000, v125
	v_mul_f32_e32 v5, v5, v16
	v_cndmask_b32_e32 v236, 0, v236, vcc
	v_exp_f32_e32 v5, v5
	v_mul_f32_e32 v236, v236, v4
	v_cmp_le_f32_e32 vcc, 0x42440000, v125
	v_add_f32_e32 v4, 0xc2480000, v125
	v_mul_f32_e32 v4, v4, v16
	v_cndmask_b32_e32 v237, 0, v237, vcc
	v_exp_f32_e32 v4, v4
	v_mul_f32_e32 v237, v237, v5
	v_cmp_le_f32_e32 vcc, 0x42480000, v125
	v_add_f32_e32 v5, 0xc24c0000, v125
	v_mul_f32_e32 v5, v5, v16
	v_cndmask_b32_e32 v238, 0, v238, vcc
	v_exp_f32_e32 v5, v5
	v_mul_f32_e32 v238, v238, v4
	v_cmp_le_f32_e32 vcc, 0x424c0000, v125
	v_add_f32_e32 v4, 0xc2800000, v125
	v_mul_f32_e32 v4, v4, v16
	v_cndmask_b32_e32 v239, 0, v239, vcc
	v_exp_f32_e32 v4, v4
	v_mul_f32_e32 v239, v239, v5
	v_cmp_le_f32_e32 vcc, 0x42800000, v125
	v_add_f32_e32 v5, 0xc2820000, v125
	v_mul_f32_e32 v5, v5, v16
	v_cndmask_b32_e32 v240, 0, v240, vcc
	v_exp_f32_e32 v5, v5
	v_mul_f32_e32 v240, v240, v4
	v_cmp_le_f32_e32 vcc, 0x42820000, v125
	v_add_f32_e32 v4, 0xc2840000, v125
	v_mul_f32_e32 v4, v4, v16
	v_cndmask_b32_e32 v241, 0, v241, vcc
	v_exp_f32_e32 v4, v4
	v_mul_f32_e32 v241, v241, v5
	v_cmp_le_f32_e32 vcc, 0x42840000, v125
	v_add_f32_e32 v5, 0xc2860000, v125
	v_mul_f32_e32 v5, v5, v16
	v_cndmask_b32_e32 v242, 0, v242, vcc
	v_exp_f32_e32 v5, v5
	v_mul_f32_e32 v242, v242, v4
	v_cmp_le_f32_e32 vcc, 0x42860000, v125
	v_add_f32_e32 v4, 0xc2a00000, v125
	v_mul_f32_e32 v4, v4, v16
	v_cndmask_b32_e32 v243, 0, v243, vcc
	v_exp_f32_e32 v4, v4
	v_mul_f32_e32 v243, v243, v5
	v_cmp_le_f32_e32 vcc, 0x42a00000, v125
	v_add_f32_e32 v5, 0xc2a20000, v125
	v_mul_f32_e32 v5, v5, v16
	v_cndmask_b32_e32 v244, 0, v244, vcc
	v_exp_f32_e32 v5, v5
	v_mul_f32_e32 v244, v244, v4
	v_cmp_le_f32_e32 vcc, 0x42a20000, v125
	v_add_f32_e32 v4, 0xc2a40000, v125
	v_mul_f32_e32 v4, v4, v16
	v_cndmask_b32_e32 v245, 0, v245, vcc
	v_exp_f32_e32 v4, v4
	v_mul_f32_e32 v245, v245, v5
	v_cmp_le_f32_e32 vcc, 0x42a40000, v125
	v_add_f32_e32 v5, 0xc2a60000, v125
	v_mul_f32_e32 v5, v5, v16
	v_cndmask_b32_e32 v246, 0, v246, vcc
	v_exp_f32_e32 v5, v5
	v_mul_f32_e32 v246, v246, v4
	v_cmp_le_f32_e32 vcc, 0x42a60000, v125
	v_add_f32_e32 v4, 0xc2c00000, v125
	v_mul_f32_e32 v4, v4, v16
	v_cndmask_b32_e32 v247, 0, v247, vcc
	v_exp_f32_e32 v4, v4
	v_mul_f32_e32 v247, v247, v5
	v_cmp_le_f32_e32 vcc, 0x42c00000, v125
	v_add_f32_e32 v5, 0xc2c20000, v125
	v_mul_f32_e32 v5, v5, v16
	v_cndmask_b32_e32 v248, 0, v248, vcc
	v_exp_f32_e32 v5, v5
	v_mul_f32_e32 v248, v248, v4
	v_cmp_le_f32_e32 vcc, 0x42c20000, v125
	v_add_f32_e32 v4, 0xc2c40000, v125
	v_mul_f32_e32 v4, v4, v16
	v_cndmask_b32_e32 v249, 0, v249, vcc
	v_exp_f32_e32 v4, v4
	v_mul_f32_e32 v249, v249, v5
	v_cmp_le_f32_e32 vcc, 0x42c40000, v125
	v_add_f32_e32 v5, 0xc2c60000, v125
	v_mul_f32_e32 v5, v5, v16
	v_cndmask_b32_e32 v250, 0, v250, vcc
	v_exp_f32_e32 v5, v5
	v_mul_f32_e32 v250, v250, v4
	v_cmp_le_f32_e32 vcc, 0x42c60000, v125
	v_add_f32_e32 v4, 0xc2e00000, v125
	v_mul_f32_e32 v4, v4, v16
	v_cndmask_b32_e32 v251, 0, v251, vcc
	v_exp_f32_e32 v4, v4
	v_mul_f32_e32 v251, v251, v5
	v_cmp_le_f32_e32 vcc, 0x42e00000, v125
	v_add_f32_e32 v5, 0xc2e20000, v125
	v_mul_f32_e32 v5, v5, v16
	v_cndmask_b32_e32 v252, 0, v252, vcc
	v_exp_f32_e32 v5, v5
	v_mul_f32_e32 v252, v252, v4
	v_cmp_le_f32_e32 vcc, 0x42e20000, v125
	v_add_f32_e32 v4, 0xc2e40000, v125
	v_mul_f32_e32 v4, v4, v16
	v_cndmask_b32_e32 v253, 0, v253, vcc
	v_exp_f32_e32 v4, v4
	v_mul_f32_e32 v253, v253, v5
	v_cmp_le_f32_e32 vcc, 0x42e40000, v125
	v_add_f32_e32 v5, 0xc2e60000, v125
	v_mul_f32_e32 v5, v5, v16
	v_cndmask_b32_e32 v254, 0, v254, vcc
	v_exp_f32_e32 v5, v5
	v_mul_f32_e32 v254, v254, v4
	v_cmp_le_f32_e32 vcc, 0x42e60000, v125
	s_nop 1
	v_cndmask_b32_e32 v255, 0, v255, vcc
	v_mul_f32_e32 v255, v255, v5
	v_cvt_pk_bf16_f32 v36, v222, v223
	v_cvt_pk_bf16_f32 v37, v224, v225
	v_cvt_pk_bf16_f32 v38, v226, v227
	v_cvt_pk_bf16_f32 v39, v228, v229
	v_cvt_pk_bf16_f32 v40, v230, v231
	v_cvt_pk_bf16_f32 v41, v232, v233
	v_cvt_pk_bf16_f32 v42, v236, v237
	v_cvt_pk_bf16_f32 v43, v238, v239
	v_cvt_pk_bf16_f32 v44, v240, v241
	v_cvt_pk_bf16_f32 v45, v242, v243
	v_cvt_pk_bf16_f32 v46, v244, v245
	v_cvt_pk_bf16_f32 v47, v246, v247
	v_cvt_pk_bf16_f32 v48, v248, v249
	v_cvt_pk_bf16_f32 v49, v250, v251
	v_cvt_pk_bf16_f32 v50, v252, v253
	v_cvt_pk_bf16_f32 v51, v254, v255
	global_load_dwordx2 v[222:223], v140, s[72:73] offset:0
	global_load_dwordx2 v[224:225], v140, s[72:73] offset:32
	global_load_dwordx2 v[226:227], v140, s[72:73] offset:64
	global_load_dwordx2 v[228:229], v140, s[72:73] offset:96
	global_load_dwordx2 v[230:231], v140, s[72:73] offset:128
	global_load_dwordx2 v[232:233], v140, s[72:73] offset:160
	global_load_dwordx2 v[236:237], v140, s[72:73] offset:192
	global_load_dwordx2 v[238:239], v140, s[72:73] offset:224
	global_load_dwordx2 v[240:241], v140, s[72:73] offset:256
	global_load_dwordx2 v[242:243], v140, s[72:73] offset:288
	global_load_dwordx2 v[244:245], v140, s[72:73] offset:320
	global_load_dwordx2 v[246:247], v140, s[72:73] offset:352
	global_load_dwordx2 v[248:249], v140, s[72:73] offset:384
	global_load_dwordx2 v[250:251], v140, s[72:73] offset:416
	global_load_dwordx2 v[252:253], v140, s[72:73] offset:448
	global_load_dwordx2 v[254:255], v140, s[72:73] offset:480
	s_waitcnt vmcnt(16)
	s_barrier
	ds_read_b128 v[158:161], v142 offset:0
	ds_read_b128 v[162:165], v143 offset:0
	ds_read_b128 v[166:169], v144 offset:0
	ds_read_b128 v[170:173], v145 offset:0
	ds_read_b64 v[174:175], v150 offset:0
	ds_read_b64 v[176:177], v154 offset:0
	ds_read_b64 v[178:179], v151 offset:0
	ds_read_b64 v[180:181], v155 offset:0
	ds_read_b64 v[182:183], v152 offset:0
	ds_read_b64 v[184:185], v156 offset:0
	ds_read_b64 v[186:187], v153 offset:0
	ds_read_b64 v[188:189], v157 offset:0
	ds_read_b128 v[190:193], v142 offset:4096
	ds_read_b128 v[194:197], v143 offset:4096
	ds_read_b128 v[198:201], v144 offset:4096
	ds_read_b128 v[202:205], v145 offset:4096
	ds_read_b64 v[206:207], v150 offset:4096
	ds_read_b64 v[208:209], v154 offset:4096
	ds_read_b64 v[210:211], v151 offset:4096
	ds_read_b64 v[212:213], v155 offset:4096
	ds_read_b64 v[214:215], v152 offset:4096
	ds_read_b64 v[216:217], v156 offset:4096
	ds_read_b64 v[218:219], v153 offset:4096
	ds_read_b64 v[220:221], v157 offset:4096
	s_waitcnt lgkmcnt(12)
	v_mfma_f32_16x16x32_bf16 v[116:119], v[158:161], v[20:23], 0
	v_mfma_f32_16x16x32_bf16 v[116:119], v[162:165], v[24:27], v[116:119]
	v_mfma_f32_16x16x32_bf16 v[116:119], v[166:169], v[28:31], v[116:119]
	v_mfma_f32_16x16x32_bf16 v[116:119], v[170:173], v[32:35], v[116:119]
	v_mfma_f32_16x16x32_bf16 v[120:123], v[174:177], v[36:39], 0
	v_mfma_f32_16x16x32_bf16 v[120:123], v[178:181], v[40:43], v[120:123]
	v_mfma_f32_16x16x32_bf16 v[120:123], v[182:185], v[44:47], v[120:123]
	v_mfma_f32_16x16x32_bf16 v[120:123], v[186:189], v[48:51], v[120:123]
	ds_read_b128 v[158:161], v142 offset:8192
	ds_read_b128 v[162:165], v143 offset:8192
	ds_read_b128 v[166:169], v144 offset:8192
	ds_read_b128 v[170:173], v145 offset:8192
	ds_read_b64 v[174:175], v150 offset:8192
	ds_read_b64 v[176:177], v154 offset:8192
	ds_read_b64 v[178:179], v151 offset:8192
	ds_read_b64 v[180:181], v155 offset:8192
	ds_read_b64 v[182:183], v152 offset:8192
	ds_read_b64 v[184:185], v156 offset:8192
	ds_read_b64 v[186:187], v153 offset:8192
	ds_read_b64 v[188:189], v157 offset:8192
	s_waitcnt lgkmcnt(12)
	v_mfma_f32_16x16x32_bf16 v[130:133], v[190:193], v[20:23], 0
	v_mfma_f32_16x16x32_bf16 v[130:133], v[194:197], v[24:27], v[130:133]
	v_mfma_f32_16x16x32_bf16 v[130:133], v[198:201], v[28:31], v[130:133]
	v_mfma_f32_16x16x32_bf16 v[130:133], v[202:205], v[32:35], v[130:133]
	v_mfma_f32_16x16x32_bf16 v[134:137], v[206:209], v[36:39], 0
	v_mfma_f32_16x16x32_bf16 v[134:137], v[210:213], v[40:43], v[134:137]
	v_mfma_f32_16x16x32_bf16 v[134:137], v[214:217], v[44:47], v[134:137]
	v_mfma_f32_16x16x32_bf16 v[134:137], v[218:221], v[48:51], v[134:137]
	v_fma_f32 v52, v116, v126, v120
	v_fma_f32 v53, v117, v126, v121
	v_fma_f32 v54, v118, v126, v122
	v_fma_f32 v55, v119, v126, v123
	ds_read_b128 v[190:193], v142 offset:12288
	ds_read_b128 v[194:197], v143 offset:12288
	ds_read_b128 v[198:201], v144 offset:12288
	ds_read_b128 v[202:205], v145 offset:12288
	ds_read_b64 v[206:207], v150 offset:12288
	ds_read_b64 v[208:209], v154 offset:12288
	ds_read_b64 v[210:211], v151 offset:12288
	ds_read_b64 v[212:213], v155 offset:12288
	ds_read_b64 v[214:215], v152 offset:12288
	ds_read_b64 v[216:217], v156 offset:12288
	ds_read_b64 v[218:219], v153 offset:12288
	ds_read_b64 v[220:221], v157 offset:12288
	s_waitcnt lgkmcnt(12)
	v_mfma_f32_16x16x32_bf16 v[116:119], v[158:161], v[20:23], 0
	v_mfma_f32_16x16x32_bf16 v[116:119], v[162:165], v[24:27], v[116:119]
	v_mfma_f32_16x16x32_bf16 v[116:119], v[166:169], v[28:31], v[116:119]
	v_mfma_f32_16x16x32_bf16 v[116:119], v[170:173], v[32:35], v[116:119]
	v_mfma_f32_16x16x32_bf16 v[120:123], v[174:177], v[36:39], 0
	v_mfma_f32_16x16x32_bf16 v[120:123], v[178:181], v[40:43], v[120:123]
	v_mfma_f32_16x16x32_bf16 v[120:123], v[182:185], v[44:47], v[120:123]
	v_mfma_f32_16x16x32_bf16 v[120:123], v[186:189], v[48:51], v[120:123]
	v_fma_f32 v56, v130, v126, v134
	v_fma_f32 v57, v131, v126, v135
	v_fma_f32 v58, v132, v126, v136
	v_fma_f32 v59, v133, v126, v137
	ds_read_b128 v[158:161], v142 offset:16384
	ds_read_b128 v[162:165], v143 offset:16384
	ds_read_b128 v[166:169], v144 offset:16384
	ds_read_b128 v[170:173], v145 offset:16384
	ds_read_b64 v[174:175], v150 offset:16384
	ds_read_b64 v[176:177], v154 offset:16384
	ds_read_b64 v[178:179], v151 offset:16384
	ds_read_b64 v[180:181], v155 offset:16384
	ds_read_b64 v[182:183], v152 offset:16384
	ds_read_b64 v[184:185], v156 offset:16384
	ds_read_b64 v[186:187], v153 offset:16384
	ds_read_b64 v[188:189], v157 offset:16384
	s_waitcnt lgkmcnt(12)
	v_mfma_f32_16x16x32_bf16 v[130:133], v[190:193], v[20:23], 0
	v_mfma_f32_16x16x32_bf16 v[130:133], v[194:197], v[24:27], v[130:133]
	v_mfma_f32_16x16x32_bf16 v[130:133], v[198:201], v[28:31], v[130:133]
	v_mfma_f32_16x16x32_bf16 v[130:133], v[202:205], v[32:35], v[130:133]
	v_mfma_f32_16x16x32_bf16 v[134:137], v[206:209], v[36:39], 0
	v_mfma_f32_16x16x32_bf16 v[134:137], v[210:213], v[40:43], v[134:137]
	v_mfma_f32_16x16x32_bf16 v[134:137], v[214:217], v[44:47], v[134:137]
	v_mfma_f32_16x16x32_bf16 v[134:137], v[218:221], v[48:51], v[134:137]
	v_fma_f32 v60, v116, v126, v120
	v_fma_f32 v61, v117, v126, v121
	v_fma_f32 v62, v118, v126, v122
	v_fma_f32 v63, v119, v126, v123
	ds_read_b128 v[190:193], v142 offset:20480
	ds_read_b128 v[194:197], v143 offset:20480
	ds_read_b128 v[198:201], v144 offset:20480
	ds_read_b128 v[202:205], v145 offset:20480
	ds_read_b64 v[206:207], v150 offset:20480
	ds_read_b64 v[208:209], v154 offset:20480
	ds_read_b64 v[210:211], v151 offset:20480
	ds_read_b64 v[212:213], v155 offset:20480
	ds_read_b64 v[214:215], v152 offset:20480
	ds_read_b64 v[216:217], v156 offset:20480
	ds_read_b64 v[218:219], v153 offset:20480
	ds_read_b64 v[220:221], v157 offset:20480
	s_waitcnt lgkmcnt(12)
	v_mfma_f32_16x16x32_bf16 v[116:119], v[158:161], v[20:23], 0
	v_mfma_f32_16x16x32_bf16 v[116:119], v[162:165], v[24:27], v[116:119]
	v_mfma_f32_16x16x32_bf16 v[116:119], v[166:169], v[28:31], v[116:119]
	v_mfma_f32_16x16x32_bf16 v[116:119], v[170:173], v[32:35], v[116:119]
	v_mfma_f32_16x16x32_bf16 v[120:123], v[174:177], v[36:39], 0
	v_mfma_f32_16x16x32_bf16 v[120:123], v[178:181], v[40:43], v[120:123]
	v_mfma_f32_16x16x32_bf16 v[120:123], v[182:185], v[44:47], v[120:123]
	v_mfma_f32_16x16x32_bf16 v[120:123], v[186:189], v[48:51], v[120:123]
	v_fma_f32 v64, v130, v126, v134
	v_fma_f32 v65, v131, v126, v135
	v_fma_f32 v66, v132, v126, v136
	v_fma_f32 v67, v133, v126, v137
	ds_read_b128 v[158:161], v142 offset:24576
	ds_read_b128 v[162:165], v143 offset:24576
	ds_read_b128 v[166:169], v144 offset:24576
	ds_read_b128 v[170:173], v145 offset:24576
	ds_read_b64 v[174:175], v150 offset:24576
	ds_read_b64 v[176:177], v154 offset:24576
	ds_read_b64 v[178:179], v151 offset:24576
	ds_read_b64 v[180:181], v155 offset:24576
	ds_read_b64 v[182:183], v152 offset:24576
	ds_read_b64 v[184:185], v156 offset:24576
	ds_read_b64 v[186:187], v153 offset:24576
	ds_read_b64 v[188:189], v157 offset:24576
	s_waitcnt lgkmcnt(12)
	v_mfma_f32_16x16x32_bf16 v[130:133], v[190:193], v[20:23], 0
	v_mfma_f32_16x16x32_bf16 v[130:133], v[194:197], v[24:27], v[130:133]
	v_mfma_f32_16x16x32_bf16 v[130:133], v[198:201], v[28:31], v[130:133]
	v_mfma_f32_16x16x32_bf16 v[130:133], v[202:205], v[32:35], v[130:133]
	v_mfma_f32_16x16x32_bf16 v[134:137], v[206:209], v[36:39], 0
	v_mfma_f32_16x16x32_bf16 v[134:137], v[210:213], v[40:43], v[134:137]
	v_mfma_f32_16x16x32_bf16 v[134:137], v[214:217], v[44:47], v[134:137]
	v_mfma_f32_16x16x32_bf16 v[134:137], v[218:221], v[48:51], v[134:137]
	v_fma_f32 v68, v116, v126, v120
	v_fma_f32 v69, v117, v126, v121
	v_fma_f32 v70, v118, v126, v122
	v_fma_f32 v71, v119, v126, v123
	ds_read_b128 v[190:193], v142 offset:28672
	ds_read_b128 v[194:197], v143 offset:28672
	ds_read_b128 v[198:201], v144 offset:28672
	ds_read_b128 v[202:205], v145 offset:28672
	ds_read_b64 v[206:207], v150 offset:28672
	ds_read_b64 v[208:209], v154 offset:28672
	ds_read_b64 v[210:211], v151 offset:28672
	ds_read_b64 v[212:213], v155 offset:28672
	ds_read_b64 v[214:215], v152 offset:28672
	ds_read_b64 v[216:217], v156 offset:28672
	ds_read_b64 v[218:219], v153 offset:28672
	ds_read_b64 v[220:221], v157 offset:28672
	s_waitcnt lgkmcnt(12)
	v_mfma_f32_16x16x32_bf16 v[116:119], v[158:161], v[20:23], 0
	v_mfma_f32_16x16x32_bf16 v[116:119], v[162:165], v[24:27], v[116:119]
	v_mfma_f32_16x16x32_bf16 v[116:119], v[166:169], v[28:31], v[116:119]
	v_mfma_f32_16x16x32_bf16 v[116:119], v[170:173], v[32:35], v[116:119]
	v_mfma_f32_16x16x32_bf16 v[120:123], v[174:177], v[36:39], 0
	v_mfma_f32_16x16x32_bf16 v[120:123], v[178:181], v[40:43], v[120:123]
	v_mfma_f32_16x16x32_bf16 v[120:123], v[182:185], v[44:47], v[120:123]
	v_mfma_f32_16x16x32_bf16 v[120:123], v[186:189], v[48:51], v[120:123]
	v_fma_f32 v72, v130, v126, v134
	v_fma_f32 v73, v131, v126, v135
	v_fma_f32 v74, v132, v126, v136
	v_fma_f32 v75, v133, v126, v137
	ds_read_b128 v[158:161], v142 offset:32768
	ds_read_b128 v[162:165], v143 offset:32768
	ds_read_b128 v[166:169], v144 offset:32768
	ds_read_b128 v[170:173], v145 offset:32768
	ds_read_b64 v[174:175], v150 offset:32768
	ds_read_b64 v[176:177], v154 offset:32768
	ds_read_b64 v[178:179], v151 offset:32768
	ds_read_b64 v[180:181], v155 offset:32768
	ds_read_b64 v[182:183], v152 offset:32768
	ds_read_b64 v[184:185], v156 offset:32768
	ds_read_b64 v[186:187], v153 offset:32768
	ds_read_b64 v[188:189], v157 offset:32768
	s_waitcnt lgkmcnt(12)
	v_mfma_f32_16x16x32_bf16 v[130:133], v[190:193], v[20:23], 0
	v_mfma_f32_16x16x32_bf16 v[130:133], v[194:197], v[24:27], v[130:133]
	v_mfma_f32_16x16x32_bf16 v[130:133], v[198:201], v[28:31], v[130:133]
	v_mfma_f32_16x16x32_bf16 v[130:133], v[202:205], v[32:35], v[130:133]
	v_mfma_f32_16x16x32_bf16 v[134:137], v[206:209], v[36:39], 0
	v_mfma_f32_16x16x32_bf16 v[134:137], v[210:213], v[40:43], v[134:137]
	v_mfma_f32_16x16x32_bf16 v[134:137], v[214:217], v[44:47], v[134:137]
	v_mfma_f32_16x16x32_bf16 v[134:137], v[218:221], v[48:51], v[134:137]
	v_fma_f32 v76, v116, v126, v120
	v_fma_f32 v77, v117, v126, v121
	v_fma_f32 v78, v118, v126, v122
	v_fma_f32 v79, v119, v126, v123
	ds_read_b128 v[190:193], v142 offset:36864
	ds_read_b128 v[194:197], v143 offset:36864
	ds_read_b128 v[198:201], v144 offset:36864
	ds_read_b128 v[202:205], v145 offset:36864
	ds_read_b64 v[206:207], v150 offset:36864
	ds_read_b64 v[208:209], v154 offset:36864
	ds_read_b64 v[210:211], v151 offset:36864
	ds_read_b64 v[212:213], v155 offset:36864
	ds_read_b64 v[214:215], v152 offset:36864
	ds_read_b64 v[216:217], v156 offset:36864
	ds_read_b64 v[218:219], v153 offset:36864
	ds_read_b64 v[220:221], v157 offset:36864
	s_waitcnt lgkmcnt(12)
	v_mfma_f32_16x16x32_bf16 v[116:119], v[158:161], v[20:23], 0
	v_mfma_f32_16x16x32_bf16 v[116:119], v[162:165], v[24:27], v[116:119]
	v_mfma_f32_16x16x32_bf16 v[116:119], v[166:169], v[28:31], v[116:119]
	v_mfma_f32_16x16x32_bf16 v[116:119], v[170:173], v[32:35], v[116:119]
	v_mfma_f32_16x16x32_bf16 v[120:123], v[174:177], v[36:39], 0
	v_mfma_f32_16x16x32_bf16 v[120:123], v[178:181], v[40:43], v[120:123]
	v_mfma_f32_16x16x32_bf16 v[120:123], v[182:185], v[44:47], v[120:123]
	v_mfma_f32_16x16x32_bf16 v[120:123], v[186:189], v[48:51], v[120:123]
	v_fma_f32 v80, v130, v126, v134
	v_fma_f32 v81, v131, v126, v135
	v_fma_f32 v82, v132, v126, v136
	v_fma_f32 v83, v133, v126, v137
	ds_read_b128 v[158:161], v142 offset:40960
	ds_read_b128 v[162:165], v143 offset:40960
	ds_read_b128 v[166:169], v144 offset:40960
	ds_read_b128 v[170:173], v145 offset:40960
	ds_read_b64 v[174:175], v150 offset:40960
	ds_read_b64 v[176:177], v154 offset:40960
	ds_read_b64 v[178:179], v151 offset:40960
	ds_read_b64 v[180:181], v155 offset:40960
	ds_read_b64 v[182:183], v152 offset:40960
	ds_read_b64 v[184:185], v156 offset:40960
	ds_read_b64 v[186:187], v153 offset:40960
	ds_read_b64 v[188:189], v157 offset:40960
	s_waitcnt lgkmcnt(12)
	v_mfma_f32_16x16x32_bf16 v[130:133], v[190:193], v[20:23], 0
	v_mfma_f32_16x16x32_bf16 v[130:133], v[194:197], v[24:27], v[130:133]
	v_mfma_f32_16x16x32_bf16 v[130:133], v[198:201], v[28:31], v[130:133]
	v_mfma_f32_16x16x32_bf16 v[130:133], v[202:205], v[32:35], v[130:133]
	v_mfma_f32_16x16x32_bf16 v[134:137], v[206:209], v[36:39], 0
	v_mfma_f32_16x16x32_bf16 v[134:137], v[210:213], v[40:43], v[134:137]
	v_mfma_f32_16x16x32_bf16 v[134:137], v[214:217], v[44:47], v[134:137]
	v_mfma_f32_16x16x32_bf16 v[134:137], v[218:221], v[48:51], v[134:137]
	v_fma_f32 v84, v116, v126, v120
	v_fma_f32 v85, v117, v126, v121
	v_fma_f32 v86, v118, v126, v122
	v_fma_f32 v87, v119, v126, v123
	ds_read_b128 v[190:193], v142 offset:45056
	ds_read_b128 v[194:197], v143 offset:45056
	ds_read_b128 v[198:201], v144 offset:45056
	ds_read_b128 v[202:205], v145 offset:45056
	ds_read_b64 v[206:207], v150 offset:45056
	ds_read_b64 v[208:209], v154 offset:45056
	ds_read_b64 v[210:211], v151 offset:45056
	ds_read_b64 v[212:213], v155 offset:45056
	ds_read_b64 v[214:215], v152 offset:45056
	ds_read_b64 v[216:217], v156 offset:45056
	ds_read_b64 v[218:219], v153 offset:45056
	ds_read_b64 v[220:221], v157 offset:45056
	s_waitcnt lgkmcnt(12)
	v_mfma_f32_16x16x32_bf16 v[116:119], v[158:161], v[20:23], 0
	v_mfma_f32_16x16x32_bf16 v[116:119], v[162:165], v[24:27], v[116:119]
	v_mfma_f32_16x16x32_bf16 v[116:119], v[166:169], v[28:31], v[116:119]
	v_mfma_f32_16x16x32_bf16 v[116:119], v[170:173], v[32:35], v[116:119]
	v_mfma_f32_16x16x32_bf16 v[120:123], v[174:177], v[36:39], 0
	v_mfma_f32_16x16x32_bf16 v[120:123], v[178:181], v[40:43], v[120:123]
	v_mfma_f32_16x16x32_bf16 v[120:123], v[182:185], v[44:47], v[120:123]
	v_mfma_f32_16x16x32_bf16 v[120:123], v[186:189], v[48:51], v[120:123]
	v_fma_f32 v88, v130, v126, v134
	v_fma_f32 v89, v131, v126, v135
	v_fma_f32 v90, v132, v126, v136
	v_fma_f32 v91, v133, v126, v137
	ds_read_b128 v[158:161], v142 offset:49152
	ds_read_b128 v[162:165], v143 offset:49152
	ds_read_b128 v[166:169], v144 offset:49152
	ds_read_b128 v[170:173], v145 offset:49152
	ds_read_b64 v[174:175], v150 offset:49152
	ds_read_b64 v[176:177], v154 offset:49152
	ds_read_b64 v[178:179], v151 offset:49152
	ds_read_b64 v[180:181], v155 offset:49152
	ds_read_b64 v[182:183], v152 offset:49152
	ds_read_b64 v[184:185], v156 offset:49152
	ds_read_b64 v[186:187], v153 offset:49152
	ds_read_b64 v[188:189], v157 offset:49152
	s_waitcnt lgkmcnt(12)
	v_mfma_f32_16x16x32_bf16 v[130:133], v[190:193], v[20:23], 0
	v_mfma_f32_16x16x32_bf16 v[130:133], v[194:197], v[24:27], v[130:133]
	v_mfma_f32_16x16x32_bf16 v[130:133], v[198:201], v[28:31], v[130:133]
	v_mfma_f32_16x16x32_bf16 v[130:133], v[202:205], v[32:35], v[130:133]
	v_mfma_f32_16x16x32_bf16 v[134:137], v[206:209], v[36:39], 0
	v_mfma_f32_16x16x32_bf16 v[134:137], v[210:213], v[40:43], v[134:137]
	v_mfma_f32_16x16x32_bf16 v[134:137], v[214:217], v[44:47], v[134:137]
	v_mfma_f32_16x16x32_bf16 v[134:137], v[218:221], v[48:51], v[134:137]
	v_fma_f32 v92, v116, v126, v120
	v_fma_f32 v93, v117, v126, v121
	v_fma_f32 v94, v118, v126, v122
	v_fma_f32 v95, v119, v126, v123
	ds_read_b128 v[190:193], v142 offset:53248
	ds_read_b128 v[194:197], v143 offset:53248
	ds_read_b128 v[198:201], v144 offset:53248
	ds_read_b128 v[202:205], v145 offset:53248
	ds_read_b64 v[206:207], v150 offset:53248
	ds_read_b64 v[208:209], v154 offset:53248
	ds_read_b64 v[210:211], v151 offset:53248
	ds_read_b64 v[212:213], v155 offset:53248
	ds_read_b64 v[214:215], v152 offset:53248
	ds_read_b64 v[216:217], v156 offset:53248
	ds_read_b64 v[218:219], v153 offset:53248
	ds_read_b64 v[220:221], v157 offset:53248
	s_waitcnt lgkmcnt(12)
	v_mfma_f32_16x16x32_bf16 v[116:119], v[158:161], v[20:23], 0
	v_mfma_f32_16x16x32_bf16 v[116:119], v[162:165], v[24:27], v[116:119]
	v_mfma_f32_16x16x32_bf16 v[116:119], v[166:169], v[28:31], v[116:119]
	v_mfma_f32_16x16x32_bf16 v[116:119], v[170:173], v[32:35], v[116:119]
	v_mfma_f32_16x16x32_bf16 v[120:123], v[174:177], v[36:39], 0
	v_mfma_f32_16x16x32_bf16 v[120:123], v[178:181], v[40:43], v[120:123]
	v_mfma_f32_16x16x32_bf16 v[120:123], v[182:185], v[44:47], v[120:123]
	v_mfma_f32_16x16x32_bf16 v[120:123], v[186:189], v[48:51], v[120:123]
	v_fma_f32 v96, v130, v126, v134
	v_fma_f32 v97, v131, v126, v135
	v_fma_f32 v98, v132, v126, v136
	v_fma_f32 v99, v133, v126, v137
	ds_read_b128 v[158:161], v142 offset:57344
	ds_read_b128 v[162:165], v143 offset:57344
	ds_read_b128 v[166:169], v144 offset:57344
	ds_read_b128 v[170:173], v145 offset:57344
	ds_read_b64 v[174:175], v150 offset:57344
	ds_read_b64 v[176:177], v154 offset:57344
	ds_read_b64 v[178:179], v151 offset:57344
	ds_read_b64 v[180:181], v155 offset:57344
	ds_read_b64 v[182:183], v152 offset:57344
	ds_read_b64 v[184:185], v156 offset:57344
	ds_read_b64 v[186:187], v153 offset:57344
	ds_read_b64 v[188:189], v157 offset:57344
	s_waitcnt lgkmcnt(12)
	v_mfma_f32_16x16x32_bf16 v[130:133], v[190:193], v[20:23], 0
	v_mfma_f32_16x16x32_bf16 v[130:133], v[194:197], v[24:27], v[130:133]
	v_mfma_f32_16x16x32_bf16 v[130:133], v[198:201], v[28:31], v[130:133]
	v_mfma_f32_16x16x32_bf16 v[130:133], v[202:205], v[32:35], v[130:133]
	v_mfma_f32_16x16x32_bf16 v[134:137], v[206:209], v[36:39], 0
	v_mfma_f32_16x16x32_bf16 v[134:137], v[210:213], v[40:43], v[134:137]
	v_mfma_f32_16x16x32_bf16 v[134:137], v[214:217], v[44:47], v[134:137]
	v_mfma_f32_16x16x32_bf16 v[134:137], v[218:221], v[48:51], v[134:137]
	v_fma_f32 v100, v116, v126, v120
	v_fma_f32 v101, v117, v126, v121
	v_fma_f32 v102, v118, v126, v122
	v_fma_f32 v103, v119, v126, v123
	ds_read_b128 v[190:193], v142 offset:61440
	ds_read_b128 v[194:197], v143 offset:61440
	ds_read_b128 v[198:201], v144 offset:61440
	ds_read_b128 v[202:205], v145 offset:61440
	ds_read_b64 v[206:207], v150 offset:61440
	ds_read_b64 v[208:209], v154 offset:61440
	ds_read_b64 v[210:211], v151 offset:61440
	ds_read_b64 v[212:213], v155 offset:61440
	ds_read_b64 v[214:215], v152 offset:61440
	ds_read_b64 v[216:217], v156 offset:61440
	ds_read_b64 v[218:219], v153 offset:61440
	ds_read_b64 v[220:221], v157 offset:61440
	s_waitcnt lgkmcnt(12)
	v_mfma_f32_16x16x32_bf16 v[116:119], v[158:161], v[20:23], 0
	v_mfma_f32_16x16x32_bf16 v[116:119], v[162:165], v[24:27], v[116:119]
	v_mfma_f32_16x16x32_bf16 v[116:119], v[166:169], v[28:31], v[116:119]
	v_mfma_f32_16x16x32_bf16 v[116:119], v[170:173], v[32:35], v[116:119]
	v_mfma_f32_16x16x32_bf16 v[120:123], v[174:177], v[36:39], 0
	v_mfma_f32_16x16x32_bf16 v[120:123], v[178:181], v[40:43], v[120:123]
	v_mfma_f32_16x16x32_bf16 v[120:123], v[182:185], v[44:47], v[120:123]
	v_mfma_f32_16x16x32_bf16 v[120:123], v[186:189], v[48:51], v[120:123]
	v_fma_f32 v104, v130, v126, v134
	v_fma_f32 v105, v131, v126, v135
	v_fma_f32 v106, v132, v126, v136
	v_fma_f32 v107, v133, v126, v137
	s_waitcnt lgkmcnt(0)
	v_mfma_f32_16x16x32_bf16 v[130:133], v[190:193], v[20:23], 0
	v_mfma_f32_16x16x32_bf16 v[130:133], v[194:197], v[24:27], v[130:133]
	v_mfma_f32_16x16x32_bf16 v[130:133], v[198:201], v[28:31], v[130:133]
	v_mfma_f32_16x16x32_bf16 v[130:133], v[202:205], v[32:35], v[130:133]
	v_mfma_f32_16x16x32_bf16 v[134:137], v[206:209], v[36:39], 0
	v_mfma_f32_16x16x32_bf16 v[134:137], v[210:213], v[40:43], v[134:137]
	v_mfma_f32_16x16x32_bf16 v[134:137], v[214:217], v[44:47], v[134:137]
	v_mfma_f32_16x16x32_bf16 v[134:137], v[218:221], v[48:51], v[134:137]
	v_fma_f32 v108, v116, v126, v120
	v_fma_f32 v109, v117, v126, v121
	v_fma_f32 v110, v118, v126, v122
	v_fma_f32 v111, v119, v126, v123
	s_barrier
	s_nop 7
	v_fma_f32 v112, v130, v126, v134
	v_fma_f32 v113, v131, v126, v135
	v_fma_f32 v114, v132, v126, v136
	v_fma_f32 v115, v133, v126, v137
	v_mul_f32_e32 v4, v52, v52
	v_mul_f32_e32 v5, v53, v53
	v_mul_f32_e32 v6, v54, v54
	v_mul_f32_e32 v7, v55, v55
	v_fmac_f32_e32 v4, v56, v56
	v_fmac_f32_e32 v5, v57, v57
	v_fmac_f32_e32 v6, v58, v58
	v_fmac_f32_e32 v7, v59, v59
	v_fmac_f32_e32 v4, v60, v60
	v_fmac_f32_e32 v5, v61, v61
	v_fmac_f32_e32 v6, v62, v62
	v_fmac_f32_e32 v7, v63, v63
	v_fmac_f32_e32 v4, v64, v64
	v_fmac_f32_e32 v5, v65, v65
	v_fmac_f32_e32 v6, v66, v66
	v_fmac_f32_e32 v7, v67, v67
	v_fmac_f32_e32 v4, v68, v68
	v_fmac_f32_e32 v5, v69, v69
	v_fmac_f32_e32 v6, v70, v70
	v_fmac_f32_e32 v7, v71, v71
	v_fmac_f32_e32 v4, v72, v72
	v_fmac_f32_e32 v5, v73, v73
	v_fmac_f32_e32 v6, v74, v74
	v_fmac_f32_e32 v7, v75, v75
	v_fmac_f32_e32 v4, v76, v76
	v_fmac_f32_e32 v5, v77, v77
	v_fmac_f32_e32 v6, v78, v78
	v_fmac_f32_e32 v7, v79, v79
	v_fmac_f32_e32 v4, v80, v80
	v_fmac_f32_e32 v5, v81, v81
	v_fmac_f32_e32 v6, v82, v82
	v_fmac_f32_e32 v7, v83, v83
	v_fmac_f32_e32 v4, v84, v84
	v_fmac_f32_e32 v5, v85, v85
	v_fmac_f32_e32 v6, v86, v86
	v_fmac_f32_e32 v7, v87, v87
	v_fmac_f32_e32 v4, v88, v88
	v_fmac_f32_e32 v5, v89, v89
	v_fmac_f32_e32 v6, v90, v90
	v_fmac_f32_e32 v7, v91, v91
	v_fmac_f32_e32 v4, v92, v92
	v_fmac_f32_e32 v5, v93, v93
	v_fmac_f32_e32 v6, v94, v94
	v_fmac_f32_e32 v7, v95, v95
	v_fmac_f32_e32 v4, v96, v96
	v_fmac_f32_e32 v5, v97, v97
	v_fmac_f32_e32 v6, v98, v98
	v_fmac_f32_e32 v7, v99, v99
	v_fmac_f32_e32 v4, v100, v100
	v_fmac_f32_e32 v5, v101, v101
	v_fmac_f32_e32 v6, v102, v102
	v_fmac_f32_e32 v7, v103, v103
	v_fmac_f32_e32 v4, v104, v104
	v_fmac_f32_e32 v5, v105, v105
	v_fmac_f32_e32 v6, v106, v106
	v_fmac_f32_e32 v7, v107, v107
	v_fmac_f32_e32 v4, v108, v108
	v_fmac_f32_e32 v5, v109, v109
	v_fmac_f32_e32 v6, v110, v110
	v_fmac_f32_e32 v7, v111, v111
	v_fmac_f32_e32 v4, v112, v112
	v_fmac_f32_e32 v5, v113, v113
	v_fmac_f32_e32 v6, v114, v114
	v_fmac_f32_e32 v7, v115, v115
	v_add_f32_e32 v4, v4, v5
	v_add_f32_e32 v6, v6, v7
	v_add_f32_e32 v4, v4, v6
	s_nop 0
	ds_bpermute_b32 v5, v127, v4
	s_waitcnt lgkmcnt(0)
	v_add_f32_e32 v4, v4, v5
	s_nop 0
	ds_bpermute_b32 v5, v11, v4
	s_waitcnt lgkmcnt(0)
	v_add_f32_e32 v4, v4, v5
	v_mul_f32_e32 v4, 0x3b800000, v4
	v_add_f32_e32 v4, 0x358637bd, v4
	v_rsq_f32_e32 v10, v4
	s_waitcnt vmcnt(0)
	v_lshlrev_b32_e32 v4, 16, v222
	v_and_b32_e32 v5, 0xffff0000, v222
	v_lshlrev_b32_e32 v6, 16, v223
	v_and_b32_e32 v7, 0xffff0000, v223
	v_mul_f32_e32 v52, v52, v10
	v_mul_f32_e32 v53, v53, v10
	v_mul_f32_e32 v54, v54, v10
	v_mul_f32_e32 v55, v55, v10
	v_mul_f32_e32 v52, v52, v4
	v_mul_f32_e32 v53, v53, v5
	v_mul_f32_e32 v54, v54, v6
	v_mul_f32_e32 v55, v55, v7
	v_cvt_pk_bf16_f32 v52, v52, v53
	v_cvt_pk_bf16_f32 v53, v54, v55
	global_store_dwordx2 v124, v[52:53], s[74:75] offset:0
	v_lshlrev_b32_e32 v4, 16, v224
	v_and_b32_e32 v5, 0xffff0000, v224
	v_lshlrev_b32_e32 v6, 16, v225
	v_and_b32_e32 v7, 0xffff0000, v225
	v_mul_f32_e32 v56, v56, v10
	v_mul_f32_e32 v57, v57, v10
	v_mul_f32_e32 v58, v58, v10
	v_mul_f32_e32 v59, v59, v10
	v_mul_f32_e32 v56, v56, v4
	v_mul_f32_e32 v57, v57, v5
	v_mul_f32_e32 v58, v58, v6
	v_mul_f32_e32 v59, v59, v7
	v_cvt_pk_bf16_f32 v56, v56, v57
	v_cvt_pk_bf16_f32 v57, v58, v59
	global_store_dwordx2 v124, v[56:57], s[74:75] offset:32
	v_lshlrev_b32_e32 v4, 16, v226
	v_and_b32_e32 v5, 0xffff0000, v226
	v_lshlrev_b32_e32 v6, 16, v227
	v_and_b32_e32 v7, 0xffff0000, v227
	v_mul_f32_e32 v60, v60, v10
	v_mul_f32_e32 v61, v61, v10
	v_mul_f32_e32 v62, v62, v10
	v_mul_f32_e32 v63, v63, v10
	v_mul_f32_e32 v60, v60, v4
	v_mul_f32_e32 v61, v61, v5
	v_mul_f32_e32 v62, v62, v6
	v_mul_f32_e32 v63, v63, v7
	v_cvt_pk_bf16_f32 v60, v60, v61
	v_cvt_pk_bf16_f32 v61, v62, v63
	global_store_dwordx2 v124, v[60:61], s[74:75] offset:64
	v_lshlrev_b32_e32 v4, 16, v228
	v_and_b32_e32 v5, 0xffff0000, v228
	v_lshlrev_b32_e32 v6, 16, v229
	v_and_b32_e32 v7, 0xffff0000, v229
	v_mul_f32_e32 v64, v64, v10
	v_mul_f32_e32 v65, v65, v10
	v_mul_f32_e32 v66, v66, v10
	v_mul_f32_e32 v67, v67, v10
	v_mul_f32_e32 v64, v64, v4
	v_mul_f32_e32 v65, v65, v5
	v_mul_f32_e32 v66, v66, v6
	v_mul_f32_e32 v67, v67, v7
	v_cvt_pk_bf16_f32 v64, v64, v65
	v_cvt_pk_bf16_f32 v65, v66, v67
	global_store_dwordx2 v124, v[64:65], s[74:75] offset:96
	v_lshlrev_b32_e32 v4, 16, v230
	v_and_b32_e32 v5, 0xffff0000, v230
	v_lshlrev_b32_e32 v6, 16, v231
	v_and_b32_e32 v7, 0xffff0000, v231
	v_mul_f32_e32 v68, v68, v10
	v_mul_f32_e32 v69, v69, v10
	v_mul_f32_e32 v70, v70, v10
	v_mul_f32_e32 v71, v71, v10
	v_mul_f32_e32 v68, v68, v4
	v_mul_f32_e32 v69, v69, v5
	v_mul_f32_e32 v70, v70, v6
	v_mul_f32_e32 v71, v71, v7
	v_cvt_pk_bf16_f32 v68, v68, v69
	v_cvt_pk_bf16_f32 v69, v70, v71
	global_store_dwordx2 v124, v[68:69], s[74:75] offset:128
	v_lshlrev_b32_e32 v4, 16, v232
	v_and_b32_e32 v5, 0xffff0000, v232
	v_lshlrev_b32_e32 v6, 16, v233
	v_and_b32_e32 v7, 0xffff0000, v233
	v_mul_f32_e32 v72, v72, v10
	v_mul_f32_e32 v73, v73, v10
	v_mul_f32_e32 v74, v74, v10
	v_mul_f32_e32 v75, v75, v10
	v_mul_f32_e32 v72, v72, v4
	v_mul_f32_e32 v73, v73, v5
	v_mul_f32_e32 v74, v74, v6
	v_mul_f32_e32 v75, v75, v7
	v_cvt_pk_bf16_f32 v72, v72, v73
	v_cvt_pk_bf16_f32 v73, v74, v75
	global_store_dwordx2 v124, v[72:73], s[74:75] offset:160
	v_lshlrev_b32_e32 v4, 16, v236
	v_and_b32_e32 v5, 0xffff0000, v236
	v_lshlrev_b32_e32 v6, 16, v237
	v_and_b32_e32 v7, 0xffff0000, v237
	v_mul_f32_e32 v76, v76, v10
	v_mul_f32_e32 v77, v77, v10
	v_mul_f32_e32 v78, v78, v10
	v_mul_f32_e32 v79, v79, v10
	v_mul_f32_e32 v76, v76, v4
	v_mul_f32_e32 v77, v77, v5
	v_mul_f32_e32 v78, v78, v6
	v_mul_f32_e32 v79, v79, v7
	v_cvt_pk_bf16_f32 v76, v76, v77
	v_cvt_pk_bf16_f32 v77, v78, v79
	global_store_dwordx2 v124, v[76:77], s[74:75] offset:192
	v_lshlrev_b32_e32 v4, 16, v238
	v_and_b32_e32 v5, 0xffff0000, v238
	v_lshlrev_b32_e32 v6, 16, v239
	v_and_b32_e32 v7, 0xffff0000, v239
	v_mul_f32_e32 v80, v80, v10
	v_mul_f32_e32 v81, v81, v10
	v_mul_f32_e32 v82, v82, v10
	v_mul_f32_e32 v83, v83, v10
	v_mul_f32_e32 v80, v80, v4
	v_mul_f32_e32 v81, v81, v5
	v_mul_f32_e32 v82, v82, v6
	v_mul_f32_e32 v83, v83, v7
	v_cvt_pk_bf16_f32 v80, v80, v81
	v_cvt_pk_bf16_f32 v81, v82, v83
	global_store_dwordx2 v124, v[80:81], s[74:75] offset:224
	v_lshlrev_b32_e32 v4, 16, v240
	v_and_b32_e32 v5, 0xffff0000, v240
	v_lshlrev_b32_e32 v6, 16, v241
	v_and_b32_e32 v7, 0xffff0000, v241
	v_mul_f32_e32 v84, v84, v10
	v_mul_f32_e32 v85, v85, v10
	v_mul_f32_e32 v86, v86, v10
	v_mul_f32_e32 v87, v87, v10
	v_mul_f32_e32 v84, v84, v4
	v_mul_f32_e32 v85, v85, v5
	v_mul_f32_e32 v86, v86, v6
	v_mul_f32_e32 v87, v87, v7
	v_cvt_pk_bf16_f32 v84, v84, v85
	v_cvt_pk_bf16_f32 v85, v86, v87
	global_store_dwordx2 v124, v[84:85], s[74:75] offset:256
	v_lshlrev_b32_e32 v4, 16, v242
	v_and_b32_e32 v5, 0xffff0000, v242
	v_lshlrev_b32_e32 v6, 16, v243
	v_and_b32_e32 v7, 0xffff0000, v243
	v_mul_f32_e32 v88, v88, v10
	v_mul_f32_e32 v89, v89, v10
	v_mul_f32_e32 v90, v90, v10
	v_mul_f32_e32 v91, v91, v10
	v_mul_f32_e32 v88, v88, v4
	v_mul_f32_e32 v89, v89, v5
	v_mul_f32_e32 v90, v90, v6
	v_mul_f32_e32 v91, v91, v7
	v_cvt_pk_bf16_f32 v88, v88, v89
	v_cvt_pk_bf16_f32 v89, v90, v91
	global_store_dwordx2 v124, v[88:89], s[74:75] offset:288
	v_lshlrev_b32_e32 v4, 16, v244
	v_and_b32_e32 v5, 0xffff0000, v244
	v_lshlrev_b32_e32 v6, 16, v245
	v_and_b32_e32 v7, 0xffff0000, v245
	v_mul_f32_e32 v92, v92, v10
	v_mul_f32_e32 v93, v93, v10
	v_mul_f32_e32 v94, v94, v10
	v_mul_f32_e32 v95, v95, v10
	v_mul_f32_e32 v92, v92, v4
	v_mul_f32_e32 v93, v93, v5
	v_mul_f32_e32 v94, v94, v6
	v_mul_f32_e32 v95, v95, v7
	v_cvt_pk_bf16_f32 v92, v92, v93
	v_cvt_pk_bf16_f32 v93, v94, v95
	global_store_dwordx2 v124, v[92:93], s[74:75] offset:320
	v_lshlrev_b32_e32 v4, 16, v246
	v_and_b32_e32 v5, 0xffff0000, v246
	v_lshlrev_b32_e32 v6, 16, v247
	v_and_b32_e32 v7, 0xffff0000, v247
	v_mul_f32_e32 v96, v96, v10
	v_mul_f32_e32 v97, v97, v10
	v_mul_f32_e32 v98, v98, v10
	v_mul_f32_e32 v99, v99, v10
	v_mul_f32_e32 v96, v96, v4
	v_mul_f32_e32 v97, v97, v5
	v_mul_f32_e32 v98, v98, v6
	v_mul_f32_e32 v99, v99, v7
	v_cvt_pk_bf16_f32 v96, v96, v97
	v_cvt_pk_bf16_f32 v97, v98, v99
	global_store_dwordx2 v124, v[96:97], s[74:75] offset:352
	v_lshlrev_b32_e32 v4, 16, v248
	v_and_b32_e32 v5, 0xffff0000, v248
	v_lshlrev_b32_e32 v6, 16, v249
	v_and_b32_e32 v7, 0xffff0000, v249
	v_mul_f32_e32 v100, v100, v10
	v_mul_f32_e32 v101, v101, v10
	v_mul_f32_e32 v102, v102, v10
	v_mul_f32_e32 v103, v103, v10
	v_mul_f32_e32 v100, v100, v4
	v_mul_f32_e32 v101, v101, v5
	v_mul_f32_e32 v102, v102, v6
	v_mul_f32_e32 v103, v103, v7
	v_cvt_pk_bf16_f32 v100, v100, v101
	v_cvt_pk_bf16_f32 v101, v102, v103
	global_store_dwordx2 v124, v[100:101], s[74:75] offset:384
	v_lshlrev_b32_e32 v4, 16, v250
	v_and_b32_e32 v5, 0xffff0000, v250
	v_lshlrev_b32_e32 v6, 16, v251
	v_and_b32_e32 v7, 0xffff0000, v251
	v_mul_f32_e32 v104, v104, v10
	v_mul_f32_e32 v105, v105, v10
	v_mul_f32_e32 v106, v106, v10
	v_mul_f32_e32 v107, v107, v10
	v_mul_f32_e32 v104, v104, v4
	v_mul_f32_e32 v105, v105, v5
	v_mul_f32_e32 v106, v106, v6
	v_mul_f32_e32 v107, v107, v7
	v_cvt_pk_bf16_f32 v104, v104, v105
	v_cvt_pk_bf16_f32 v105, v106, v107
	global_store_dwordx2 v124, v[104:105], s[74:75] offset:416
	v_lshlrev_b32_e32 v4, 16, v252
	v_and_b32_e32 v5, 0xffff0000, v252
	v_lshlrev_b32_e32 v6, 16, v253
	v_and_b32_e32 v7, 0xffff0000, v253
	v_mul_f32_e32 v108, v108, v10
	v_mul_f32_e32 v109, v109, v10
	v_mul_f32_e32 v110, v110, v10
	v_mul_f32_e32 v111, v111, v10
	v_mul_f32_e32 v108, v108, v4
	v_mul_f32_e32 v109, v109, v5
	v_mul_f32_e32 v110, v110, v6
	v_mul_f32_e32 v111, v111, v7
	v_cvt_pk_bf16_f32 v108, v108, v109
	v_cvt_pk_bf16_f32 v109, v110, v111
	global_store_dwordx2 v124, v[108:109], s[74:75] offset:448
	v_lshlrev_b32_e32 v4, 16, v254
	v_and_b32_e32 v5, 0xffff0000, v254
	v_lshlrev_b32_e32 v6, 16, v255
	v_and_b32_e32 v7, 0xffff0000, v255
	v_mul_f32_e32 v112, v112, v10
	v_mul_f32_e32 v113, v113, v10
	v_mul_f32_e32 v114, v114, v10
	v_mul_f32_e32 v115, v115, v10
	v_mul_f32_e32 v112, v112, v4
	v_mul_f32_e32 v113, v113, v5
	v_mul_f32_e32 v114, v114, v6
	v_mul_f32_e32 v115, v115, v7
	v_cvt_pk_bf16_f32 v112, v112, v113
	v_cvt_pk_bf16_f32 v113, v114, v115
	global_store_dwordx2 v124, v[112:113], s[74:75] offset:480
	s_add_u32 s64, s64, s94
	s_cmp_lt_u32 s64, 0x200
	s_cbranch_scc1 .LR3_unit

.LBB0_1413:
	s_abs_i32 s4, s94
	v_cvt_f32_u32_e32 v0, s4
	s_sub_i32 s5, 0, s4
	v_rcp_iflag_f32_e32 v0, v0
	s_nop 0
	v_mul_f32_e32 v0, 0x4f7ffffe, v0
	v_cvt_u32_f32_e32 v0, v0
	s_nop 0
	v_readfirstlane_b32 s6, v0
	s_mul_i32 s5, s5, s6
	s_mul_hi_u32 s5, s6, s5
	s_add_i32 s6, s6, s5
	s_mul_hi_u32 s5, s6, 0x120
	s_mul_i32 s5, s5, s4
	s_sub_i32 s5, 0x120, s5
	s_sub_i32 s6, s5, s4
	s_cmp_ge_u32 s5, s4
	s_cselect_b32 s5, s6, s5
	s_sub_i32 s6, s5, s4
	s_cmp_ge_u32 s5, s4
	s_cselect_b32 s6, s6, s5
	s_cmp_lg_u32 s6, 0
	s_cbranch_scc0 .LBB0_1486
	s_cmp_lt_i32 s34, s6
	s_cbranch_scc1 .LBB0_1485
	v_lshrrev_b32_e32 v0, 6, v128
	s_sub_i32 s4, s34, s6
	v_lshl_add_u32 v5, s4, 3, v0
	s_movk_i32 s4, 0x1600
	v_cmp_gt_i32_e32 vcc, s4, v5
	s_and_saveexec_b64 s[4:5], vcc
	s_cbranch_execz .LBB0_1484
	s_sub_i32 s6, s94, s6
	s_lshl_b32 s33, s6, 3
	s_movk_i32 s6, 0x2200
	v_mad_u32_u24 v1, v0, s6, 0
	s_add_u32 s6, s50, 0x8404000
	s_addc_u32 s7, s51, 0
	s_add_u32 s8, s50, 0x7c04000
	s_addc_u32 s9, s51, 0
	s_add_u32 s12, s50, 0x4204000
	s_addc_u32 s13, s51, 0
	s_add_u32 s14, s50, 0x2c04000
	s_addc_u32 s15, s51, 0
	s_add_u32 s16, s50, 0x4000
	s_waitcnt vmcnt(0)
	v_lshlrev_b32_e32 v2, 3, v128
	s_addc_u32 s17, s51, 0
	v_bfe_u32 v9, v128, 3, 3
	v_and_b32_e32 v2, 56, v2
	s_add_u32 s18, s50, 0xb004000
	v_bfe_u32 v4, v128, 5, 1
	v_and_b32_e32 v0, 31, v128
	v_mul_u32_u24_e32 v3, 0x84, v2
	v_lshlrev_b32_e32 v6, 2, v9
	s_addc_u32 s19, s51, 0
	v_mov_b32_e32 v7, 0
	v_lshl_add_u32 v8, v0, 2, v1
	s_movk_i32 s35, 0x84
	v_add3_u32 v20, v1, v3, v6
	v_or_b32_e32 v21, 8, v9
	v_or_b32_e32 v22, 16, v9
	v_or_b32_e32 v23, 24, v9
	v_mov_b32_e32 v1, v4
	s_mov_b64 s[20:21], 0
	s_movk_i32 s54, 0xf7ff
	s_movk_i32 s55, 0xfc00
	v_lshlrev_b32_e32 v6, 2, v0
	v_lshlrev_b32_e32 v10, 1, v2
	s_movk_i32 s56, 0x15ff
.LBB0_1417:
	s_mov_b64 s[22:23], 0
	s_mov_b32 s52, 9
	v_mov_b32_e32 v0, v5
	s_branch .LBB0_1420
.LBB0_1418:
	v_add_u32_e32 v0, s28, v11
	s_add_i32 s28, s52, 1
	s_xor_b64 s[26:27], exec, -1
.LBB0_1419:
	s_or_b64 exec, exec, s[24:25]
	s_and_b64 s[24:25], exec, s[26:27]
	s_or_b64 s[22:23], s[24:25], s[22:23]
	v_mov_b32_e32 v16, s52
	s_mov_b32 s52, s28
	s_andn2_b64 exec, exec, s[22:23]
	s_cbranch_execz .LBB0_1439
.LBB0_1420:
	v_mov_b32_e32 v11, v0
	s_cmp_lt_i32 s52, 3
	s_movk_i32 s26, 0x1600
	s_cbranch_scc1 .LBB0_1426
	s_mov_b64 s[28:29], -1
	s_mov_b64 s[24:25], 0
	s_cmp_lt_i32 s52, 7
	s_mov_b64 s[26:27], 0
	s_cbranch_scc0 .LBB0_1432
	s_andn2_b64 vcc, exec, s[28:29]
	s_cbranch_vccz .LBB0_1433
.LBB0_1423:
	s_andn2_b64 vcc, exec, s[26:27]
	s_movk_i32 s26, 0x1600
	s_cbranch_vccz .LBB0_1434
.LBB0_1424:
	s_andn2_b64 vcc, exec, s[24:25]
	s_cbranch_vccnz .LBB0_1426
.LBB0_1425:
	s_movk_i32 s26, 0x2e00
.LBB0_1426:
	v_cmp_le_i32_e32 vcc, s26, v11
	s_mov_b64 s[26:27], -1
	v_readfirstlane_b32 s28, v0
	s_and_saveexec_b64 s[24:25], vcc
	s_cbranch_execz .LBB0_1419
	s_cmp_lt_i32 s52, 3
	s_movk_i32 s28, 0xea00
	s_cbranch_scc1 .LBB0_1418
	s_mov_b64 s[30:31], -1
	s_mov_b64 s[26:27], 0
	s_cmp_lt_i32 s52, 7
	s_mov_b64 s[28:29], 0
	s_cbranch_scc0 .LBB0_1435
	s_andn2_b64 vcc, exec, s[30:31]
	s_cbranch_vccz .LBB0_1436
.LBB0_1430:
	s_andn2_b64 vcc, exec, s[28:29]
	s_movk_i32 s28, 0xea00
	s_cbranch_vccz .LBB0_1437
.LBB0_1431:
	s_andn2_b64 vcc, exec, s[26:27]
	s_cbranch_vccnz .LBB0_1418
	s_branch .LBB0_1438
.LBB0_1432:
	s_cmp_gt_i32 s52, 9
	s_cselect_b64 s[26:27], -1, 0
	s_cbranch_execnz .LBB0_1423
.LBB0_1433:
	s_cmp_lg_u32 s52, 3
	s_mov_b64 s[24:25], -1
	s_cselect_b64 s[26:27], -1, 0
	s_andn2_b64 vcc, exec, s[26:27]
	s_movk_i32 s26, 0x1600
	s_cbranch_vccnz .LBB0_1424
.LBB0_1434:
	s_movk_i32 s26, 0x800
	s_cbranch_execz .LBB0_1425
	s_branch .LBB0_1426
.LBB0_1435:
	s_cmp_gt_i32 s52, 9
	s_cselect_b64 s[28:29], -1, 0
	s_cbranch_execnz .LBB0_1430
.LBB0_1436:
	s_cmp_lg_u32 s52, 3
	s_mov_b64 s[26:27], -1
	s_cselect_b64 s[28:29], -1, 0
	s_andn2_b64 vcc, exec, s[28:29]
	s_movk_i32 s28, 0xea00
	s_cbranch_vccnz .LBB0_1431
.LBB0_1437:
	s_movk_i32 s28, 0xf800
	s_cbranch_execnz .LBB0_1418
.LBB0_1438:
	s_movk_i32 s28, 0xd200
	s_branch .LBB0_1418
.LBB0_1439:
	s_or_b64 exec, exec, s[22:23]
	v_cmp_lt_i32_e32 vcc, 3, v16
	s_and_saveexec_b64 s[24:25], vcc
	s_xor_b64 s[24:25], exec, s[24:25]
	s_cbranch_execz .LBB0_1461
	v_cmp_lt_i32_e32 vcc, 5, v16
	s_and_saveexec_b64 s[26:27], vcc
	s_xor_b64 s[26:27], exec, s[26:27]
	s_cbranch_execz .LBB0_1454
	v_readlane_b32 s60, v235, 1
	v_readlane_b32 s74, v235, 15
	v_readlane_b32 s75, v235, 16
	v_cmp_lt_i32_e32 vcc, 6, v16
	v_readlane_b32 s61, v235, 2
	v_mov_b64_e32 v[2:3], s[74:75]
	v_readlane_b32 s62, v235, 3
	v_readlane_b32 s63, v235, 4
	v_readlane_b32 s64, v235, 5
	v_readlane_b32 s65, v235, 6
	v_readlane_b32 s66, v235, 7
	v_readlane_b32 s67, v235, 8
	v_readlane_b32 s68, v235, 9
	v_readlane_b32 s69, v235, 10
	v_readlane_b32 s70, v235, 11
	v_readlane_b32 s71, v235, 12
	v_readlane_b32 s72, v235, 13
	v_readlane_b32 s73, v235, 14
	s_and_saveexec_b64 s[28:29], vcc
	s_xor_b64 s[28:29], exec, s[28:29]
	s_cbranch_execz .LBB0_1451
	v_cmp_lt_i32_e32 vcc, 7, v16
	v_mov_b64_e32 v[2:3], s[42:43]
	s_and_saveexec_b64 s[30:31], vcc
	s_xor_b64 s[30:31], exec, s[30:31]
	s_cbranch_execz .LBB0_1448
	v_cmp_ne_u32_e32 vcc, 8, v16
	v_mov_b64_e32 v[2:3], s[44:45]
	s_and_saveexec_b64 s[22:23], vcc
	s_xor_b64 s[22:23], exec, s[22:23]
	v_mov_b64_e32 v[2:3], s[46:47]
	s_or_saveexec_b64 s[52:53], s[22:23]
	v_mov_b64_e32 v[12:13], 0x1600
	v_mov_b32_e32 v0, 0x800
	s_mov_b64 s[22:23], -1
	v_mov_b32_e32 v17, 0
	v_mov_b64_e32 v[14:15], s[18:19]
	s_xor_b64 exec, exec, s[52:53]
	v_mov_b64_e32 v[12:13], 0x800
	v_mov_b32_e32 v0, 0x1600
	v_mov_b32_e32 v17, 0x80
	v_mov_b64_e32 v[14:15], s[6:7]
	s_xor_b64 s[22:23], exec, -1
	s_or_b64 exec, exec, s[52:53]
.LBB0_1448:
	s_andn2_saveexec_b64 s[30:31], s[30:31]
	v_mov_b64_e32 v[12:13], 0x800
	v_mov_b32_e32 v0, 0x1600
	v_mov_b32_e32 v17, 0
	v_mov_b64_e32 v[14:15], s[6:7]
	s_andn2_b64 s[22:23], s[22:23], exec
	s_or_b64 exec, exec, s[30:31]
.LBB0_1451:
	s_andn2_saveexec_b64 s[28:29], s[28:29]
	v_mov_b64_e32 v[12:13], 0x800
	v_mov_b32_e32 v0, 0x800
	v_mov_b32_e32 v17, 0
	v_mov_b64_e32 v[14:15], s[8:9]
	s_or_b64 s[22:23], s[22:23], exec
	s_or_b64 exec, exec, s[28:29]
.LBB0_1454:
	s_andn2_saveexec_b64 s[26:27], s[26:27]
	s_cbranch_execz .LBB0_1460
	v_readlane_b32 s60, v235, 1
	v_readlane_b32 s70, v235, 11
	v_readlane_b32 s71, v235, 12
	v_cmp_lt_i32_e32 vcc, 4, v16
	v_readlane_b32 s61, v235, 2
	v_mov_b64_e32 v[2:3], s[70:71]
	v_readlane_b32 s62, v235, 3
	v_readlane_b32 s63, v235, 4
	v_readlane_b32 s64, v235, 5
	v_readlane_b32 s65, v235, 6
	v_readlane_b32 s66, v235, 7
	v_readlane_b32 s67, v235, 8
	v_readlane_b32 s68, v235, 9
	v_readlane_b32 s69, v235, 10
	v_readlane_b32 s72, v235, 13
	v_readlane_b32 s73, v235, 14
	v_readlane_b32 s74, v235, 15
	v_readlane_b32 s75, v235, 16
	s_and_saveexec_b64 s[28:29], vcc
	s_xor_b64 s[28:29], exec, s[28:29]
	s_cbranch_execz .LBB0_1457
	v_readlane_b32 s60, v235, 1
	v_readlane_b32 s72, v235, 13
	v_readlane_b32 s73, v235, 14
	v_readlane_b32 s61, v235, 2
	v_readlane_b32 s62, v235, 3
	v_readlane_b32 s63, v235, 4
	v_readlane_b32 s64, v235, 5
	v_readlane_b32 s65, v235, 6
	v_readlane_b32 s66, v235, 7
	v_readlane_b32 s67, v235, 8
	v_readlane_b32 s68, v235, 9
	v_readlane_b32 s69, v235, 10
	v_readlane_b32 s70, v235, 11
	v_readlane_b32 s71, v235, 12
	v_readlane_b32 s74, v235, 15
	v_readlane_b32 s75, v235, 16
	v_mov_b64_e32 v[2:3], s[72:73]
.LBB0_1457:
	s_or_saveexec_b64 s[28:29], s[28:29]
	v_mov_b64_e32 v[12:13], 0x800
	v_mov_b64_e32 v[14:15], s[10:11]
	s_xor_b64 exec, exec, s[28:29]
	v_mov_b64_e32 v[12:13], 0x400
	v_mov_b64_e32 v[14:15], s[2:3]
	s_or_b64 exec, exec, s[28:29]
	v_mov_b32_e32 v0, 0x800
	v_mov_b32_e32 v17, 0
	s_or_b64 s[22:23], s[22:23], exec

.LBB0_1461:
	s_or_saveexec_b64 s[24:25], s[24:25]
	s_mov_b64 s[26:27], 0
	s_xor_b64 exec, exec, s[24:25]
	s_cbranch_execz .LBB0_1473
	v_cmp_lt_i32_e32 vcc, 1, v16
	s_and_saveexec_b64 s[30:31], vcc
	s_xor_b64 s[30:31], exec, s[30:31]
	s_cbranch_execz .LBB0_1468
	v_cmp_lt_i32_e32 vcc, 2, v16
	v_mov_b64_e32 v[2:3], s[40:41]
	s_and_saveexec_b64 s[26:27], vcc
	s_xor_b64 s[26:27], exec, s[26:27]
	s_cbranch_execz .LBB0_1465
	v_readlane_b32 s60, v235, 1
	v_readlane_b32 s66, v235, 7
	v_readlane_b32 s67, v235, 8
	v_readlane_b32 s61, v235, 2
	v_readlane_b32 s62, v235, 3
	v_readlane_b32 s63, v235, 4
	v_readlane_b32 s64, v235, 5
	v_readlane_b32 s65, v235, 6
	v_readlane_b32 s68, v235, 9
	v_readlane_b32 s69, v235, 10
	v_readlane_b32 s70, v235, 11
	v_readlane_b32 s71, v235, 12
	v_readlane_b32 s72, v235, 13
	v_readlane_b32 s73, v235, 14
	v_readlane_b32 s74, v235, 15
	v_readlane_b32 s75, v235, 16
	v_mov_b64_e32 v[2:3], s[66:67]
.LBB0_1465:
	s_or_saveexec_b64 s[52:53], s[26:27]
	v_mov_b64_e32 v[12:13], 0x800
	v_mov_b32_e32 v0, 0x2e00
	s_mov_b64 s[26:27], 0
	s_mov_b64 s[28:29], -1
	v_mov_b64_e32 v[14:15], s[12:13]
	s_xor_b64 exec, exec, s[52:53]
	s_mov_b64 s[26:27], exec
	v_mov_b64_e32 v[12:13], 0x1600
	v_mov_b32_e32 v0, 0x800
	v_mov_b64_e32 v[14:15], s[14:15]
	s_xor_b64 s[28:29], exec, -1
	s_or_b64 exec, exec, s[52:53]
.LBB0_1468:
	s_or_saveexec_b64 s[30:31], s[30:31]
	v_mov_b32_e32 v17, 0
	s_xor_b64 exec, exec, s[30:31]
	s_cbranch_execz .LBB0_1472
	v_cmp_lt_i32_e32 vcc, 0, v16
	v_mov_b64_e32 v[2:3], s[36:37]
	s_and_saveexec_b64 s[52:53], vcc
	v_mov_b32_e32 v16, 0x80
	v_mov_b64_e32 v[2:3], s[38:39]
	s_or_b64 exec, exec, s[52:53]
	v_mov_b64_e32 v[12:13], 0x800
	v_mov_b32_e32 v0, 0x1600
	v_mov_b64_e32 v[14:15], s[16:17]
	s_andn2_b64 s[28:29], s[28:29], exec
	s_andn2_b64 s[26:27], s[26:27], exec
	v_mov_b32_e32 v17, v16
.LBB0_1472:
	s_or_b64 exec, exec, s[30:31]
	s_andn2_b64 s[22:23], s[22:23], exec
	s_and_b64 s[26:27], s[26:27], exec
	s_or_b64 s[22:23], s[22:23], s[26:27]
	s_and_b64 s[26:27], s[28:29], exec
.LBB0_1473:
	s_or_b64 exec, exec, s[24:25]
	v_lshrrev_b32_e32 v18, 5, v0
	v_cvt_f32_u32_e32 v16, v18
	v_sub_u32_e32 v25, 0, v18
	v_sub_u32_e32 v24, 0, v11
	v_max_i32_e32 v24, v11, v24
	v_rcp_iflag_f32_e32 v16, v16
	v_ashrrev_i32_e32 v19, 31, v11
	s_xor_b64 s[24:25], s[22:23], -1
	v_mul_f32_e32 v16, 0x4f7ffffe, v16
	v_cvt_u32_f32_e32 v16, v16
	v_mul_lo_u32 v25, v25, v16
	v_mul_hi_u32 v25, v16, v25
	v_add_u32_e32 v16, v16, v25
	v_mul_hi_u32 v16, v24, v16
	v_mul_lo_u32 v25, v16, v18
	v_sub_u32_e32 v24, v24, v25
	v_add_u32_e32 v26, 1, v16
	v_cmp_ge_u32_e32 vcc, v24, v18
	v_sub_u32_e32 v25, v24, v18
	s_nop 0
	v_cndmask_b32_e32 v16, v16, v26, vcc
	v_cndmask_b32_e32 v24, v24, v25, vcc
	v_add_u32_e32 v25, 1, v16
	v_cmp_ge_u32_e32 vcc, v24, v18
	s_nop 1
	v_cndmask_b32_e32 v16, v16, v25, vcc
	v_xor_b32_e32 v16, v16, v19
	v_sub_u32_e32 v16, v16, v19
	v_mul_lo_u32 v18, v16, v18
	v_sub_u32_e32 v11, v11, v18
	v_lshlrev_b32_e32 v18, 5, v11
	v_mov_b32_e32 v24, v18
	s_and_saveexec_b64 s[22:23], s[24:25]
	s_cbranch_execz .LBB0_1481
	s_xor_b64 s[24:25], s[26:27], -1
	s_and_saveexec_b64 s[26:27], s[24:25]
	s_xor_b64 s[24:25], exec, s[26:27]
	v_lshlrev_b32_e32 v11, 6, v11
	v_and_b32_e32 v11, 0xffffff00, v11
	v_and_b32_e32 v19, 0x60, v18
	v_or3_b32 v24, v19, v17, v11
	s_andn2_saveexec_b64 s[24:25], s[24:25]
	s_cbranch_execz .LBB0_1480
	v_add_u32_e32 v17, 0xfffff200, v18
	v_cmp_lt_u32_e32 vcc, s54, v17
	v_mov_b32_e32 v24, v18
	s_and_saveexec_b64 s[26:27], vcc
	s_cbranch_execz .LBB0_1479
	v_lshlrev_b32_e32 v11, 6, v11
	v_and_b32_e32 v11, 0x80, v11
	v_add_u32_e32 v17, 0xfffffa00, v18
	v_lshrrev_b32_e32 v24, 1, v18
	v_and_or_b32 v11, v18, 32, v11
	v_and_b32_e32 v19, 0x300, v17
	v_and_b32_e32 v24, 64, v24
	v_and_or_b32 v11, v17, s55, v11
	v_or3_b32 v11, v11, v19, v24
	v_add_u32_e32 v24, 0x600, v11
.LBB0_1479:
	s_or_b64 exec, exec, s[26:27]
.LBB0_1480:
	s_or_b64 exec, exec, s[24:25]
.LBB0_1481:
	s_or_b64 exec, exec, s[22:23]
	v_ashrrev_i32_e32 v19, 31, v18
	v_lshlrev_b32_e32 v16, 6, v16
	v_lshl_add_u64 v[2:3], v[18:19], 2, v[2:3]
	v_lshl_add_u64 v[18:19], v[2:3], 0, v[6:7]
	v_mov_b32_e32 v2, v0
	v_mov_b32_e32 v3, v16
	s_mov_b32 s22, 1
	s_mov_b32 s23, 0
	s_mov_b32 s24, 32
.LBB0_1482:
	s_lshl_b32 s25, s22, 1
	s_lshl_b32 s26, s23, 1
	v_or_b32_e32 v11, s25, v1
	v_or_b32_e32 v17, s26, v4
	s_add_i32 s27, s25, 4
	s_add_i32 s28, s26, 4
	s_add_i32 s29, s25, 8
	s_add_i32 s30, s26, 8
	s_add_i32 s31, s25, 12
	s_add_i32 s52, s26, 12
	s_add_i32 s53, s25, 16
	s_add_i32 s57, s26, 16
	s_add_i32 s58, s25, 20
	s_add_i32 s59, s26, 20
	s_add_i32 s60, s25, 24
	s_add_i32 s61, s26, 24
	s_add_i32 s25, s25, 28
	s_add_i32 s26, s26, 28
	v_add_u32_e32 v25, v11, v3
	v_add_u32_e32 v28, v17, v16
	v_or_b32_e32 v87, s27, v1
	v_or_b32_e32 v89, s28, v4
	v_or_b32_e32 v90, s29, v1
	v_or_b32_e32 v91, s30, v4
	v_or_b32_e32 v92, s31, v1
	v_or_b32_e32 v93, s52, v4
	v_or_b32_e32 v94, s53, v1
	v_or_b32_e32 v95, s57, v4
	v_or_b32_e32 v96, s58, v1
	v_or_b32_e32 v97, s59, v4
	v_or_b32_e32 v98, s60, v1
	v_or_b32_e32 v99, s61, v4
	v_or_b32_e32 v100, s25, v1
	v_or_b32_e32 v101, s26, v4
	v_ashrrev_i32_e32 v33, 31, v28
	v_ashrrev_i32_e32 v31, 31, v25
	v_mad_u64_u32 v[26:27], s[26:27], v2, v25, 0
	v_mad_u64_u32 v[28:29], s[26:27], v0, v28, 0
	v_add_u32_e32 v25, v87, v3
	v_add_u32_e32 v36, v89, v16
	v_add_u32_e32 v38, v90, v3
	v_add_u32_e32 v40, v91, v16
	v_add_u32_e32 v42, v92, v3
	v_add_u32_e32 v44, v93, v16
	v_add_u32_e32 v46, v94, v3
	v_add_u32_e32 v48, v95, v16
	v_add_u32_e32 v50, v96, v3
	v_add_u32_e32 v52, v97, v16
	v_add_u32_e32 v54, v98, v3
	v_add_u32_e32 v56, v99, v16
	v_add_u32_e32 v58, v100, v3
	v_add_u32_e32 v60, v101, v16
	v_mov_b32_e32 v30, v27
	v_mov_b32_e32 v32, v29
	v_ashrrev_i32_e32 v63, 31, v36
	v_ashrrev_i32_e32 v65, 31, v25
	v_mad_u64_u32 v[34:35], s[26:27], v2, v25, 0
	v_mad_u64_u32 v[36:37], s[26:27], v0, v36, 0
	v_ashrrev_i32_e32 v25, 31, v40
	v_ashrrev_i32_e32 v67, 31, v38
	v_mad_u64_u32 v[38:39], s[26:27], v2, v38, 0
	v_mad_u64_u32 v[40:41], s[26:27], v0, v40, 0
	v_ashrrev_i32_e32 v69, 31, v44
	v_ashrrev_i32_e32 v71, 31, v42
	v_mad_u64_u32 v[42:43], s[26:27], v2, v42, 0
	v_mad_u64_u32 v[44:45], s[26:27], v0, v44, 0
	v_ashrrev_i32_e32 v73, 31, v48
	v_ashrrev_i32_e32 v75, 31, v46
	v_mad_u64_u32 v[46:47], s[26:27], v2, v46, 0
	v_mad_u64_u32 v[48:49], s[26:27], v0, v48, 0
	v_ashrrev_i32_e32 v77, 31, v52
	v_ashrrev_i32_e32 v79, 31, v50
	v_mad_u64_u32 v[50:51], s[26:27], v2, v50, 0
	v_mad_u64_u32 v[52:53], s[26:27], v0, v52, 0
	v_ashrrev_i32_e32 v81, 31, v56
	v_ashrrev_i32_e32 v83, 31, v54
	v_mad_u64_u32 v[54:55], s[26:27], v2, v54, 0
	v_mad_u64_u32 v[56:57], s[26:27], v0, v56, 0
	v_ashrrev_i32_e32 v85, 31, v60
	v_ashrrev_i32_e32 v102, 31, v58
	v_mad_u64_u32 v[58:59], s[26:27], v2, v58, 0
	v_mad_u64_u32 v[60:61], s[26:27], v0, v60, 0
	v_mad_u64_u32 v[30:31], s[26:27], v2, v31, v[30:31]
	v_mad_u64_u32 v[32:33], s[26:27], v0, v33, v[32:33]
	v_mov_b32_e32 v62, v35
	v_mov_b32_e32 v64, v37
	v_mov_b32_e32 v66, v39
	v_mov_b32_e32 v68, v41
	v_mov_b32_e32 v70, v43
	v_mov_b32_e32 v72, v45
	v_mov_b32_e32 v74, v47
	v_mov_b32_e32 v76, v49
	v_mov_b32_e32 v78, v51
	v_mov_b32_e32 v80, v53
	v_mov_b32_e32 v82, v55
	v_mov_b32_e32 v84, v57
	v_mov_b32_e32 v86, v59
	v_mov_b32_e32 v88, v61
	v_mov_b32_e32 v27, v30
	v_mov_b32_e32 v29, v32
	v_mad_u64_u32 v[30:31], s[26:27], v2, v65, v[62:63]
	v_mad_u64_u32 v[32:33], s[26:27], v0, v63, v[64:65]
	v_mad_u64_u32 v[62:63], s[26:27], v2, v67, v[66:67]
	v_mad_u64_u32 v[64:65], s[26:27], v0, v25, v[68:69]
	v_mad_u64_u32 v[66:67], s[26:27], v2, v71, v[70:71]
	v_mad_u64_u32 v[68:69], s[26:27], v0, v69, v[72:73]
	v_mad_u64_u32 v[70:71], s[26:27], v2, v75, v[74:75]
	v_mad_u64_u32 v[72:73], s[26:27], v0, v73, v[76:77]
	v_mad_u64_u32 v[74:75], s[26:27], v2, v79, v[78:79]
	v_mad_u64_u32 v[76:77], s[26:27], v0, v77, v[80:81]
	v_mad_u64_u32 v[78:79], s[26:27], v2, v83, v[82:83]
	v_mad_u64_u32 v[80:81], s[26:27], v0, v81, v[84:85]
	v_mad_u64_u32 v[82:83], s[26:27], v2, v102, v[86:87]
	v_mad_u64_u32 v[84:85], s[26:27], v0, v85, v[88:89]
	v_lshl_add_u64 v[28:29], v[28:29], 2, v[18:19]
	v_mov_b32_e32 v35, v30
	v_mov_b32_e32 v37, v32
	v_mov_b32_e32 v39, v62
	v_mov_b32_e32 v41, v64
	v_mov_b32_e32 v43, v66
	v_mov_b32_e32 v45, v68
	v_mov_b32_e32 v47, v70
	v_mov_b32_e32 v49, v72
	v_mov_b32_e32 v51, v74
	v_mov_b32_e32 v53, v76
	v_mov_b32_e32 v55, v78
	v_mov_b32_e32 v57, v80
	v_mov_b32_e32 v59, v82
	v_mov_b32_e32 v61, v84
	v_lshl_add_u64 v[26:27], v[26:27], 2, v[18:19]
	v_lshl_add_u64 v[30:31], v[36:37], 2, v[18:19]
	v_lshl_add_u64 v[32:33], v[34:35], 2, v[18:19]
	v_lshl_add_u64 v[34:35], v[40:41], 2, v[18:19]
	v_lshl_add_u64 v[36:37], v[38:39], 2, v[18:19]
	v_lshl_add_u64 v[38:39], v[44:45], 2, v[18:19]
	v_lshl_add_u64 v[40:41], v[42:43], 2, v[18:19]
	v_lshl_add_u64 v[42:43], v[48:49], 2, v[18:19]
	v_lshl_add_u64 v[44:45], v[46:47], 2, v[18:19]
	v_lshl_add_u64 v[46:47], v[52:53], 2, v[18:19]
	v_lshl_add_u64 v[48:49], v[50:51], 2, v[18:19]
	v_lshl_add_u64 v[50:51], v[56:57], 2, v[18:19]
	v_lshl_add_u64 v[52:53], v[54:55], 2, v[18:19]
	v_lshl_add_u64 v[54:55], v[60:61], 2, v[18:19]
	v_lshl_add_u64 v[56:57], v[58:59], 2, v[18:19]
	global_load_dword v25, v[28:29], off
	global_load_dword v58, v[26:27], off
	global_load_dword v59, v[30:31], off
	global_load_dword v60, v[32:33], off
	global_load_dword v61, v[34:35], off
	global_load_dword v62, v[36:37], off
	global_load_dword v63, v[38:39], off
	global_load_dword v64, v[40:41], off
	global_load_dword v65, v[42:43], off
	global_load_dword v66, v[44:45], off
	global_load_dword v67, v[46:47], off
	global_load_dword v68, v[48:49], off
	global_load_dword v69, v[50:51], off
	global_load_dword v70, v[52:53], off
	global_load_dword v71, v[54:55], off
	global_load_dword v72, v[56:57], off
	s_add_i32 s23, s23, 16
	s_add_i32 s22, s22, 16
	s_add_i32 s24, s24, -16
	v_mad_u64_u32 v[26:27], s[26:27], v17, s35, v[8:9]
	s_cmp_lg_u32 s24, 0
	v_mad_u64_u32 v[28:29], s[26:27], v11, s35, v[8:9]
	v_mad_u64_u32 v[30:31], s[26:27], v89, s35, v[8:9]
	v_mad_u64_u32 v[32:33], s[26:27], v87, s35, v[8:9]
	v_mad_u64_u32 v[34:35], s[26:27], v91, s35, v[8:9]
	v_mad_u64_u32 v[36:37], s[26:27], v90, s35, v[8:9]
	v_mad_u64_u32 v[38:39], s[26:27], v93, s35, v[8:9]
	v_mad_u64_u32 v[40:41], s[26:27], v92, s35, v[8:9]
	v_mad_u64_u32 v[42:43], s[26:27], v95, s35, v[8:9]
	v_mad_u64_u32 v[44:45], s[26:27], v94, s35, v[8:9]
	v_mad_u64_u32 v[46:47], s[26:27], v97, s35, v[8:9]
	v_mad_u64_u32 v[48:49], s[26:27], v96, s35, v[8:9]
	v_mad_u64_u32 v[50:51], s[26:27], v99, s35, v[8:9]
	v_mad_u64_u32 v[52:53], s[26:27], v98, s35, v[8:9]
	v_mad_u64_u32 v[54:55], s[26:27], v101, s35, v[8:9]
	v_mad_u64_u32 v[56:57], s[26:27], v100, s35, v[8:9]
	s_waitcnt vmcnt(15)
	ds_write_b32 v26, v25
	s_waitcnt vmcnt(14)
	ds_write_b32 v28, v58
	s_waitcnt vmcnt(13)
	ds_write_b32 v30, v59
	s_waitcnt vmcnt(12)
	ds_write_b32 v32, v60
	s_waitcnt vmcnt(11)
	ds_write_b32 v34, v61
	s_waitcnt vmcnt(10)
	ds_write_b32 v36, v62
	s_waitcnt vmcnt(9)
	ds_write_b32 v38, v63
	s_waitcnt vmcnt(8)
	ds_write_b32 v40, v64
	s_waitcnt vmcnt(7)
	ds_write_b32 v42, v65
	s_waitcnt vmcnt(6)
	ds_write_b32 v44, v66
	s_waitcnt vmcnt(5)
	ds_write_b32 v46, v67
	s_waitcnt vmcnt(4)
	ds_write_b32 v48, v68
	s_waitcnt vmcnt(3)
	ds_write_b32 v50, v69
	s_waitcnt vmcnt(2)
	ds_write_b32 v52, v70
	s_waitcnt vmcnt(1)
	ds_write_b32 v54, v71
	s_waitcnt vmcnt(0)
	ds_write_b32 v56, v72
	s_cbranch_scc1 .LBB0_1482
	s_waitcnt lgkmcnt(0)
	v_ashrrev_i32_e32 v17, 31, v16
	ds_read2_b32 v[18:19], v20 offset0:33 offset1:41
	ds_read2_b32 v[26:27], v20 offset1:8
	ds_read2_b32 v[28:29], v20 offset0:66 offset1:74
	ds_read2_b32 v[30:31], v20 offset0:99 offset1:107
	ds_read2_b32 v[32:33], v20 offset0:132 offset1:140
	ds_read2_b32 v[34:35], v20 offset0:165 offset1:173
	ds_read2_b32 v[36:37], v20 offset0:198 offset1:206
	ds_read2_b32 v[38:39], v20 offset0:231 offset1:239
	v_lshl_add_u64 v[2:3], v[16:17], 1, v[14:15]
	v_mov_b32_e32 v11, v7
	v_add_u32_e32 v0, v24, v9
	v_lshl_add_u64 v[2:3], v[2:3], 0, v[10:11]
	v_ashrrev_i32_e32 v11, 31, v0
	s_waitcnt lgkmcnt(6)
	v_cvt_pk_bf16_f32 v14, v26, v18
	v_mul_lo_u32 v11, v12, v11
	v_mul_lo_u32 v18, v13, v0
	v_mad_u64_u32 v[40:41], s[22:23], v12, v0, 0
	v_add3_u32 v41, v41, v11, v18
	s_waitcnt lgkmcnt(4)
	v_cvt_pk_bf16_f32 v15, v28, v30
	s_waitcnt lgkmcnt(2)
	v_cvt_pk_bf16_f32 v16, v32, v34
	s_waitcnt lgkmcnt(0)
	v_cvt_pk_bf16_f32 v17, v36, v38
	v_lshl_add_u64 v[40:41], v[40:41], 1, v[2:3]
	v_add_u32_e32 v0, v24, v21
	global_store_dwordx4 v[40:41], v[14:17], off
	v_ashrrev_i32_e32 v11, 31, v0
	v_mul_lo_u32 v11, v12, v11
	v_cvt_pk_bf16_f32 v14, v27, v19
	v_cvt_pk_bf16_f32 v15, v29, v31
	v_cvt_pk_bf16_f32 v16, v33, v35
	v_cvt_pk_bf16_f32 v17, v37, v39
	v_mul_lo_u32 v25, v13, v0
	v_mad_u64_u32 v[18:19], s[22:23], v12, v0, 0
	ds_read2_b32 v[26:27], v20 offset0:16 offset1:24
	ds_read2_b32 v[28:29], v20 offset0:49 offset1:57
	ds_read2_b32 v[30:31], v20 offset0:82 offset1:90
	ds_read2_b32 v[32:33], v20 offset0:115 offset1:123
	ds_read2_b32 v[34:35], v20 offset0:148 offset1:156
	ds_read2_b32 v[36:37], v20 offset0:181 offset1:189
	ds_read2_b32 v[38:39], v20 offset0:214 offset1:222
	ds_read2_b32 v[40:41], v20 offset0:247 offset1:255
	v_add3_u32 v19, v19, v11, v25
	v_add_u32_e32 v0, v24, v22
	v_lshl_add_u64 v[18:19], v[18:19], 1, v[2:3]
	v_ashrrev_i32_e32 v11, 31, v0
	global_store_dwordx4 v[18:19], v[14:17], off
	v_mul_lo_u32 v11, v12, v11
	v_mul_lo_u32 v25, v13, v0
	v_mad_u64_u32 v[18:19], s[22:23], v12, v0, 0
	v_add3_u32 v19, v19, v11, v25
	v_add_u32_e32 v0, v24, v23
	s_waitcnt lgkmcnt(6)
	v_cvt_pk_bf16_f32 v14, v26, v28
	s_waitcnt lgkmcnt(4)
	v_cvt_pk_bf16_f32 v15, v30, v32
	s_waitcnt lgkmcnt(2)
	v_cvt_pk_bf16_f32 v16, v34, v36
	s_waitcnt lgkmcnt(0)
	v_cvt_pk_bf16_f32 v17, v38, v40
	v_lshl_add_u64 v[18:19], v[18:19], 1, v[2:3]
	v_ashrrev_i32_e32 v11, 31, v0
	global_store_dwordx4 v[18:19], v[14:17], off
	v_mul_lo_u32 v11, v12, v11
	v_mul_lo_u32 v18, v13, v0
	v_mad_u64_u32 v[12:13], s[22:23], v12, v0, 0
	v_add3_u32 v13, v13, v11, v18
	v_cvt_pk_bf16_f32 v14, v27, v29
	v_cvt_pk_bf16_f32 v15, v31, v33
	v_cvt_pk_bf16_f32 v16, v35, v37
	v_cvt_pk_bf16_f32 v17, v39, v41
	v_lshl_add_u64 v[2:3], v[12:13], 1, v[2:3]
	global_store_dwordx4 v[2:3], v[14:17], off
	v_add_u32_e32 v5, s33, v5
	s_waitcnt lgkmcnt(0)
	v_cmp_lt_i32_e32 vcc, s56, v5
	s_or_b64 s[20:21], vcc, s[20:21]
	s_andn2_b64 exec, exec, s[20:21]
	s_cbranch_execnz .LBB0_1417

.LBB0_1486:
.LBB0_1487:
	v_lshrrev_b32_e32 v0, 6, v128
	v_lshl_add_u32 v14, s34, 3, v0
	s_movk_i32 s2, 0x1600
	v_cmp_gt_i32_e32 vcc, s2, v14
	s_and_saveexec_b64 s[2:3], vcc
	s_cbranch_execz .LBB0_1492
	s_waitcnt vmcnt(0)
	v_lshlrev_b32_e32 v3, 3, v128
	s_movk_i32 s4, 0x2200
	v_lshlrev_b32_e32 v2, 2, v128
	v_bfe_u32 v15, v128, 3, 3
	v_and_b32_e32 v3, 56, v3
	v_mad_u32_u24 v1, v0, s4, 0
	v_and_b32_e32 v6, 0x7c, v2
	v_mul_u32_u24_e32 v4, 0x84, v3
	v_lshlrev_b32_e32 v5, 2, v15
	v_mov_b32_e32 v7, 0
	v_add_u32_e32 v2, v1, v6
	v_add3_u32 v16, v1, v4, v5
	v_lshl_add_u64 v[4:5], s[46:47], 0, v[6:7]
	v_lshlrev_b32_e32 v6, 1, v3
	v_bfe_u32 v0, v128, 5, 1
	v_lshl_add_u64 v[6:7], s[50:51], 0, v[6:7]
	s_mov_b64 s[4:5], 0xb004000
	s_lshl_b32 s6, s94, 3
	s_movk_i32 s7, 0x84
	v_or_b32_e32 v17, 8, v15
	v_or_b32_e32 v18, 16, v15
	v_or_b32_e32 v19, 24, v15
	v_lshl_add_u64 v[6:7], v[6:7], 0, s[4:5]
	v_mov_b32_e32 v1, v0
	s_mov_b64 s[4:5], 0
	s_movk_i32 s8, 0x2c00
	s_movk_i32 s9, 0x15ff
.LBB0_1489:
	v_ashrrev_i32_e32 v3, 31, v14
	v_lshrrev_b32_e32 v3, 26, v3
	v_add_u32_e32 v3, v14, v3
	v_and_b32_e32 v10, 0xffffffc0, v3
	v_lshlrev_b32_e32 v3, 5, v3
	v_and_b32_e32 v3, 0xfffff800, v3
	v_lshlrev_b32_e32 v8, 5, v14
	v_sub_u32_e32 v8, v8, v3
	v_ashrrev_i32_e32 v9, 31, v8
	v_lshl_add_u64 v[12:13], v[8:9], 2, v[4:5]
	v_mov_b32_e32 v3, v10
	s_mov_b32 s10, 32
	s_mov_b32 s11, 0
	s_mov_b32 s12, 1
.LBB0_1490:
	s_lshl_b32 s13, s12, 1
	s_lshl_b32 s14, s11, 1
	v_or_b32_e32 v9, s13, v1
	v_or_b32_e32 v11, s14, v0
	s_add_i32 s15, s13, 4
	s_add_i32 s16, s14, 4
	s_add_i32 s17, s13, 8
	s_add_i32 s18, s14, 8
	s_add_i32 s19, s13, 12
	s_add_i32 s20, s14, 12
	s_add_i32 s21, s13, 16
	s_add_i32 s22, s14, 16
	s_add_i32 s23, s13, 20
	s_add_i32 s24, s14, 20
	s_add_i32 s25, s13, 24
	s_add_i32 s26, s14, 24
	s_add_i32 s13, s13, 28
	s_add_i32 s14, s14, 28
	v_add_u32_e32 v22, v11, v10
	v_or_b32_e32 v52, s15, v1
	v_or_b32_e32 v53, s16, v0
	v_or_b32_e32 v54, s17, v1
	v_or_b32_e32 v55, s18, v0
	v_or_b32_e32 v56, s19, v1
	v_or_b32_e32 v57, s20, v0
	v_or_b32_e32 v58, s21, v1
	v_or_b32_e32 v59, s22, v0
	v_or_b32_e32 v60, s23, v1
	v_or_b32_e32 v61, s24, v0
	v_or_b32_e32 v62, s25, v1
	v_or_b32_e32 v63, s26, v0
	v_or_b32_e32 v64, s13, v1
	v_or_b32_e32 v65, s14, v0
	v_add_u32_e32 v20, v9, v3
	v_ashrrev_i32_e32 v23, 31, v22
	v_add_u32_e32 v24, v52, v3
	v_add_u32_e32 v26, v53, v10
	v_add_u32_e32 v28, v54, v3
	v_add_u32_e32 v30, v55, v10
	v_add_u32_e32 v32, v56, v3
	v_add_u32_e32 v34, v57, v10
	v_add_u32_e32 v36, v58, v3
	v_add_u32_e32 v38, v59, v10
	v_add_u32_e32 v40, v60, v3
	v_add_u32_e32 v42, v61, v10
	v_add_u32_e32 v44, v62, v3
	v_add_u32_e32 v46, v63, v10
	v_add_u32_e32 v48, v64, v3
	v_add_u32_e32 v50, v65, v10
	v_ashrrev_i32_e32 v21, 31, v20
	v_lshlrev_b64 v[22:23], 13, v[22:23]
	v_ashrrev_i32_e32 v27, 31, v26
	v_ashrrev_i32_e32 v25, 31, v24
	v_ashrrev_i32_e32 v31, 31, v30
	v_ashrrev_i32_e32 v29, 31, v28
	v_ashrrev_i32_e32 v35, 31, v34
	v_ashrrev_i32_e32 v33, 31, v32
	v_ashrrev_i32_e32 v39, 31, v38
	v_ashrrev_i32_e32 v37, 31, v36
	v_ashrrev_i32_e32 v43, 31, v42
	v_ashrrev_i32_e32 v41, 31, v40
	v_ashrrev_i32_e32 v47, 31, v46
	v_ashrrev_i32_e32 v45, 31, v44
	v_ashrrev_i32_e32 v51, 31, v50
	v_ashrrev_i32_e32 v49, 31, v48
	v_lshlrev_b64 v[20:21], 13, v[20:21]
	v_lshl_add_u64 v[22:23], v[12:13], 0, v[22:23]
	v_lshlrev_b64 v[24:25], 13, v[24:25]
	v_lshlrev_b64 v[26:27], 13, v[26:27]
	v_lshlrev_b64 v[28:29], 13, v[28:29]
	v_lshlrev_b64 v[30:31], 13, v[30:31]
	v_lshlrev_b64 v[32:33], 13, v[32:33]
	v_lshlrev_b64 v[34:35], 13, v[34:35]
	v_lshlrev_b64 v[36:37], 13, v[36:37]
	v_lshlrev_b64 v[38:39], 13, v[38:39]
	v_lshlrev_b64 v[40:41], 13, v[40:41]
	v_lshlrev_b64 v[42:43], 13, v[42:43]
	v_lshlrev_b64 v[44:45], 13, v[44:45]
	v_lshlrev_b64 v[46:47], 13, v[46:47]
	v_lshlrev_b64 v[48:49], 13, v[48:49]
	v_lshlrev_b64 v[50:51], 13, v[50:51]
	v_lshl_add_u64 v[20:21], v[12:13], 0, v[20:21]
	v_lshl_add_u64 v[26:27], v[12:13], 0, v[26:27]
	v_lshl_add_u64 v[24:25], v[12:13], 0, v[24:25]
	v_lshl_add_u64 v[30:31], v[12:13], 0, v[30:31]
	v_lshl_add_u64 v[28:29], v[12:13], 0, v[28:29]
	v_lshl_add_u64 v[34:35], v[12:13], 0, v[34:35]
	v_lshl_add_u64 v[32:33], v[12:13], 0, v[32:33]
	v_lshl_add_u64 v[38:39], v[12:13], 0, v[38:39]
	v_lshl_add_u64 v[36:37], v[12:13], 0, v[36:37]
	v_lshl_add_u64 v[42:43], v[12:13], 0, v[42:43]
	v_lshl_add_u64 v[40:41], v[12:13], 0, v[40:41]
	v_lshl_add_u64 v[46:47], v[12:13], 0, v[46:47]
	v_lshl_add_u64 v[44:45], v[12:13], 0, v[44:45]
	v_lshl_add_u64 v[50:51], v[12:13], 0, v[50:51]
	v_lshl_add_u64 v[48:49], v[12:13], 0, v[48:49]
	global_load_dword v66, v[22:23], off
	global_load_dword v67, v[20:21], off
	global_load_dword v68, v[26:27], off
	global_load_dword v69, v[24:25], off
	global_load_dword v70, v[30:31], off
	global_load_dword v71, v[28:29], off
	global_load_dword v72, v[34:35], off
	global_load_dword v73, v[32:33], off
	global_load_dword v74, v[38:39], off
	global_load_dword v75, v[36:37], off
	global_load_dword v76, v[42:43], off
	global_load_dword v77, v[40:41], off
	global_load_dword v78, v[46:47], off
	global_load_dword v79, v[44:45], off
	global_load_dword v80, v[50:51], off
	global_load_dword v81, v[48:49], off
	s_add_i32 s11, s11, 16
	s_add_i32 s12, s12, 16
	s_add_i32 s10, s10, -16
	v_mad_u64_u32 v[20:21], s[14:15], v11, s7, v[2:3]
	s_cmp_lg_u32 s10, 0
	v_mad_u64_u32 v[22:23], s[14:15], v9, s7, v[2:3]
	v_mad_u64_u32 v[24:25], s[14:15], v53, s7, v[2:3]
	v_mad_u64_u32 v[26:27], s[14:15], v52, s7, v[2:3]
	v_mad_u64_u32 v[28:29], s[14:15], v55, s7, v[2:3]
	v_mad_u64_u32 v[30:31], s[14:15], v54, s7, v[2:3]
	v_mad_u64_u32 v[32:33], s[14:15], v57, s7, v[2:3]
	v_mad_u64_u32 v[34:35], s[14:15], v56, s7, v[2:3]
	v_mad_u64_u32 v[36:37], s[14:15], v59, s7, v[2:3]
	v_mad_u64_u32 v[38:39], s[14:15], v58, s7, v[2:3]
	v_mad_u64_u32 v[40:41], s[14:15], v61, s7, v[2:3]
	v_mad_u64_u32 v[42:43], s[14:15], v60, s7, v[2:3]
	v_mad_u64_u32 v[44:45], s[14:15], v63, s7, v[2:3]
	v_mad_u64_u32 v[46:47], s[14:15], v62, s7, v[2:3]
	v_mad_u64_u32 v[48:49], s[14:15], v65, s7, v[2:3]
	v_mad_u64_u32 v[50:51], s[14:15], v64, s7, v[2:3]
	s_waitcnt vmcnt(15)
	ds_write_b32 v20, v66
	s_waitcnt vmcnt(14)
	ds_write_b32 v22, v67
	s_waitcnt vmcnt(13)
	ds_write_b32 v24, v68
	s_waitcnt vmcnt(12)
	ds_write_b32 v26, v69
	s_waitcnt vmcnt(11)
	ds_write_b32 v28, v70
	s_waitcnt vmcnt(10)
	ds_write_b32 v30, v71
	s_waitcnt vmcnt(9)
	ds_write_b32 v32, v72
	s_waitcnt vmcnt(8)
	ds_write_b32 v34, v73
	s_waitcnt vmcnt(7)
	ds_write_b32 v36, v74
	s_waitcnt vmcnt(6)
	ds_write_b32 v38, v75
	s_waitcnt vmcnt(5)
	ds_write_b32 v40, v76
	s_waitcnt vmcnt(4)
	ds_write_b32 v42, v77
	s_waitcnt vmcnt(3)
	ds_write_b32 v44, v78
	s_waitcnt vmcnt(2)
	ds_write_b32 v46, v79
	s_waitcnt vmcnt(1)
	ds_write_b32 v48, v80
	s_waitcnt vmcnt(0)
	ds_write_b32 v50, v81
	s_cbranch_scc1 .LBB0_1490
	s_waitcnt lgkmcnt(0)
	ds_read2_b32 v[20:21], v16 offset0:33 offset1:41
	ds_read2_b32 v[22:23], v16 offset1:8
	ds_read2_b32 v[24:25], v16 offset0:66 offset1:74
	ds_read2_b32 v[26:27], v16 offset0:99 offset1:107
	ds_read2_b32 v[28:29], v16 offset0:132 offset1:140
	ds_read2_b32 v[30:31], v16 offset0:165 offset1:173
	ds_read2_b32 v[32:33], v16 offset0:198 offset1:206
	ds_read2_b32 v[34:35], v16 offset0:231 offset1:239
	v_ashrrev_i32_e32 v11, 31, v10
	v_lshl_add_u64 v[36:37], v[10:11], 1, v[6:7]
	v_or_b32_e32 v3, v8, v15
	s_waitcnt lgkmcnt(6)
	v_cvt_pk_bf16_f32 v10, v22, v20
	s_waitcnt lgkmcnt(4)
	v_cvt_pk_bf16_f32 v11, v24, v26
	s_waitcnt lgkmcnt(2)
	v_cvt_pk_bf16_f32 v12, v28, v30
	s_waitcnt lgkmcnt(0)
	v_cvt_pk_bf16_f32 v13, v32, v34
	v_mad_i64_i32 v[38:39], s[10:11], v3, s8, v[36:37]
	global_store_dwordx4 v[38:39], v[10:13], off
	v_or_b32_e32 v3, v8, v17
	v_add_u32_e32 v14, s6, v14
	v_cvt_pk_bf16_f32 v10, v23, v21
	v_cvt_pk_bf16_f32 v11, v25, v27
	v_cvt_pk_bf16_f32 v12, v29, v31
	v_cvt_pk_bf16_f32 v13, v33, v35
	ds_read2_b32 v[22:23], v16 offset0:49 offset1:57
	ds_read2_b32 v[24:25], v16 offset0:16 offset1:24
	ds_read2_b32 v[26:27], v16 offset0:82 offset1:90
	ds_read2_b32 v[28:29], v16 offset0:115 offset1:123
	ds_read2_b32 v[30:31], v16 offset0:148 offset1:156
	ds_read2_b32 v[32:33], v16 offset0:181 offset1:189
	ds_read2_b32 v[34:35], v16 offset0:214 offset1:222
	ds_read2_b32 v[38:39], v16 offset0:247 offset1:255
	v_mad_i64_i32 v[20:21], s[10:11], v3, s8, v[36:37]
	v_or_b32_e32 v3, v8, v18
	global_store_dwordx4 v[20:21], v[10:13], off
	v_mad_i64_i32 v[20:21], s[10:11], v3, s8, v[36:37]
	s_waitcnt lgkmcnt(6)
	v_cvt_pk_bf16_f32 v10, v24, v22
	s_waitcnt lgkmcnt(4)
	v_cvt_pk_bf16_f32 v11, v26, v28
	s_waitcnt lgkmcnt(2)
	v_cvt_pk_bf16_f32 v12, v30, v32
	s_waitcnt lgkmcnt(0)
	v_cvt_pk_bf16_f32 v13, v34, v38
	v_or_b32_e32 v3, v8, v19
	global_store_dwordx4 v[20:21], v[10:13], off
	v_mad_i64_i32 v[8:9], s[10:11], v3, s8, v[36:37]
	s_nop 0
	v_cvt_pk_bf16_f32 v10, v25, v23
	v_cvt_pk_bf16_f32 v11, v27, v29
	v_cvt_pk_bf16_f32 v12, v31, v33
	v_cvt_pk_bf16_f32 v13, v35, v39
	global_store_dwordx4 v[8:9], v[10:13], off
	s_waitcnt lgkmcnt(0)
	v_cmp_lt_i32_e32 vcc, s9, v14
	s_or_b64 s[4:5], vcc, s[4:5]
	s_andn2_b64 exec, exec, s[4:5]
	s_cbranch_execnz .LBB0_1489
.LBB0_1492:
	s_or_b64 exec, exec, s[2:3]
.LBB0_1493:
	s_cmp_lt_i32 s92, 12
	s_cselect_b64 s[2:3], -1, 0
	s_cmp_gt_i32 s93, 11
	s_cselect_b64 s[4:5], -1, 0
	s_and_b64 s[4:5], s[2:3], s[4:5]
	s_andn2_b64 vcc, exec, s[4:5]
	s_cbranch_vccnz .LBB0_1568
	s_andn2_b64 vcc, exec, s[0:1]
	s_cbranch_vccnz .LBB0_1548
	s_waitcnt vmcnt(0)
	s_waitcnt vmcnt(0)
	s_barrier
	s_mov_b64 s[0:1], exec
	v_readlane_b32 s4, v235, 17
	v_readlane_b32 s5, v235, 18
	s_and_b64 s[4:5], s[0:1], s[4:5]
	s_mov_b64 exec, s[4:5]
	s_cbranch_execz .LBB0_1547
	s_add_i32 s4, 0, 0x23ff0
	v_mov_b32_e32 v0, s4
	s_waitcnt vmcnt(0) expcnt(0) lgkmcnt(0)
	ds_read_b32 v2, v0
	s_add_i32 s4, 0, 0x23ff4
	v_mov_b32_e32 v0, s4
	ds_read_b32 v0, v0
	s_waitcnt lgkmcnt(1)
	v_cmp_ne_u32_e32 vcc, 0, v2
	s_cbranch_vccnz .LBB0_1511
	v_readlane_b32 s4, v235, 0
	s_mul_i32 s18, s95, s4
	s_add_u32 s4, s50, 0x1000
	s_addc_u32 s5, s51, 0
	s_add_u32 s6, s50, 0x1100
	s_addc_u32 s7, s51, 0
	s_add_u32 s8, s50, 0x1200
	s_addc_u32 s9, s51, 0
	s_add_u32 s10, s50, 0x1300
	s_mul_i32 s18, s18, s94
	s_addc_u32 s11, s51, 0
	s_mov_b32 s19, 1
	v_mov_b32_e32 v16, 0
	s_branch .LBB0_1499

	.amdhsa_kernel _Z4mega6Params
		.amdhsa_group_segment_fixed_size 0
		.amdhsa_private_segment_fixed_size 0
		.amdhsa_kernarg_size 456
		.amdhsa_user_sgpr_count 2
		.amdhsa_user_sgpr_dispatch_ptr 0
		.amdhsa_user_sgpr_queue_ptr 0
		.amdhsa_user_sgpr_kernarg_segment_ptr 1
		.amdhsa_user_sgpr_dispatch_id 0
		.amdhsa_user_sgpr_kernarg_preload_length 0
		.amdhsa_user_sgpr_kernarg_preload_offset 0
		.amdhsa_user_sgpr_private_segment_size 0
		.amdhsa_uses_dynamic_stack 0
		.amdhsa_enable_private_segment 0
		.amdhsa_system_sgpr_workgroup_id_x 1
		.amdhsa_system_sgpr_workgroup_id_y 0
		.amdhsa_system_sgpr_workgroup_id_z 0
		.amdhsa_system_sgpr_workgroup_info 0
		.amdhsa_system_vgpr_workitem_id 2
		.amdhsa_next_free_vgpr 256
		.amdhsa_next_free_sgpr 98
		.amdhsa_accum_offset 256
		.amdhsa_reserve_vcc 1
		.amdhsa_float_round_mode_32 0
		.amdhsa_float_round_mode_16_64 0
		.amdhsa_float_denorm_mode_32 3
		.amdhsa_float_denorm_mode_16_64 3
		.amdhsa_dx10_clamp 1
		.amdhsa_ieee_mode 1
		.amdhsa_fp16_overflow 0
		.amdhsa_tg_split 0
		.amdhsa_exception_fp_ieee_invalid_op 0
		.amdhsa_exception_fp_denorm_src 0
		.amdhsa_exception_fp_ieee_div_zero 0
		.amdhsa_exception_fp_ieee_overflow 0
		.amdhsa_exception_fp_ieee_underflow 0
		.amdhsa_exception_fp_ieee_inexact 0
		.amdhsa_exception_int_div_zero 0
	.end_amdhsa_kernel

amdhsa.kernels:
  - .agpr_count:     0
    .args:
      - .offset:         0
        .size:           200
        .value_kind:     by_value
      - .offset:         200
        .size:           4
        .value_kind:     hidden_block_count_x
      - .offset:         204
        .size:           4
        .value_kind:     hidden_block_count_y
      - .offset:         208
        .size:           4
        .value_kind:     hidden_block_count_z
      - .offset:         212
        .size:           2
        .value_kind:     hidden_group_size_x
      - .offset:         214
        .size:           2
        .value_kind:     hidden_group_size_y
      - .offset:         216
        .size:           2
        .value_kind:     hidden_group_size_z
      - .offset:         218
        .size:           2
        .value_kind:     hidden_remainder_x
      - .offset:         220
        .size:           2
        .value_kind:     hidden_remainder_y
      - .offset:         222
        .size:           2
        .value_kind:     hidden_remainder_z
      - .offset:         240
        .size:           8
        .value_kind:     hidden_global_offset_x
      - .offset:         248
        .size:           8
        .value_kind:     hidden_global_offset_y
      - .offset:         256
        .size:           8
        .value_kind:     hidden_global_offset_z
      - .offset:         264
        .size:           2
        .value_kind:     hidden_grid_dims
      - .offset:         288
        .size:           8
        .value_kind:     hidden_multigrid_sync_arg
      - .offset:         320
        .size:           4
        .value_kind:     hidden_dynamic_lds_size
    .group_segment_fixed_size: 0
    .kernarg_segment_align: 8
    .kernarg_segment_size: 456
    .language:       OpenCL C
    .language_version:
      - 2
      - 0
    .max_flat_workgroup_size: 512
    .name:           _Z4mega6Params
    .private_segment_fixed_size: 0
    .sgpr_count:     104
    .sgpr_spill_count: 44
    .symbol:         _Z4mega6Params.kd
    .uniform_work_group_size: 1
    .uses_dynamic_stack: false
    .vgpr_count:     256
    .vgpr_spill_count: 0
    .wavefront_size: 64
